# v33
# baseline (speedup 1.0000x reference)
; template <class Epi, class Sched>
; __device__ __forceinline__ void gemm_simple(PG8_LAS unsigned char* lds, const Gemm g, const Sched& S, const Epi& E, int wave_s) {
;     ...
;             PG8_TILE(0, cA + (size_t)(t + 1) * kstep, cB + (size_t)(t + 1) * kstep, true);
.LBB0_63:
	s_waitcnt vmcnt(2) lgkmcnt(0)
	s_barrier
	ds_read_b128 v[142:145], v132
	ds_read_b128 v[170:173], v154
	ds_read_b128 v[156:159], v132 offset:2048
	ds_read_b128 v[178:181], v154 offset:2048
	s_add_u32 s16, s63, s54
	s_addc_u32 s17, s64, 0
	s_mov_b32 m0, s39
	s_nop 0
	global_load_lds_dwordx4 v139, s[16:17]
	s_mov_b32 m0, s43
	s_nop 0
	global_load_lds_dwordx4 v152, s[16:17]
	s_waitcnt lgkmcnt(2)
	v_mfma_f32_16x16x32_bf16 v[128:131], v[142:145], v[170:173], v[128:131]
	ds_read_b128 v[186:189], v154 offset:4096
	s_waitcnt lgkmcnt(2)
	v_mfma_f32_16x16x32_bf16 v[124:127], v[156:159], v[170:173], v[124:127]
	ds_read_b128 v[194:197], v154 offset:6144
	s_waitcnt lgkmcnt(2)
	v_mfma_f32_16x16x32_bf16 v[112:115], v[142:145], v[178:181], v[112:115]
	v_mfma_f32_16x16x32_bf16 v[108:111], v[156:159], v[178:181], v[108:111]
	ds_read_b128 v[146:149], v132 offset:1024
	ds_read_b128 v[174:177], v154 offset:1024
	s_waitcnt lgkmcnt(3)
	v_mfma_f32_16x16x32_bf16 v[96:99], v[142:145], v[186:189], v[96:99]
	ds_read_b128 v[160:163], v132 offset:3072
	v_mfma_f32_16x16x32_bf16 v[92:95], v[156:159], v[186:189], v[92:95]
	ds_read_b128 v[182:185], v154 offset:3072
	s_waitcnt lgkmcnt(4)
	v_mfma_f32_16x16x32_bf16 v[80:83], v[142:145], v[194:197], v[80:83]
	v_mfma_f32_16x16x32_bf16 v[76:79], v[156:159], v[194:197], v[76:79]
	ds_read_b128 v[190:193], v154 offset:5120
	s_waitcnt lgkmcnt(3)
	v_mfma_f32_16x16x32_bf16 v[128:131], v[146:149], v[174:177], v[128:131]
	s_waitcnt lgkmcnt(2)
	v_mfma_f32_16x16x32_bf16 v[124:127], v[160:163], v[174:177], v[124:127]
	ds_read_b128 v[198:201], v154 offset:7168
	s_waitcnt lgkmcnt(2)
	v_mfma_f32_16x16x32_bf16 v[112:115], v[146:149], v[182:185], v[112:115]
	v_mfma_f32_16x16x32_bf16 v[108:111], v[160:163], v[182:185], v[108:111]
	ds_read_b128 v[202:205], v133
	s_waitcnt lgkmcnt(2)
	v_mfma_f32_16x16x32_bf16 v[96:99], v[146:149], v[190:193], v[96:99]
	ds_read_b128 v[210:213], v133 offset:2048
	v_mfma_f32_16x16x32_bf16 v[92:95], v[160:163], v[190:193], v[92:95]
	s_waitcnt lgkmcnt(2)
	v_mfma_f32_16x16x32_bf16 v[80:83], v[146:149], v[198:201], v[80:83]
	v_mfma_f32_16x16x32_bf16 v[76:79], v[160:163], v[198:201], v[76:79]
	s_add_u32 s16, s18, s54
	s_addc_u32 s17, s19, 0
	s_mov_b32 m0, s40
	s_nop 0
	global_load_lds_dwordx4 v138, s[16:17]
	s_mov_b32 m0, s44
	s_nop 0
	global_load_lds_dwordx4 v140, s[16:17]
	s_waitcnt lgkmcnt(1)
	v_mfma_f32_16x16x32_bf16 v[120:123], v[202:205], v[170:173], v[120:123]
	s_waitcnt lgkmcnt(0)
	v_mfma_f32_16x16x32_bf16 v[116:119], v[210:213], v[170:173], v[116:119]
	v_mfma_f32_16x16x32_bf16 v[104:107], v[202:205], v[178:181], v[104:107]
	v_mfma_f32_16x16x32_bf16 v[100:103], v[210:213], v[178:181], v[100:103]
	ds_read_b128 v[206:209], v133 offset:1024
	v_mfma_f32_16x16x32_bf16 v[88:91], v[202:205], v[186:189], v[88:91]
	ds_read_b128 v[214:217], v133 offset:3072
	v_mfma_f32_16x16x32_bf16 v[84:87], v[210:213], v[186:189], v[84:87]
	v_mfma_f32_16x16x32_bf16 v[72:75], v[202:205], v[194:197], v[72:75]
	v_mfma_f32_16x16x32_bf16 v[68:71], v[210:213], v[194:197], v[68:71]
	s_waitcnt lgkmcnt(1)
	v_mfma_f32_16x16x32_bf16 v[120:123], v[206:209], v[174:177], v[120:123]
	s_waitcnt lgkmcnt(0)
	v_mfma_f32_16x16x32_bf16 v[116:119], v[214:217], v[174:177], v[116:119]
	v_mfma_f32_16x16x32_bf16 v[104:107], v[206:209], v[182:185], v[104:107]
	v_mfma_f32_16x16x32_bf16 v[100:103], v[214:217], v[182:185], v[100:103]
	v_mfma_f32_16x16x32_bf16 v[88:91], v[206:209], v[190:193], v[88:91]
	v_mfma_f32_16x16x32_bf16 v[84:87], v[214:217], v[190:193], v[84:87]
	v_mfma_f32_16x16x32_bf16 v[72:75], v[206:209], v[198:201], v[72:75]
	v_mfma_f32_16x16x32_bf16 v[68:71], v[214:217], v[198:201], v[68:71]
	s_waitcnt vmcnt(4) lgkmcnt(0)
	s_barrier
	ds_read_b128 v[170:173], v154 offset:16384
	ds_read_b128 v[178:181], v154 offset:18432
	s_add_u32 s16, s61, s54
	s_addc_u32 s17, s62, 0
	s_mov_b32 m0, s41
	s_nop 0
	global_load_lds_dwordx4 v139, s[16:17]
	s_mov_b32 m0, s45
	s_nop 0
	global_load_lds_dwordx4 v152, s[16:17]
	s_waitcnt lgkmcnt(1)
	v_mfma_f32_16x16x32_bf16 v[64:67], v[142:145], v[170:173], v[64:67]
	ds_read_b128 v[186:189], v154 offset:20480
	v_mfma_f32_16x16x32_bf16 v[60:63], v[156:159], v[170:173], v[60:63]
	ds_read_b128 v[194:197], v154 offset:22528
	s_waitcnt lgkmcnt(2)
	v_mfma_f32_16x16x32_bf16 v[48:51], v[142:145], v[178:181], v[48:51]
	v_mfma_f32_16x16x32_bf16 v[44:47], v[156:159], v[178:181], v[44:47]
	ds_read_b128 v[174:177], v154 offset:17408
	s_waitcnt lgkmcnt(2)
	v_mfma_f32_16x16x32_bf16 v[32:35], v[142:145], v[186:189], v[32:35]
	v_mfma_f32_16x16x32_bf16 v[28:31], v[156:159], v[186:189], v[28:31]
	ds_read_b128 v[182:185], v154 offset:19456
	s_waitcnt lgkmcnt(2)
	v_mfma_f32_16x16x32_bf16 v[16:19], v[142:145], v[194:197], v[16:19]
	v_mfma_f32_16x16x32_bf16 v[12:15], v[156:159], v[194:197], v[12:15]
	ds_read_b128 v[190:193], v154 offset:21504
	s_waitcnt lgkmcnt(2)
	v_mfma_f32_16x16x32_bf16 v[64:67], v[146:149], v[174:177], v[64:67]
	v_mfma_f32_16x16x32_bf16 v[60:63], v[160:163], v[174:177], v[60:63]
	ds_read_b128 v[198:201], v154 offset:23552
	s_waitcnt lgkmcnt(2)
	v_mfma_f32_16x16x32_bf16 v[48:51], v[146:149], v[182:185], v[48:51]
	v_mfma_f32_16x16x32_bf16 v[44:47], v[160:163], v[182:185], v[44:47]
	s_waitcnt lgkmcnt(1)
	v_mfma_f32_16x16x32_bf16 v[32:35], v[146:149], v[190:193], v[32:35]
	v_mfma_f32_16x16x32_bf16 v[28:31], v[160:163], v[190:193], v[28:31]
	s_waitcnt lgkmcnt(0)
	v_mfma_f32_16x16x32_bf16 v[16:19], v[146:149], v[198:201], v[16:19]
	v_mfma_f32_16x16x32_bf16 v[12:15], v[160:163], v[198:201], v[12:15]
	s_add_u32 s16, s59, s54
	s_addc_u32 s17, s60, 0
	s_mov_b32 m0, s42
	s_nop 0
	global_load_lds_dwordx4 v138, s[16:17]
	s_mov_b32 m0, s46
	s_nop 0
	global_load_lds_dwordx4 v140, s[16:17]
	v_mfma_f32_16x16x32_bf16 v[56:59], v[202:205], v[170:173], v[56:59]
	s_add_u32 s16, s57, s54
	s_addc_u32 s17, s58, 0
	s_add_u32 s65, s55, s54
	v_mfma_f32_16x16x32_bf16 v[52:55], v[210:213], v[170:173], v[52:55]
	s_addc_u32 s66, s56, 0
	v_mfma_f32_16x16x32_bf16 v[40:43], v[202:205], v[178:181], v[40:43]
	v_mfma_f32_16x16x32_bf16 v[36:39], v[210:213], v[178:181], v[36:39]
	v_mfma_f32_16x16x32_bf16 v[24:27], v[202:205], v[186:189], v[24:27]
	v_mfma_f32_16x16x32_bf16 v[20:23], v[210:213], v[186:189], v[20:23]
	v_mfma_f32_16x16x32_bf16 v[8:11], v[202:205], v[194:197], v[8:11]
	v_mfma_f32_16x16x32_bf16 v[4:7], v[210:213], v[194:197], v[4:7]
	v_mfma_f32_16x16x32_bf16 v[56:59], v[206:209], v[174:177], v[56:59]
	v_mfma_f32_16x16x32_bf16 v[52:55], v[214:217], v[174:177], v[52:55]
	v_mfma_f32_16x16x32_bf16 v[40:43], v[206:209], v[182:185], v[40:43]
	v_mfma_f32_16x16x32_bf16 v[36:39], v[214:217], v[182:185], v[36:39]
	v_mfma_f32_16x16x32_bf16 v[24:27], v[206:209], v[190:193], v[24:27]
	v_mfma_f32_16x16x32_bf16 v[20:23], v[214:217], v[190:193], v[20:23]
	v_mfma_f32_16x16x32_bf16 v[8:11], v[206:209], v[198:201], v[8:11]
	v_mfma_f32_16x16x32_bf16 v[4:7], v[214:217], v[198:201], v[4:7]
	s_waitcnt vmcnt(2) lgkmcnt(0)
	s_barrier
; template <class Epi, class Sched>
; __device__ __forceinline__ void gemm_simple(PG8_LAS unsigned char* lds, const Gemm g, const Sched& S, const Epi& E, int wave_s) {
;     ...
;             const char* a2 = last ? nA : cA + (size_t)(t + 2) * kstep; const char* b2 = last ? nB : cB + (size_t)(t + 2) * kstep;
;             PG8_TILE(1, a2, b2, (!last || has_next));
	ds_read_b128 v[142:145], v134
	ds_read_b128 v[170:173], v154 offset:32768
	ds_read_b128 v[156:159], v134 offset:2048
	ds_read_b128 v[178:181], v154 offset:34816
	s_cmp_eq_u32 s54, s10
	s_cselect_b32 s17, s5, s17
	s_cselect_b32 s16, s4, s16
	s_cselect_b32 s67, s9, s66
	s_cselect_b32 s66, s8, s65
	s_mov_b32 m0, s26
	s_nop 0
	global_load_lds_dwordx4 v139, s[66:67]
	s_mov_b32 m0, s27
	s_nop 0
	global_load_lds_dwordx4 v152, s[66:67]
	s_waitcnt lgkmcnt(2)
	v_mfma_f32_16x16x32_bf16 v[128:131], v[142:145], v[170:173], v[128:131]
	ds_read_b128 v[186:189], v154 offset:36864
	s_waitcnt lgkmcnt(2)
	v_mfma_f32_16x16x32_bf16 v[124:127], v[156:159], v[170:173], v[124:127]
	ds_read_b128 v[194:197], v154 offset:38912
	s_waitcnt lgkmcnt(2)
	v_mfma_f32_16x16x32_bf16 v[112:115], v[142:145], v[178:181], v[112:115]
	v_mfma_f32_16x16x32_bf16 v[108:111], v[156:159], v[178:181], v[108:111]
	ds_read_b128 v[146:149], v134 offset:1024
	ds_read_b128 v[174:177], v154 offset:33792
	s_waitcnt lgkmcnt(3)
	v_mfma_f32_16x16x32_bf16 v[96:99], v[142:145], v[186:189], v[96:99]
	ds_read_b128 v[160:163], v134 offset:3072
	v_mfma_f32_16x16x32_bf16 v[92:95], v[156:159], v[186:189], v[92:95]
	ds_read_b128 v[182:185], v154 offset:35840
	s_waitcnt lgkmcnt(4)
	v_mfma_f32_16x16x32_bf16 v[80:83], v[142:145], v[194:197], v[80:83]
	v_mfma_f32_16x16x32_bf16 v[76:79], v[156:159], v[194:197], v[76:79]
	ds_read_b128 v[190:193], v154 offset:37888
	s_waitcnt lgkmcnt(3)
	v_mfma_f32_16x16x32_bf16 v[128:131], v[146:149], v[174:177], v[128:131]
	s_waitcnt lgkmcnt(2)
	v_mfma_f32_16x16x32_bf16 v[124:127], v[160:163], v[174:177], v[124:127]
	ds_read_b128 v[198:201], v154 offset:39936
	s_waitcnt lgkmcnt(2)
	v_mfma_f32_16x16x32_bf16 v[112:115], v[146:149], v[182:185], v[112:115]
	v_mfma_f32_16x16x32_bf16 v[108:111], v[160:163], v[182:185], v[108:111]
	ds_read_b128 v[202:205], v135
	s_waitcnt lgkmcnt(2)
	v_mfma_f32_16x16x32_bf16 v[96:99], v[146:149], v[190:193], v[96:99]
	ds_read_b128 v[210:213], v135 offset:2048
	v_mfma_f32_16x16x32_bf16 v[92:95], v[160:163], v[190:193], v[92:95]
	s_waitcnt lgkmcnt(2)
	v_mfma_f32_16x16x32_bf16 v[80:83], v[146:149], v[198:201], v[80:83]
	v_mfma_f32_16x16x32_bf16 v[76:79], v[160:163], v[198:201], v[76:79]
	s_mov_b32 m0, s25
	s_nop 0
	global_load_lds_dwordx4 v138, s[16:17]
	s_mov_b32 m0, s28
	s_nop 0
	global_load_lds_dwordx4 v140, s[16:17]
	s_waitcnt lgkmcnt(1)
	v_mfma_f32_16x16x32_bf16 v[120:123], v[202:205], v[170:173], v[120:123]
	s_waitcnt lgkmcnt(0)
	v_mfma_f32_16x16x32_bf16 v[116:119], v[210:213], v[170:173], v[116:119]
	v_mfma_f32_16x16x32_bf16 v[104:107], v[202:205], v[178:181], v[104:107]
	v_mfma_f32_16x16x32_bf16 v[100:103], v[210:213], v[178:181], v[100:103]
	ds_read_b128 v[206:209], v135 offset:1024
	v_mfma_f32_16x16x32_bf16 v[88:91], v[202:205], v[186:189], v[88:91]
	ds_read_b128 v[214:217], v135 offset:3072
	v_mfma_f32_16x16x32_bf16 v[84:87], v[210:213], v[186:189], v[84:87]
	v_mfma_f32_16x16x32_bf16 v[72:75], v[202:205], v[194:197], v[72:75]
	v_mfma_f32_16x16x32_bf16 v[68:71], v[210:213], v[194:197], v[68:71]
	s_waitcnt lgkmcnt(1)
	v_mfma_f32_16x16x32_bf16 v[120:123], v[206:209], v[174:177], v[120:123]
	s_waitcnt lgkmcnt(0)
	v_mfma_f32_16x16x32_bf16 v[116:119], v[214:217], v[174:177], v[116:119]
	v_mfma_f32_16x16x32_bf16 v[104:107], v[206:209], v[182:185], v[104:107]
	v_mfma_f32_16x16x32_bf16 v[100:103], v[214:217], v[182:185], v[100:103]
	v_mfma_f32_16x16x32_bf16 v[88:91], v[206:209], v[190:193], v[88:91]
	v_mfma_f32_16x16x32_bf16 v[84:87], v[214:217], v[190:193], v[84:87]
	v_mfma_f32_16x16x32_bf16 v[72:75], v[206:209], v[198:201], v[72:75]
	v_mfma_f32_16x16x32_bf16 v[68:71], v[214:217], v[198:201], v[68:71]
	s_waitcnt vmcnt(4) lgkmcnt(0)
	s_barrier
	ds_read_b128 v[170:173], v154 offset:49152
	ds_read_b128 v[178:181], v154 offset:51200
	s_add_u32 s66, s66, 0x160000
	s_addc_u32 s67, s67, 0
	s_mov_b32 m0, s29
	s_nop 0
	global_load_lds_dwordx4 v139, s[66:67]
	s_mov_b32 m0, s36
	s_nop 0
	global_load_lds_dwordx4 v152, s[66:67]
	s_waitcnt lgkmcnt(1)
	v_mfma_f32_16x16x32_bf16 v[64:67], v[142:145], v[170:173], v[64:67]
	ds_read_b128 v[186:189], v154 offset:53248
	v_mfma_f32_16x16x32_bf16 v[60:63], v[156:159], v[170:173], v[60:63]
	ds_read_b128 v[194:197], v154 offset:55296
	s_waitcnt lgkmcnt(2)
	v_mfma_f32_16x16x32_bf16 v[48:51], v[142:145], v[178:181], v[48:51]
	v_mfma_f32_16x16x32_bf16 v[44:47], v[156:159], v[178:181], v[44:47]
	ds_read_b128 v[174:177], v154 offset:50176
	s_waitcnt lgkmcnt(2)
	v_mfma_f32_16x16x32_bf16 v[32:35], v[142:145], v[186:189], v[32:35]
	v_mfma_f32_16x16x32_bf16 v[28:31], v[156:159], v[186:189], v[28:31]
	ds_read_b128 v[182:185], v154 offset:52224
	s_waitcnt lgkmcnt(2)
	v_mfma_f32_16x16x32_bf16 v[16:19], v[142:145], v[194:197], v[16:19]
	v_mfma_f32_16x16x32_bf16 v[12:15], v[156:159], v[194:197], v[12:15]
	ds_read_b128 v[190:193], v154 offset:54272
	s_waitcnt lgkmcnt(2)
	v_mfma_f32_16x16x32_bf16 v[64:67], v[146:149], v[174:177], v[64:67]
	v_mfma_f32_16x16x32_bf16 v[60:63], v[160:163], v[174:177], v[60:63]
	ds_read_b128 v[198:201], v154 offset:56320
	s_waitcnt lgkmcnt(2)
	v_mfma_f32_16x16x32_bf16 v[48:51], v[146:149], v[182:185], v[48:51]
	v_mfma_f32_16x16x32_bf16 v[44:47], v[160:163], v[182:185], v[44:47]
	s_waitcnt lgkmcnt(1)
	v_mfma_f32_16x16x32_bf16 v[32:35], v[146:149], v[190:193], v[32:35]
	v_mfma_f32_16x16x32_bf16 v[28:31], v[160:163], v[190:193], v[28:31]
	s_waitcnt lgkmcnt(0)
; __device__ __forceinline__ unsigned cvt_pk_bf16(float lo, float hi) { unsigned r; asm volatile("v_cvt_pk_bf16_f32 %0, %1, %2" : "=v"(r) : "v"(lo), "v"(hi)); return r; }
; __device__ __forceinline__ float bflo(unsigned w) { return __uint_as_float(w << 16); }
; __device__ __forceinline__ float bfhi(unsigned w) { return __uint_as_float(w & 0xffff0000u); }
; __device__ __forceinline__ float sigmoidf_(float y) { return __builtin_amdgcn_rcpf(1.0f + __builtin_amdgcn_exp2f(-1.4426950408889634f * y)); }
;     __device__ __forceinline__ void operator()(const f32x4 (&acc)[2][2][4][2], const Unit& u, int wr, int wc, int fr, int fq, const LAS float* rt) const {
;     ...
;             for (int m = 0; m < 4; ++m) { const size_t row = (size_t)(row0 + ai * 128 + m * 16); const float rs = (MODE == 1) ? rt[ai * 128 + wr * 64 + m * 16 + fr] : 1.0f; float ss = 0.f;
; #pragma unroll
;                 for (int bj = 0; bj < 2; ++bj) { const size_t o = row * DM + col0 + bj * 128; const u32x4 xv = *(const u32x4*)(xin + o);
;                     f32x4 v0 = acc[ai][bj][m][0], v1 = acc[ai][bj][m][1];
;                     if (MODE == 1) { const u32x4 p = *(const u32x4*)(pe + o);
;                         v0[0] = sigmoidf_(v0[0] * rs) * bflo(p.x); v0[1] = sigmoidf_(v0[1] * rs) * bfhi(p.x); v0[2] = sigmoidf_(v0[2] * rs) * bflo(p.y); v0[3] = sigmoidf_(v0[3] * rs) * bfhi(p.y);
;                         v1[0] = sigmoidf_(v1[0] * rs) * bflo(p.z); v1[1] = sigmoidf_(v1[1] * rs) * bfhi(p.z); v1[2] = sigmoidf_(v1[2] * rs) * bflo(p.w); v1[3] = sigmoidf_(v1[3] * rs) * bfhi(p.w); }
;                     v0[0] += bflo(xv.x); v0[1] += bfhi(xv.x); v0[2] += bflo(xv.y); v0[3] += bfhi(xv.y); v1[0] += bflo(xv.z); v1[1] += bfhi(xv.z); v1[2] += bflo(xv.w); v1[3] += bfhi(xv.w);
;                     ss += (v0[0] * v0[0] + v0[1] * v0[1]) + (v0[2] * v0[2] + v0[3] * v0[3]) + (v1[0] * v1[0] + v1[1] * v1[1]) + (v1[2] * v1[2] + v1[3] * v1[3]);
;                     u32x4 w; w.x = cvt_pk_bf16(v0[0], v0[1]); w.y = cvt_pk_bf16(v0[2], v0[3]); w.z = cvt_pk_bf16(v1[0], v1[1]); w.w = cvt_pk_bf16(v1[2], v1[3]);
;                     __builtin_nontemporal_store(w, (u32x4*)(xout + o)); }
;                 ss += shx(ss, 16, lane); ss += shx(ss, 32, lane);
;                 if (fq == 0) ssq_out[row * 32 + u.pn * 4 + wc] = ss; }
	v_mfma_f32_16x16x32_bf16 v[16:19], v[146:149], v[198:201], v[16:19]
	v_mfma_f32_16x16x32_bf16 v[12:15], v[160:163], v[198:201], v[12:15]
	s_add_u32 s16, s16, 0x160000
	s_addc_u32 s17, s17, 0
	s_mov_b32 m0, s37
	s_nop 0
	global_load_lds_dwordx4 v138, s[16:17]
	s_mov_b32 m0, s38
	s_nop 0
	global_load_lds_dwordx4 v140, s[16:17]
	s_add_i32 s53, s53, 2
	s_add_u32 s10, s10, 0xffffff00
	s_addc_u32 s11, s11, -1
	s_add_u32 s55, s55, 0x100
	s_addc_u32 s56, s56, 0
	s_add_u32 s57, s57, 0x100
	s_addc_u32 s58, s58, 0
	s_add_u32 s59, s59, 0x100
	v_mfma_f32_16x16x32_bf16 v[56:59], v[202:205], v[170:173], v[56:59]
	s_addc_u32 s60, s60, 0
	s_add_u32 s61, s61, 0x100
	s_addc_u32 s62, s62, 0
	v_mfma_f32_16x16x32_bf16 v[52:55], v[210:213], v[170:173], v[52:55]
	s_add_u32 s18, s18, 0x100
	s_addc_u32 s19, s19, 0
	s_add_u32 s63, s63, 0x100
	v_mfma_f32_16x16x32_bf16 v[40:43], v[202:205], v[178:181], v[40:43]
	s_addc_u32 s64, s64, 0
	s_cmpk_lt_u32 s53, 0x56
	v_mfma_f32_16x16x32_bf16 v[36:39], v[210:213], v[178:181], v[36:39]
	v_mfma_f32_16x16x32_bf16 v[24:27], v[202:205], v[186:189], v[24:27]
	v_mfma_f32_16x16x32_bf16 v[20:23], v[210:213], v[186:189], v[20:23]
	v_mfma_f32_16x16x32_bf16 v[8:11], v[202:205], v[194:197], v[8:11]
	v_mfma_f32_16x16x32_bf16 v[4:7], v[210:213], v[194:197], v[4:7]
	v_mfma_f32_16x16x32_bf16 v[56:59], v[206:209], v[174:177], v[56:59]
	v_mfma_f32_16x16x32_bf16 v[52:55], v[214:217], v[174:177], v[52:55]
	v_mfma_f32_16x16x32_bf16 v[40:43], v[206:209], v[182:185], v[40:43]
	v_mfma_f32_16x16x32_bf16 v[36:39], v[214:217], v[182:185], v[36:39]
	v_mfma_f32_16x16x32_bf16 v[24:27], v[206:209], v[190:193], v[24:27]
	v_mfma_f32_16x16x32_bf16 v[20:23], v[214:217], v[190:193], v[20:23]
	v_mfma_f32_16x16x32_bf16 v[8:11], v[206:209], v[198:201], v[8:11]
	v_mfma_f32_16x16x32_bf16 v[4:7], v[214:217], v[198:201], v[4:7]
	s_cbranch_scc1 .LBB0_63
	v_mov_b32_e32 v132, v141
	s_lshl_b32 s10, s52, 8
	v_mbcnt_lo_u32_b32 v132, -1, v132
	v_mbcnt_hi_u32_b32 v135, -1, v132
	v_and_b32_e32 v136, 15, v135
	s_add_i32 s10, s10, s23
	v_or_b32_e32 v134, s10, v136
	s_lshl_b32 s10, s35, 8
	v_ashrrev_i32_e32 v137, 4, v135
	s_or_b32 s10, s10, s24
	v_lshl_add_u32 v132, v137, 3, s10
	v_lshlrev_b32_e32 v137, 6, v137
	v_lshlrev_b32_e32 v136, 2, v136
	s_movk_i32 s10, 0x80
	v_cmp_gt_u32_e32 vcc, 16, v135
	v_ashrrev_i32_e32 v135, 31, v134
	v_bitop3_b32 v156, v137, 64, v136 bitop3:0x36
	v_bitop3_b32 v155, v137, s10, v136 bitop3:0x36
	v_lshlrev_b64 v[136:137], 12, v[134:135]
	v_ashrrev_i32_e32 v133, 31, v132
	v_lshl_add_u64 v[136:137], s[94:95], 0, v[136:137]
	v_lshl_add_u64 v[136:137], v[132:133], 1, v[136:137]
	v_lshlrev_b32_e32 v236, 12, v134
	v_lshl_add_u32 v236, v132, 1, v236
	global_load_dwordx4 v[172:175], v236, s[94:95]
	global_load_dwordx4 v[176:179], v236, s[94:95] offset:256
	v_add_u32_e32 v237, 0x10000, v236
	global_load_dwordx4 v[180:183], v237, s[94:95]
	global_load_dwordx4 v[184:187], v237, s[94:95] offset:256
	v_add_u32_e32 v237, 0x20000, v236
	global_load_dwordx4 v[188:191], v237, s[94:95]
	global_load_dwordx4 v[192:195], v237, s[94:95] offset:256
	v_add_u32_e32 v237, 0x30000, v236
	global_load_dwordx4 v[196:199], v237, s[94:95]
	global_load_dwordx4 v[200:203], v237, s[94:95] offset:256
	v_add_u32_e32 v237, 0x80000, v236
	global_load_dwordx4 v[204:207], v237, s[94:95]
	global_load_dwordx4 v[208:211], v237, s[94:95] offset:256
	v_add_u32_e32 v237, 0x90000, v236
	global_load_dwordx4 v[212:215], v237, s[94:95]
	global_load_dwordx4 v[216:219], v237, s[94:95] offset:256
	v_add_u32_e32 v237, 0xa0000, v236
	global_load_dwordx4 v[220:223], v237, s[94:95]
	global_load_dwordx4 v[224:227], v237, s[94:95] offset:256
	v_add_u32_e32 v237, 0xb0000, v236
	global_load_dwordx4 v[228:231], v237, s[94:95]
	global_load_dwordx4 v[232:235], v237, s[94:95] offset:256
	s_lshl_b32 s10, s35, 2
	s_ashr_i32 s11, s10, 31
	s_waitcnt vmcnt(15)
	s_nop 1
	v_mov_b64_e32 v[142:143], v[172:173]
	v_mov_b64_e32 v[144:145], v[174:175]
	v_lshlrev_b32_e32 v146, 16, v142
	v_and_b32_e32 v142, 0xffff0000, v142
	v_add_f32_e32 v129, v129, v142
	v_lshlrev_b32_e32 v142, 16, v143
	v_add_f32_e32 v130, v130, v142
	v_and_b32_e32 v142, 0xffff0000, v143
	v_add_f32_e32 v131, v131, v142
	v_lshlrev_b32_e32 v142, 16, v144
	v_add_f32_e32 v142, v124, v142
	v_and_b32_e32 v124, 0xffff0000, v144
	v_add_f32_e32 v143, v125, v124
	v_lshlrev_b32_e32 v124, 16, v145
	v_add_f32_e32 v144, v126, v124
	v_and_b32_e32 v124, 0xffff0000, v145
	v_add_f32_e32 v128, v128, v146
	v_add_f32_e32 v127, v127, v124
	v_mul_f32_e32 v124, v129, v129
	v_mul_f32_e32 v125, v131, v131
	v_fmac_f32_e32 v124, v128, v128
	v_fmac_f32_e32 v125, v130, v130
	v_add_f32_e32 v124, v124, v125
	v_mul_f32_e32 v125, v143, v143
	v_fmac_f32_e32 v125, v142, v142
	v_add_f32_e32 v124, v125, v124
	v_mul_f32_e32 v125, v127, v127
	v_fmac_f32_e32 v125, v144, v144
	v_add_f32_e32 v145, v125, v124
	v_cvt_pk_bf16_f32 v124, v128, v129
	v_cvt_pk_bf16_f32 v125, v130, v131
	v_cvt_pk_bf16_f32 v126, v142, v143
	v_cvt_pk_bf16_f32 v127, v144, v127
	global_store_dwordx4 v[136:137], v[124:127], off nt
	s_waitcnt vmcnt(15)
	s_nop 1
	v_mov_b64_e32 v[124:125], v[176:177]
	v_mov_b64_e32 v[126:127], v[178:179]
	v_lshlrev_b32_e32 v128, 16, v124
	v_and_b32_e32 v124, 0xffff0000, v124
	v_add_f32_e32 v121, v121, v124
	v_lshlrev_b32_e32 v124, 16, v125
	v_add_f32_e32 v122, v122, v124
	v_and_b32_e32 v124, 0xffff0000, v125
	v_add_f32_e32 v123, v123, v124
	v_lshlrev_b32_e32 v124, 16, v126
	v_add_f32_e32 v124, v116, v124
	v_and_b32_e32 v116, 0xffff0000, v126
	v_add_f32_e32 v125, v117, v116
	v_lshlrev_b32_e32 v116, 16, v127
	v_add_f32_e32 v126, v118, v116
	v_and_b32_e32 v116, 0xffff0000, v127
	v_add_f32_e32 v120, v120, v128
	v_add_f32_e32 v119, v119, v116
	v_mul_f32_e32 v116, v121, v121
	v_mul_f32_e32 v117, v123, v123
	v_fmac_f32_e32 v116, v120, v120
	v_fmac_f32_e32 v117, v122, v122
	v_add_f32_e32 v116, v116, v117
	v_mul_f32_e32 v117, v125, v125
	v_fmac_f32_e32 v117, v124, v124
	v_add_f32_e32 v116, v117, v116
	v_mul_f32_e32 v117, v119, v119
	v_fmac_f32_e32 v117, v126, v126
	v_add_f32_e32 v116, v117, v116
	v_add_f32_e32 v127, v145, v116
	v_cvt_pk_bf16_f32 v116, v120, v121
	v_cvt_pk_bf16_f32 v117, v122, v123
	v_cvt_pk_bf16_f32 v118, v124, v125
	v_cvt_pk_bf16_f32 v119, v126, v119
	global_store_dwordx4 v[136:137], v[116:119], off offset:256 nt
	ds_bpermute_b32 v116, v156, v127
	s_waitcnt lgkmcnt(0)
	v_add_f32_e32 v116, v127, v116
	ds_bpermute_b32 v117, v155, v116
	s_and_saveexec_b64 s[16:17], vcc
	s_cbranch_execz .LBB0_66
	v_readlane_b32 s18, v255, 2
	v_lshlrev_b64 v[118:119], 7, v[134:135]
	v_readlane_b32 s19, v255, 3
	s_lshl_b32 s84, s22, 2
	s_mov_b32 s69, 0xf800000
	v_lshl_add_u64 v[118:119], s[18:19], 0, v[118:119]
	v_lshl_add_u64 v[118:119], s[10:11], 2, v[118:119]
	v_lshl_add_u64 v[118:119], v[118:119], 0, s[84:85]
	s_waitcnt lgkmcnt(0)
	v_add_f32_e32 v116, v116, v117
	global_store_dword v[118:119], v116, off

; template <class Epi, class Sched>
; __device__ __forceinline__ void gemm_simple(PG8_LAS unsigned char* lds, const Gemm g, const Sched& S, const Epi& E, int wave_s) {
;     ...
;             PG8_TILE(0, cA + (size_t)(t + 1) * kstep, cB + (size_t)(t + 1) * kstep, true);
.LBB0_95:
	s_waitcnt vmcnt(2) lgkmcnt(0)
	s_barrier
	ds_read_b128 v[142:145], v132
	ds_read_b128 v[174:177], v156
	ds_read_b128 v[158:161], v132 offset:2048
	ds_read_b128 v[182:185], v156 offset:2048
	s_add_u32 s64, s10, s63
	s_addc_u32 s65, s11, 0
	s_add_u32 s28, s64, 0x80
	s_addc_u32 s29, s65, 0
	s_mov_b32 m0, s48
	s_nop 0
	global_load_lds_dwordx4 v140, s[28:29]
	s_mov_b32 m0, s52
	s_nop 0
	global_load_lds_dwordx4 v153, s[28:29]
	s_waitcnt lgkmcnt(2)
	v_mfma_f32_16x16x32_bf16 v[124:127], v[142:145], v[174:177], v[124:127]
	ds_read_b128 v[190:193], v156 offset:4096
	s_waitcnt lgkmcnt(2)
	v_mfma_f32_16x16x32_bf16 v[116:119], v[158:161], v[174:177], v[116:119]
	ds_read_b128 v[198:201], v156 offset:6144
	s_waitcnt lgkmcnt(2)
	v_mfma_f32_16x16x32_bf16 v[108:111], v[142:145], v[182:185], v[108:111]
	v_mfma_f32_16x16x32_bf16 v[100:103], v[158:161], v[182:185], v[100:103]
	ds_read_b128 v[146:149], v132 offset:1024
	ds_read_b128 v[178:181], v156 offset:1024
	s_waitcnt lgkmcnt(3)
	v_mfma_f32_16x16x32_bf16 v[92:95], v[142:145], v[190:193], v[92:95]
	ds_read_b128 v[170:173], v132 offset:3072
	v_mfma_f32_16x16x32_bf16 v[84:87], v[158:161], v[190:193], v[84:87]
	ds_read_b128 v[186:189], v156 offset:3072
	s_waitcnt lgkmcnt(4)
	v_mfma_f32_16x16x32_bf16 v[76:79], v[142:145], v[198:201], v[76:79]
	v_mfma_f32_16x16x32_bf16 v[68:71], v[158:161], v[198:201], v[68:71]
	ds_read_b128 v[194:197], v156 offset:5120
	s_waitcnt lgkmcnt(3)
	v_mfma_f32_16x16x32_bf16 v[124:127], v[146:149], v[178:181], v[124:127]
	s_waitcnt lgkmcnt(2)
	v_mfma_f32_16x16x32_bf16 v[116:119], v[170:173], v[178:181], v[116:119]
	ds_read_b128 v[202:205], v156 offset:7168
	s_waitcnt lgkmcnt(2)
	v_mfma_f32_16x16x32_bf16 v[108:111], v[146:149], v[186:189], v[108:111]
	v_mfma_f32_16x16x32_bf16 v[100:103], v[170:173], v[186:189], v[100:103]
	ds_read_b128 v[206:209], v133
	s_waitcnt lgkmcnt(2)
	v_mfma_f32_16x16x32_bf16 v[92:95], v[146:149], v[194:197], v[92:95]
	ds_read_b128 v[214:217], v133 offset:2048
	v_mfma_f32_16x16x32_bf16 v[84:87], v[170:173], v[194:197], v[84:87]
	s_waitcnt lgkmcnt(2)
	v_mfma_f32_16x16x32_bf16 v[76:79], v[146:149], v[202:205], v[76:79]
	v_mfma_f32_16x16x32_bf16 v[68:71], v[170:173], v[202:205], v[68:71]
	s_add_u32 s66, s24, s63
	s_addc_u32 s67, s25, 0
	s_add_u32 s28, s66, 0x80
	s_addc_u32 s29, s67, 0
	s_mov_b32 m0, s49
	s_nop 0
	global_load_lds_dwordx4 v139, s[28:29]
	s_mov_b32 m0, s53
	s_nop 0
	global_load_lds_dwordx4 v152, s[28:29]
	s_waitcnt lgkmcnt(1)
	v_mfma_f32_16x16x32_bf16 v[128:131], v[206:209], v[174:177], v[128:131]
	s_waitcnt lgkmcnt(0)
	v_mfma_f32_16x16x32_bf16 v[120:123], v[214:217], v[174:177], v[120:123]
	v_mfma_f32_16x16x32_bf16 v[112:115], v[206:209], v[182:185], v[112:115]
	v_mfma_f32_16x16x32_bf16 v[104:107], v[214:217], v[182:185], v[104:107]
	ds_read_b128 v[210:213], v133 offset:1024
	v_mfma_f32_16x16x32_bf16 v[96:99], v[206:209], v[190:193], v[96:99]
	ds_read_b128 v[218:221], v133 offset:3072
	v_mfma_f32_16x16x32_bf16 v[88:91], v[214:217], v[190:193], v[88:91]
	v_mfma_f32_16x16x32_bf16 v[80:83], v[206:209], v[198:201], v[80:83]
	v_mfma_f32_16x16x32_bf16 v[72:75], v[214:217], v[198:201], v[72:75]
	s_waitcnt lgkmcnt(1)
	v_mfma_f32_16x16x32_bf16 v[128:131], v[210:213], v[178:181], v[128:131]
	s_waitcnt lgkmcnt(0)
	v_mfma_f32_16x16x32_bf16 v[120:123], v[218:221], v[178:181], v[120:123]
	v_mfma_f32_16x16x32_bf16 v[112:115], v[210:213], v[186:189], v[112:115]
	v_mfma_f32_16x16x32_bf16 v[104:107], v[218:221], v[186:189], v[104:107]
	v_mfma_f32_16x16x32_bf16 v[96:99], v[210:213], v[194:197], v[96:99]
	v_mfma_f32_16x16x32_bf16 v[88:91], v[218:221], v[194:197], v[88:91]
	v_mfma_f32_16x16x32_bf16 v[80:83], v[210:213], v[202:205], v[80:83]
	v_mfma_f32_16x16x32_bf16 v[72:75], v[218:221], v[202:205], v[72:75]
	s_waitcnt vmcnt(4) lgkmcnt(0)
	s_barrier
	ds_read_b128 v[174:177], v156 offset:16384
	ds_read_b128 v[182:185], v156 offset:18432
	s_add_u32 s28, s64, 0x80080
	s_addc_u32 s29, s65, 0
	s_mov_b32 m0, s50
	s_nop 0
	global_load_lds_dwordx4 v140, s[28:29]
	s_mov_b32 m0, s54
	s_nop 0
	global_load_lds_dwordx4 v153, s[28:29]
	s_waitcnt lgkmcnt(1)
	v_mfma_f32_16x16x32_bf16 v[60:63], v[142:145], v[174:177], v[60:63]
	ds_read_b128 v[190:193], v156 offset:20480
	v_mfma_f32_16x16x32_bf16 v[52:55], v[158:161], v[174:177], v[52:55]
	ds_read_b128 v[198:201], v156 offset:22528
	s_waitcnt lgkmcnt(2)
	v_mfma_f32_16x16x32_bf16 v[44:47], v[142:145], v[182:185], v[44:47]
	v_mfma_f32_16x16x32_bf16 v[36:39], v[158:161], v[182:185], v[36:39]
	ds_read_b128 v[178:181], v156 offset:17408
	s_waitcnt lgkmcnt(2)
	v_mfma_f32_16x16x32_bf16 v[28:31], v[142:145], v[190:193], v[28:31]
	v_mfma_f32_16x16x32_bf16 v[20:23], v[158:161], v[190:193], v[20:23]
	ds_read_b128 v[186:189], v156 offset:19456
	s_waitcnt lgkmcnt(2)
	v_mfma_f32_16x16x32_bf16 v[8:11], v[142:145], v[198:201], v[8:11]
	v_mfma_f32_16x16x32_bf16 v[4:7], v[158:161], v[198:201], v[4:7]
	ds_read_b128 v[194:197], v156 offset:21504
	s_waitcnt lgkmcnt(2)
	v_mfma_f32_16x16x32_bf16 v[60:63], v[146:149], v[178:181], v[60:63]
	v_mfma_f32_16x16x32_bf16 v[52:55], v[170:173], v[178:181], v[52:55]
	ds_read_b128 v[202:205], v156 offset:23552
	s_waitcnt lgkmcnt(2)
	v_mfma_f32_16x16x32_bf16 v[44:47], v[146:149], v[186:189], v[44:47]
	v_mfma_f32_16x16x32_bf16 v[36:39], v[170:173], v[186:189], v[36:39]
	s_waitcnt lgkmcnt(1)
	v_mfma_f32_16x16x32_bf16 v[28:31], v[146:149], v[194:197], v[28:31]
	v_mfma_f32_16x16x32_bf16 v[20:23], v[170:173], v[194:197], v[20:23]
	s_waitcnt lgkmcnt(0)
	v_mfma_f32_16x16x32_bf16 v[8:11], v[146:149], v[202:205], v[8:11]
	v_mfma_f32_16x16x32_bf16 v[4:7], v[170:173], v[202:205], v[4:7]
	s_add_u32 s28, s66, 0x80080
	s_addc_u32 s29, s67, 0
	s_mov_b32 m0, s51
	s_nop 0
	global_load_lds_dwordx4 v139, s[28:29]
	s_mov_b32 m0, s55
	s_nop 0
	global_load_lds_dwordx4 v152, s[28:29]
	v_mfma_f32_16x16x32_bf16 v[64:67], v[206:209], v[174:177], v[64:67]
	s_add_u32 s28, s66, 0x100
	s_addc_u32 s29, s67, 0
	s_add_u32 s64, s64, 0x100
	v_mfma_f32_16x16x32_bf16 v[56:59], v[214:217], v[174:177], v[56:59]
	s_addc_u32 s65, s65, 0
	v_mfma_f32_16x16x32_bf16 v[48:51], v[206:209], v[182:185], v[48:51]
	v_mfma_f32_16x16x32_bf16 v[40:43], v[214:217], v[182:185], v[40:43]
	v_mfma_f32_16x16x32_bf16 v[32:35], v[206:209], v[190:193], v[32:35]
	v_mfma_f32_16x16x32_bf16 v[24:27], v[214:217], v[190:193], v[24:27]
	v_mfma_f32_16x16x32_bf16 v[16:19], v[206:209], v[198:201], v[16:19]
	v_mfma_f32_16x16x32_bf16 v[12:15], v[214:217], v[198:201], v[12:15]
	v_mfma_f32_16x16x32_bf16 v[64:67], v[210:213], v[178:181], v[64:67]
	v_mfma_f32_16x16x32_bf16 v[56:59], v[218:221], v[178:181], v[56:59]
	v_mfma_f32_16x16x32_bf16 v[48:51], v[210:213], v[186:189], v[48:51]
	v_mfma_f32_16x16x32_bf16 v[40:43], v[218:221], v[186:189], v[40:43]
	v_mfma_f32_16x16x32_bf16 v[32:35], v[210:213], v[194:197], v[32:35]
	v_mfma_f32_16x16x32_bf16 v[24:27], v[218:221], v[194:197], v[24:27]
	v_mfma_f32_16x16x32_bf16 v[16:19], v[210:213], v[202:205], v[16:19]
	v_mfma_f32_16x16x32_bf16 v[12:15], v[218:221], v[202:205], v[12:15]
	s_waitcnt vmcnt(2) lgkmcnt(0)
	s_barrier
	ds_read_b128 v[142:145], v134
	ds_read_b128 v[174:177], v156 offset:32768
	ds_read_b128 v[158:161], v134 offset:2048
	ds_read_b128 v[182:185], v156 offset:34816
	s_cmp_eq_u32 s63, s26
	s_cselect_b32 s29, s17, s29
	s_cselect_b32 s28, s60, s28
	s_cselect_b32 s65, s5, s65
	s_cselect_b32 s64, s61, s64
	s_mov_b32 m0, s35
	s_nop 0
	global_load_lds_dwordx4 v140, s[64:65]
	s_mov_b32 m0, s39
	s_nop 0
	global_load_lds_dwordx4 v153, s[64:65]
	s_waitcnt lgkmcnt(2)
	v_mfma_f32_16x16x32_bf16 v[124:127], v[142:145], v[174:177], v[124:127]
	ds_read_b128 v[190:193], v156 offset:36864
	s_waitcnt lgkmcnt(2)
	v_mfma_f32_16x16x32_bf16 v[116:119], v[158:161], v[174:177], v[116:119]
	ds_read_b128 v[198:201], v156 offset:38912
	s_waitcnt lgkmcnt(2)
	v_mfma_f32_16x16x32_bf16 v[108:111], v[142:145], v[182:185], v[108:111]
	v_mfma_f32_16x16x32_bf16 v[100:103], v[158:161], v[182:185], v[100:103]
	ds_read_b128 v[146:149], v134 offset:1024
	ds_read_b128 v[178:181], v156 offset:33792
	s_waitcnt lgkmcnt(3)
	v_mfma_f32_16x16x32_bf16 v[92:95], v[142:145], v[190:193], v[92:95]
	ds_read_b128 v[170:173], v134 offset:3072
	v_mfma_f32_16x16x32_bf16 v[84:87], v[158:161], v[190:193], v[84:87]
	ds_read_b128 v[186:189], v156 offset:35840
	s_waitcnt lgkmcnt(4)
	v_mfma_f32_16x16x32_bf16 v[76:79], v[142:145], v[198:201], v[76:79]
	v_mfma_f32_16x16x32_bf16 v[68:71], v[158:161], v[198:201], v[68:71]
	ds_read_b128 v[194:197], v156 offset:37888
	s_waitcnt lgkmcnt(3)
	v_mfma_f32_16x16x32_bf16 v[124:127], v[146:149], v[178:181], v[124:127]
	s_waitcnt lgkmcnt(2)
	v_mfma_f32_16x16x32_bf16 v[116:119], v[170:173], v[178:181], v[116:119]
	ds_read_b128 v[202:205], v156 offset:39936
	s_waitcnt lgkmcnt(2)
	v_mfma_f32_16x16x32_bf16 v[108:111], v[146:149], v[186:189], v[108:111]
	v_mfma_f32_16x16x32_bf16 v[100:103], v[170:173], v[186:189], v[100:103]
	ds_read_b128 v[206:209], v135
	s_waitcnt lgkmcnt(2)
	v_mfma_f32_16x16x32_bf16 v[92:95], v[146:149], v[194:197], v[92:95]
	ds_read_b128 v[214:217], v135 offset:2048
	v_mfma_f32_16x16x32_bf16 v[84:87], v[170:173], v[194:197], v[84:87]
	s_waitcnt lgkmcnt(2)
	v_mfma_f32_16x16x32_bf16 v[76:79], v[146:149], v[202:205], v[76:79]
	v_mfma_f32_16x16x32_bf16 v[68:71], v[170:173], v[202:205], v[68:71]
	s_mov_b32 m0, s23
	s_nop 0
	global_load_lds_dwordx4 v139, s[28:29]
	s_mov_b32 m0, s40
	s_nop 0
	global_load_lds_dwordx4 v152, s[28:29]
	s_waitcnt lgkmcnt(1)
	v_mfma_f32_16x16x32_bf16 v[128:131], v[206:209], v[174:177], v[128:131]
	s_waitcnt lgkmcnt(0)
	v_mfma_f32_16x16x32_bf16 v[120:123], v[214:217], v[174:177], v[120:123]
	v_mfma_f32_16x16x32_bf16 v[112:115], v[206:209], v[182:185], v[112:115]
	v_mfma_f32_16x16x32_bf16 v[104:107], v[214:217], v[182:185], v[104:107]
	ds_read_b128 v[210:213], v135 offset:1024
	v_mfma_f32_16x16x32_bf16 v[96:99], v[206:209], v[190:193], v[96:99]
	ds_read_b128 v[218:221], v135 offset:3072
	v_mfma_f32_16x16x32_bf16 v[88:91], v[214:217], v[190:193], v[88:91]
	v_mfma_f32_16x16x32_bf16 v[80:83], v[206:209], v[198:201], v[80:83]
	v_mfma_f32_16x16x32_bf16 v[72:75], v[214:217], v[198:201], v[72:75]
	s_waitcnt lgkmcnt(1)
	v_mfma_f32_16x16x32_bf16 v[128:131], v[210:213], v[178:181], v[128:131]
	s_waitcnt lgkmcnt(0)
	v_mfma_f32_16x16x32_bf16 v[120:123], v[218:221], v[178:181], v[120:123]
	v_mfma_f32_16x16x32_bf16 v[112:115], v[210:213], v[186:189], v[112:115]
	v_mfma_f32_16x16x32_bf16 v[104:107], v[218:221], v[186:189], v[104:107]
	v_mfma_f32_16x16x32_bf16 v[96:99], v[210:213], v[194:197], v[96:99]
	v_mfma_f32_16x16x32_bf16 v[88:91], v[218:221], v[194:197], v[88:91]
	v_mfma_f32_16x16x32_bf16 v[80:83], v[210:213], v[202:205], v[80:83]
	v_mfma_f32_16x16x32_bf16 v[72:75], v[218:221], v[202:205], v[72:75]
	s_waitcnt vmcnt(4) lgkmcnt(0)
	s_barrier
; #define LAS __attribute__((address_space(3)))
; __device__ __forceinline__ void rstd_table(const float* ssq, LAS unsigned char* lds, const Unit& u, int tid, int par) {
;     if (tid < 256) { const f32x4* p = (const f32x4*)(ssq + (size_t)(u.pm * 256 + tid) * 32); f32x4 a = p[0];
; #pragma unroll
;         for (int i = 1; i < 8; ++i) a += p[i];
;         ((LAS float*)(lds + 131072 + par * 1024))[tid] = 1.0f / sqrtf(((a[0] + a[1]) + (a[2] + a[3])) * (1.0f / DM) + 1e-6f); }
	ds_read_b128 v[174:177], v156 offset:49152
	ds_read_b128 v[182:185], v156 offset:51200
	s_add_u32 s64, s64, 0x80000
	s_addc_u32 s65, s65, 0
	s_mov_b32 m0, s41
	s_nop 0
	global_load_lds_dwordx4 v140, s[64:65]
	s_mov_b32 m0, s42
	s_nop 0
	global_load_lds_dwordx4 v153, s[64:65]
	s_waitcnt lgkmcnt(1)
	v_mfma_f32_16x16x32_bf16 v[60:63], v[142:145], v[174:177], v[60:63]
	ds_read_b128 v[190:193], v156 offset:53248
	v_mfma_f32_16x16x32_bf16 v[52:55], v[158:161], v[174:177], v[52:55]
	ds_read_b128 v[198:201], v156 offset:55296
	s_waitcnt lgkmcnt(2)
	v_mfma_f32_16x16x32_bf16 v[44:47], v[142:145], v[182:185], v[44:47]
	v_mfma_f32_16x16x32_bf16 v[36:39], v[158:161], v[182:185], v[36:39]
	ds_read_b128 v[178:181], v156 offset:50176
	s_waitcnt lgkmcnt(2)
	v_mfma_f32_16x16x32_bf16 v[28:31], v[142:145], v[190:193], v[28:31]
	v_mfma_f32_16x16x32_bf16 v[20:23], v[158:161], v[190:193], v[20:23]
	ds_read_b128 v[186:189], v156 offset:52224
	s_waitcnt lgkmcnt(2)
	v_mfma_f32_16x16x32_bf16 v[8:11], v[142:145], v[198:201], v[8:11]
	v_mfma_f32_16x16x32_bf16 v[4:7], v[158:161], v[198:201], v[4:7]
	ds_read_b128 v[194:197], v156 offset:54272
	s_waitcnt lgkmcnt(2)
	v_mfma_f32_16x16x32_bf16 v[60:63], v[146:149], v[178:181], v[60:63]
	v_mfma_f32_16x16x32_bf16 v[52:55], v[170:173], v[178:181], v[52:55]
	ds_read_b128 v[202:205], v156 offset:56320
	s_waitcnt lgkmcnt(2)
	v_mfma_f32_16x16x32_bf16 v[44:47], v[146:149], v[186:189], v[44:47]
	v_mfma_f32_16x16x32_bf16 v[36:39], v[170:173], v[186:189], v[36:39]
	s_waitcnt lgkmcnt(1)
	v_mfma_f32_16x16x32_bf16 v[28:31], v[146:149], v[194:197], v[28:31]
	v_mfma_f32_16x16x32_bf16 v[20:23], v[170:173], v[194:197], v[20:23]
	s_waitcnt lgkmcnt(0)
	v_mfma_f32_16x16x32_bf16 v[8:11], v[146:149], v[202:205], v[8:11]
	v_mfma_f32_16x16x32_bf16 v[4:7], v[170:173], v[202:205], v[4:7]
	s_add_u32 s28, s28, 0x80000
	s_addc_u32 s29, s29, 0
	s_mov_b32 m0, s43
	s_nop 0
	global_load_lds_dwordx4 v139, s[28:29]
	s_mov_b32 m0, s44
	s_nop 0
	global_load_lds_dwordx4 v152, s[28:29]
	v_mfma_f32_16x16x32_bf16 v[64:67], v[206:209], v[174:177], v[64:67]
	s_add_i32 s62, s62, 2
	s_add_u32 s26, s26, 0xffffff00
	s_addc_u32 s27, s27, -1
	v_mfma_f32_16x16x32_bf16 v[56:59], v[214:217], v[174:177], v[56:59]
	s_add_u32 s24, s24, 0x100
	s_addc_u32 s25, s25, 0
	s_add_u32 s10, s10, 0x100
	v_mfma_f32_16x16x32_bf16 v[48:51], v[206:209], v[182:185], v[48:51]
	s_addc_u32 s11, s11, 0
	s_cmp_lt_u32 s62, 30
	v_mfma_f32_16x16x32_bf16 v[40:43], v[214:217], v[182:185], v[40:43]
	v_mfma_f32_16x16x32_bf16 v[32:35], v[206:209], v[190:193], v[32:35]
	v_mfma_f32_16x16x32_bf16 v[24:27], v[214:217], v[190:193], v[24:27]
	v_mfma_f32_16x16x32_bf16 v[16:19], v[206:209], v[198:201], v[16:19]
	v_mfma_f32_16x16x32_bf16 v[12:15], v[214:217], v[198:201], v[12:15]
	v_mfma_f32_16x16x32_bf16 v[64:67], v[210:213], v[178:181], v[64:67]
	v_mfma_f32_16x16x32_bf16 v[56:59], v[218:221], v[178:181], v[56:59]
	v_mfma_f32_16x16x32_bf16 v[48:51], v[210:213], v[186:189], v[48:51]
	v_mfma_f32_16x16x32_bf16 v[40:43], v[218:221], v[186:189], v[40:43]
	v_mfma_f32_16x16x32_bf16 v[32:35], v[210:213], v[194:197], v[32:35]
	v_mfma_f32_16x16x32_bf16 v[24:27], v[218:221], v[194:197], v[24:27]
	v_mfma_f32_16x16x32_bf16 v[16:19], v[210:213], v[202:205], v[16:19]
	v_mfma_f32_16x16x32_bf16 v[12:15], v[218:221], v[202:205], v[12:15]
	s_cbranch_scc1 .LBB0_95
	s_nor_b64 s[10:11], s[6:7], s[8:9]
	s_and_saveexec_b64 s[24:25], s[10:11]
	s_cbranch_execz .LBB0_89
	v_lshl_add_u32 v132, s16, 8, v138
	v_ashrrev_i32_e32 v133, 31, v132
	v_lshlrev_b64 v[132:133], 7, v[132:133]
	v_lshl_add_u64 v[136:137], s[0:1], 0, v[132:133]
	global_load_dwordx4 v[132:135], v[136:137], off offset:48
	global_load_dwordx4 v[142:145], v[136:137], off offset:32
	global_load_dwordx4 v[146:149], v[136:137], off
	global_load_dwordx4 v[158:161], v[136:137], off offset:16
	s_lshl_b32 s5, s57, 10
	s_and_b32 s5, s5, 0x400
	s_waitcnt vmcnt(0)
	v_pk_add_f32 v[148:149], v[148:149], v[160:161]
	v_pk_add_f32 v[146:147], v[146:147], v[158:159]
	v_pk_add_f32 v[144:145], v[148:149], v[144:145]
	v_pk_add_f32 v[142:143], v[146:147], v[142:143]
	v_pk_add_f32 v[162:163], v[144:145], v[134:135]
	v_pk_add_f32 v[170:171], v[142:143], v[132:133]
	global_load_dwordx4 v[132:135], v[136:137], off offset:112
	global_load_dwordx4 v[142:145], v[136:137], off offset:96
	global_load_dwordx4 v[146:149], v[136:137], off offset:80
	global_load_dwordx4 v[158:161], v[136:137], off offset:64
	s_waitcnt vmcnt(0)
	v_pk_add_f32 v[136:137], v[162:163], v[160:161]
	v_pk_add_f32 v[158:159], v[170:171], v[158:159]
	v_pk_add_f32 v[136:137], v[136:137], v[148:149]
	v_pk_add_f32 v[146:147], v[158:159], v[146:147]
	v_pk_add_f32 v[136:137], v[136:137], v[144:145]
	v_pk_add_f32 v[142:143], v[146:147], v[142:143]
	v_pk_add_f32 v[134:135], v[136:137], v[134:135]
	v_pk_add_f32 v[132:133], v[142:143], v[132:133]
	s_nop 0
	v_pk_mov_b32 v[136:137], v[132:133], v[134:135] op_sel:[1,0]
	v_mov_b32_e32 v133, v135
	v_pk_add_f32 v[132:133], v[136:137], v[132:133]
	s_nop 0
	v_add_f32_e32 v132, v132, v133
	v_fmamk_f32 v132, v132, 0x3a000000, v164
	v_cmp_gt_f32_e32 vcc, s69, v132
	v_mul_f32_e32 v133, 0x4f800000, v132
	s_nop 0
	v_cndmask_b32_e32 v132, v132, v133, vcc
	v_sqrt_f32_e32 v133, v132
	s_nop 0
	v_add_u32_e32 v134, -1, v133
	v_fma_f32 v135, -v134, v133, v132
	v_cmp_ge_f32_e64 s[10:11], 0, v135
	v_add_u32_e32 v135, 1, v133
	s_nop 0
	v_cndmask_b32_e64 v134, v133, v134, s[10:11]
	v_fma_f32 v133, -v135, v133, v132
	v_cmp_lt_f32_e64 s[10:11], 0, v133
	s_nop 1
	v_cndmask_b32_e64 v133, v134, v135, s[10:11]
	v_mul_f32_e32 v134, 0x37800000, v133
	v_cndmask_b32_e32 v133, v133, v134, vcc
	v_cmp_class_f32_e32 vcc, v132, v165
	s_nop 1
	v_cndmask_b32_e32 v132, v133, v132, vcc
	v_div_scale_f32 v133, s[10:11], v132, v132, 1.0
	v_rcp_f32_e32 v134, v133
	s_nop 0
	v_fma_f32 v135, -v133, v134, 1.0
	v_fmac_f32_e32 v134, v135, v134
	v_div_scale_f32 v135, vcc, 1.0, v132, 1.0
	v_mul_f32_e32 v136, v135, v134
	v_fma_f32 v137, -v133, v136, v135
	v_fmac_f32_e32 v136, v137, v134
	v_fma_f32 v133, -v133, v136, v135
	v_div_fmas_f32 v133, v133, v134, v136
	v_div_fixup_f32 v132, v133, v132, 1.0
	v_add_u32_e32 v133, s5, v154
	ds_write_b32 v133, v132
	s_branch .LBB0_89

.LBB0_119:
	s_waitcnt vmcnt(2) lgkmcnt(0)
	s_barrier
	ds_read_b128 v[146:149], v132
	ds_read_b128 v[174:177], v154
	ds_read_b128 v[160:163], v132 offset:2048
	ds_read_b128 v[182:185], v154 offset:2048
	s_add_u32 s26, s69, s58
	s_addc_u32 s27, s70, 0
	s_mov_b32 m0, s47
	s_nop 0
	global_load_lds_dwordx4 v139, s[26:27]
	s_mov_b32 m0, s51
	s_nop 0
	global_load_lds_dwordx4 v152, s[26:27]
	s_waitcnt lgkmcnt(2)
	v_mfma_f32_16x16x32_bf16 v[128:131], v[146:149], v[174:177], v[128:131]
	ds_read_b128 v[190:193], v154 offset:4096
	s_waitcnt lgkmcnt(2)
	v_mfma_f32_16x16x32_bf16 v[124:127], v[160:163], v[174:177], v[124:127]
	ds_read_b128 v[198:201], v154 offset:6144
	s_waitcnt lgkmcnt(2)
	v_mfma_f32_16x16x32_bf16 v[112:115], v[146:149], v[182:185], v[112:115]
	v_mfma_f32_16x16x32_bf16 v[108:111], v[160:163], v[182:185], v[108:111]
	ds_read_b128 v[156:159], v132 offset:1024
	ds_read_b128 v[178:181], v154 offset:1024
	s_waitcnt lgkmcnt(3)
	v_mfma_f32_16x16x32_bf16 v[96:99], v[146:149], v[190:193], v[96:99]
	ds_read_b128 v[170:173], v132 offset:3072
	v_mfma_f32_16x16x32_bf16 v[92:95], v[160:163], v[190:193], v[92:95]
	ds_read_b128 v[186:189], v154 offset:3072
	s_waitcnt lgkmcnt(4)
	v_mfma_f32_16x16x32_bf16 v[80:83], v[146:149], v[198:201], v[80:83]
	v_mfma_f32_16x16x32_bf16 v[76:79], v[160:163], v[198:201], v[76:79]
	ds_read_b128 v[194:197], v154 offset:5120
	s_waitcnt lgkmcnt(3)
	v_mfma_f32_16x16x32_bf16 v[128:131], v[156:159], v[178:181], v[128:131]
	s_waitcnt lgkmcnt(2)
	v_mfma_f32_16x16x32_bf16 v[124:127], v[170:173], v[178:181], v[124:127]
	ds_read_b128 v[202:205], v154 offset:7168
	s_waitcnt lgkmcnt(2)
	v_mfma_f32_16x16x32_bf16 v[112:115], v[156:159], v[186:189], v[112:115]
	v_mfma_f32_16x16x32_bf16 v[108:111], v[170:173], v[186:189], v[108:111]
	ds_read_b128 v[206:209], v133
	s_waitcnt lgkmcnt(2)
	v_mfma_f32_16x16x32_bf16 v[96:99], v[156:159], v[194:197], v[96:99]
	ds_read_b128 v[214:217], v133 offset:2048
	v_mfma_f32_16x16x32_bf16 v[92:95], v[170:173], v[194:197], v[92:95]
	s_waitcnt lgkmcnt(2)
	v_mfma_f32_16x16x32_bf16 v[80:83], v[156:159], v[202:205], v[80:83]
	v_mfma_f32_16x16x32_bf16 v[76:79], v[170:173], v[202:205], v[76:79]
	s_add_u32 s26, s67, s58
	s_addc_u32 s27, s68, 0
	s_mov_b32 m0, s48
	s_nop 0
	global_load_lds_dwordx4 v138, s[26:27]
	s_mov_b32 m0, s52
	s_nop 0
	global_load_lds_dwordx4 v140, s[26:27]
	s_waitcnt lgkmcnt(1)
	v_mfma_f32_16x16x32_bf16 v[120:123], v[206:209], v[174:177], v[120:123]
	s_waitcnt lgkmcnt(0)
	v_mfma_f32_16x16x32_bf16 v[116:119], v[214:217], v[174:177], v[116:119]
	v_mfma_f32_16x16x32_bf16 v[104:107], v[206:209], v[182:185], v[104:107]
	v_mfma_f32_16x16x32_bf16 v[100:103], v[214:217], v[182:185], v[100:103]
	ds_read_b128 v[210:213], v133 offset:1024
	v_mfma_f32_16x16x32_bf16 v[88:91], v[206:209], v[190:193], v[88:91]
	ds_read_b128 v[218:221], v133 offset:3072
	v_mfma_f32_16x16x32_bf16 v[84:87], v[214:217], v[190:193], v[84:87]
	v_mfma_f32_16x16x32_bf16 v[72:75], v[206:209], v[198:201], v[72:75]
	v_mfma_f32_16x16x32_bf16 v[68:71], v[214:217], v[198:201], v[68:71]
	s_waitcnt lgkmcnt(1)
	v_mfma_f32_16x16x32_bf16 v[120:123], v[210:213], v[178:181], v[120:123]
	s_waitcnt lgkmcnt(0)
	v_mfma_f32_16x16x32_bf16 v[116:119], v[218:221], v[178:181], v[116:119]
	v_mfma_f32_16x16x32_bf16 v[104:107], v[210:213], v[186:189], v[104:107]
	v_mfma_f32_16x16x32_bf16 v[100:103], v[218:221], v[186:189], v[100:103]
	v_mfma_f32_16x16x32_bf16 v[88:91], v[210:213], v[194:197], v[88:91]
	v_mfma_f32_16x16x32_bf16 v[84:87], v[218:221], v[194:197], v[84:87]
	v_mfma_f32_16x16x32_bf16 v[72:75], v[210:213], v[202:205], v[72:75]
	v_mfma_f32_16x16x32_bf16 v[68:71], v[218:221], v[202:205], v[68:71]
	s_waitcnt vmcnt(4) lgkmcnt(0)
	s_barrier
	ds_read_b128 v[174:177], v154 offset:16384
	ds_read_b128 v[182:185], v154 offset:18432
	s_add_u32 s26, s65, s58
	s_addc_u32 s27, s66, 0
	s_mov_b32 m0, s49
	s_nop 0
	global_load_lds_dwordx4 v139, s[26:27]
	s_mov_b32 m0, s53
	s_nop 0
	global_load_lds_dwordx4 v152, s[26:27]
	s_waitcnt lgkmcnt(1)
	v_mfma_f32_16x16x32_bf16 v[64:67], v[146:149], v[174:177], v[64:67]
	ds_read_b128 v[190:193], v154 offset:20480
	v_mfma_f32_16x16x32_bf16 v[60:63], v[160:163], v[174:177], v[60:63]
	ds_read_b128 v[198:201], v154 offset:22528
	s_waitcnt lgkmcnt(2)
	v_mfma_f32_16x16x32_bf16 v[48:51], v[146:149], v[182:185], v[48:51]
	v_mfma_f32_16x16x32_bf16 v[44:47], v[160:163], v[182:185], v[44:47]
	ds_read_b128 v[178:181], v154 offset:17408
	s_waitcnt lgkmcnt(2)
	v_mfma_f32_16x16x32_bf16 v[32:35], v[146:149], v[190:193], v[32:35]
	v_mfma_f32_16x16x32_bf16 v[28:31], v[160:163], v[190:193], v[28:31]
	ds_read_b128 v[186:189], v154 offset:19456
	s_waitcnt lgkmcnt(2)
	v_mfma_f32_16x16x32_bf16 v[16:19], v[146:149], v[198:201], v[16:19]
	v_mfma_f32_16x16x32_bf16 v[12:15], v[160:163], v[198:201], v[12:15]
	ds_read_b128 v[194:197], v154 offset:21504
	s_waitcnt lgkmcnt(2)
	v_mfma_f32_16x16x32_bf16 v[64:67], v[156:159], v[178:181], v[64:67]
	v_mfma_f32_16x16x32_bf16 v[60:63], v[170:173], v[178:181], v[60:63]
	ds_read_b128 v[202:205], v154 offset:23552
	s_waitcnt lgkmcnt(2)
	v_mfma_f32_16x16x32_bf16 v[48:51], v[156:159], v[186:189], v[48:51]
	v_mfma_f32_16x16x32_bf16 v[44:47], v[170:173], v[186:189], v[44:47]
	s_waitcnt lgkmcnt(1)
	v_mfma_f32_16x16x32_bf16 v[32:35], v[156:159], v[194:197], v[32:35]
	v_mfma_f32_16x16x32_bf16 v[28:31], v[170:173], v[194:197], v[28:31]
	s_waitcnt lgkmcnt(0)
	v_mfma_f32_16x16x32_bf16 v[16:19], v[156:159], v[202:205], v[16:19]
	v_mfma_f32_16x16x32_bf16 v[12:15], v[170:173], v[202:205], v[12:15]
	s_add_u32 s26, s63, s58
	s_addc_u32 s27, s64, 0
	s_mov_b32 m0, s50
	s_nop 0
	global_load_lds_dwordx4 v138, s[26:27]
	s_mov_b32 m0, s54
	s_nop 0
	global_load_lds_dwordx4 v140, s[26:27]
	v_mfma_f32_16x16x32_bf16 v[56:59], v[206:209], v[174:177], v[56:59]
	s_add_u32 s26, s61, s58
	s_addc_u32 s27, s62, 0
	s_add_u32 s71, s59, s58
	v_mfma_f32_16x16x32_bf16 v[52:55], v[214:217], v[174:177], v[52:55]
	s_addc_u32 s72, s60, 0
	v_mfma_f32_16x16x32_bf16 v[40:43], v[206:209], v[182:185], v[40:43]
	v_mfma_f32_16x16x32_bf16 v[36:39], v[214:217], v[182:185], v[36:39]
	v_mfma_f32_16x16x32_bf16 v[24:27], v[206:209], v[190:193], v[24:27]
	v_mfma_f32_16x16x32_bf16 v[20:23], v[214:217], v[190:193], v[20:23]
	v_mfma_f32_16x16x32_bf16 v[8:11], v[206:209], v[198:201], v[8:11]
	v_mfma_f32_16x16x32_bf16 v[4:7], v[214:217], v[198:201], v[4:7]
	v_mfma_f32_16x16x32_bf16 v[56:59], v[210:213], v[178:181], v[56:59]
	v_mfma_f32_16x16x32_bf16 v[52:55], v[218:221], v[178:181], v[52:55]
	v_mfma_f32_16x16x32_bf16 v[40:43], v[210:213], v[186:189], v[40:43]
	v_mfma_f32_16x16x32_bf16 v[36:39], v[218:221], v[186:189], v[36:39]
	v_mfma_f32_16x16x32_bf16 v[24:27], v[210:213], v[194:197], v[24:27]
	v_mfma_f32_16x16x32_bf16 v[20:23], v[218:221], v[194:197], v[20:23]
	v_mfma_f32_16x16x32_bf16 v[8:11], v[210:213], v[202:205], v[8:11]
	v_mfma_f32_16x16x32_bf16 v[4:7], v[218:221], v[202:205], v[4:7]
	s_waitcnt vmcnt(2) lgkmcnt(0)
	s_barrier
; template <class Epi, class Sched>
; __device__ __forceinline__ void gemm_simple(PG8_LAS unsigned char* lds, const Gemm g, const Sched& S, const Epi& E, int wave_s) {
;     ...
;             const char* a2 = last ? nA : cA + (size_t)(t + 2) * kstep; const char* b2 = last ? nB : cB + (size_t)(t + 2) * kstep;
	ds_read_b128 v[146:149], v134
	ds_read_b128 v[174:177], v154 offset:32768
	ds_read_b128 v[160:163], v134 offset:2048
	ds_read_b128 v[182:185], v154 offset:34816
	s_cmp_eq_u32 s58, s24
	s_cselect_b32 s27, s11, s27
	s_cselect_b32 s26, s21, s26
	s_cselect_b32 s73, s5, s72
	s_cselect_b32 s72, s23, s71
	s_mov_b32 m0, s40
	s_nop 0
	global_load_lds_dwordx4 v139, s[72:73]
	s_mov_b32 m0, s41
	s_nop 0
	global_load_lds_dwordx4 v152, s[72:73]
	s_waitcnt lgkmcnt(2)
	v_mfma_f32_16x16x32_bf16 v[128:131], v[146:149], v[174:177], v[128:131]
	ds_read_b128 v[190:193], v154 offset:36864
	s_waitcnt lgkmcnt(2)
	v_mfma_f32_16x16x32_bf16 v[124:127], v[160:163], v[174:177], v[124:127]
	ds_read_b128 v[198:201], v154 offset:38912
	s_waitcnt lgkmcnt(2)
	v_mfma_f32_16x16x32_bf16 v[112:115], v[146:149], v[182:185], v[112:115]
	v_mfma_f32_16x16x32_bf16 v[108:111], v[160:163], v[182:185], v[108:111]
	ds_read_b128 v[156:159], v134 offset:1024
	ds_read_b128 v[178:181], v154 offset:33792
	s_waitcnt lgkmcnt(3)
	v_mfma_f32_16x16x32_bf16 v[96:99], v[146:149], v[190:193], v[96:99]
	ds_read_b128 v[170:173], v134 offset:3072
	v_mfma_f32_16x16x32_bf16 v[92:95], v[160:163], v[190:193], v[92:95]
	ds_read_b128 v[186:189], v154 offset:35840
	s_waitcnt lgkmcnt(4)
	v_mfma_f32_16x16x32_bf16 v[80:83], v[146:149], v[198:201], v[80:83]
	v_mfma_f32_16x16x32_bf16 v[76:79], v[160:163], v[198:201], v[76:79]
	ds_read_b128 v[194:197], v154 offset:37888
	s_waitcnt lgkmcnt(3)
	v_mfma_f32_16x16x32_bf16 v[128:131], v[156:159], v[178:181], v[128:131]
	s_waitcnt lgkmcnt(2)
	v_mfma_f32_16x16x32_bf16 v[124:127], v[170:173], v[178:181], v[124:127]
	ds_read_b128 v[202:205], v154 offset:39936
	s_waitcnt lgkmcnt(2)
	v_mfma_f32_16x16x32_bf16 v[112:115], v[156:159], v[186:189], v[112:115]
	v_mfma_f32_16x16x32_bf16 v[108:111], v[170:173], v[186:189], v[108:111]
	ds_read_b128 v[206:209], v135
	s_waitcnt lgkmcnt(2)
	v_mfma_f32_16x16x32_bf16 v[96:99], v[156:159], v[194:197], v[96:99]
	ds_read_b128 v[214:217], v135 offset:2048
	v_mfma_f32_16x16x32_bf16 v[92:95], v[170:173], v[194:197], v[92:95]
	s_waitcnt lgkmcnt(2)
	v_mfma_f32_16x16x32_bf16 v[80:83], v[156:159], v[202:205], v[80:83]
	v_mfma_f32_16x16x32_bf16 v[76:79], v[170:173], v[202:205], v[76:79]
	s_mov_b32 m0, s39
	s_nop 0
	global_load_lds_dwordx4 v138, s[26:27]
	s_mov_b32 m0, s42
	s_nop 0
	global_load_lds_dwordx4 v140, s[26:27]
	s_waitcnt lgkmcnt(1)
	v_mfma_f32_16x16x32_bf16 v[120:123], v[206:209], v[174:177], v[120:123]
	s_waitcnt lgkmcnt(0)
	v_mfma_f32_16x16x32_bf16 v[116:119], v[214:217], v[174:177], v[116:119]
	v_mfma_f32_16x16x32_bf16 v[104:107], v[206:209], v[182:185], v[104:107]
	v_mfma_f32_16x16x32_bf16 v[100:103], v[214:217], v[182:185], v[100:103]
	ds_read_b128 v[210:213], v135 offset:1024
	v_mfma_f32_16x16x32_bf16 v[88:91], v[206:209], v[190:193], v[88:91]
	ds_read_b128 v[218:221], v135 offset:3072
	v_mfma_f32_16x16x32_bf16 v[84:87], v[214:217], v[190:193], v[84:87]
	v_mfma_f32_16x16x32_bf16 v[72:75], v[206:209], v[198:201], v[72:75]
	v_mfma_f32_16x16x32_bf16 v[68:71], v[214:217], v[198:201], v[68:71]
	s_waitcnt lgkmcnt(1)
	v_mfma_f32_16x16x32_bf16 v[120:123], v[210:213], v[178:181], v[120:123]
	s_waitcnt lgkmcnt(0)
	v_mfma_f32_16x16x32_bf16 v[116:119], v[218:221], v[178:181], v[116:119]
	v_mfma_f32_16x16x32_bf16 v[104:107], v[210:213], v[186:189], v[104:107]
	v_mfma_f32_16x16x32_bf16 v[100:103], v[218:221], v[186:189], v[100:103]
	v_mfma_f32_16x16x32_bf16 v[88:91], v[210:213], v[194:197], v[88:91]
	v_mfma_f32_16x16x32_bf16 v[84:87], v[218:221], v[194:197], v[84:87]
	v_mfma_f32_16x16x32_bf16 v[72:75], v[210:213], v[202:205], v[72:75]
	v_mfma_f32_16x16x32_bf16 v[68:71], v[218:221], v[202:205], v[68:71]
	s_waitcnt vmcnt(4) lgkmcnt(0)
	s_barrier
	ds_read_b128 v[174:177], v154 offset:49152
	ds_read_b128 v[182:185], v154 offset:51200
	s_add_u32 s72, s72, 0x80000
	s_addc_u32 s73, s73, 0
	s_mov_b32 m0, s43
	s_nop 0
	global_load_lds_dwordx4 v139, s[72:73]
	s_mov_b32 m0, s44
	s_nop 0
	global_load_lds_dwordx4 v152, s[72:73]
	s_waitcnt lgkmcnt(1)
	v_mfma_f32_16x16x32_bf16 v[64:67], v[146:149], v[174:177], v[64:67]
	ds_read_b128 v[190:193], v154 offset:53248
	v_mfma_f32_16x16x32_bf16 v[60:63], v[160:163], v[174:177], v[60:63]
	ds_read_b128 v[198:201], v154 offset:55296
	s_waitcnt lgkmcnt(2)
	v_mfma_f32_16x16x32_bf16 v[48:51], v[146:149], v[182:185], v[48:51]
	v_mfma_f32_16x16x32_bf16 v[44:47], v[160:163], v[182:185], v[44:47]
	ds_read_b128 v[178:181], v154 offset:50176
	s_waitcnt lgkmcnt(2)
	v_mfma_f32_16x16x32_bf16 v[32:35], v[146:149], v[190:193], v[32:35]
	v_mfma_f32_16x16x32_bf16 v[28:31], v[160:163], v[190:193], v[28:31]
	ds_read_b128 v[186:189], v154 offset:52224
	s_waitcnt lgkmcnt(2)
	v_mfma_f32_16x16x32_bf16 v[16:19], v[146:149], v[198:201], v[16:19]
	v_mfma_f32_16x16x32_bf16 v[12:15], v[160:163], v[198:201], v[12:15]
	ds_read_b128 v[194:197], v154 offset:54272
	s_waitcnt lgkmcnt(2)
	v_mfma_f32_16x16x32_bf16 v[64:67], v[156:159], v[178:181], v[64:67]
	v_mfma_f32_16x16x32_bf16 v[60:63], v[170:173], v[178:181], v[60:63]
	ds_read_b128 v[202:205], v154 offset:56320
	s_waitcnt lgkmcnt(2)
	v_mfma_f32_16x16x32_bf16 v[48:51], v[156:159], v[186:189], v[48:51]
	v_mfma_f32_16x16x32_bf16 v[44:47], v[170:173], v[186:189], v[44:47]
	s_waitcnt lgkmcnt(1)
	v_mfma_f32_16x16x32_bf16 v[32:35], v[156:159], v[194:197], v[32:35]
	v_mfma_f32_16x16x32_bf16 v[28:31], v[170:173], v[194:197], v[28:31]
	s_waitcnt lgkmcnt(0)
; __device__ __forceinline__ unsigned cvt_pk_bf16(float lo, float hi) { unsigned r; asm volatile("v_cvt_pk_bf16_f32 %0, %1, %2" : "=v"(r) : "v"(lo), "v"(hi)); return r; }
; __device__ __forceinline__ float bflo(unsigned w) { return __uint_as_float(w << 16); }
; __device__ __forceinline__ float bfhi(unsigned w) { return __uint_as_float(w & 0xffff0000u); }
; __device__ __forceinline__ float sigmoidf_(float y) { return __builtin_amdgcn_rcpf(1.0f + __builtin_amdgcn_exp2f(-1.4426950408889634f * y)); }
;     __device__ __forceinline__ void operator()(const f32x4 (&acc)[2][2][4][2], const Unit& u, int wr, int wc, int fr, int fq, const LAS float* rt) const {
;     ...
;             for (int m = 0; m < 4; ++m) { const size_t row = (size_t)(row0 + ai * 128 + m * 16); const float rs = (MODE == 1) ? rt[ai * 128 + wr * 64 + m * 16 + fr] : 1.0f; float ss = 0.f;
; #pragma unroll
;                 for (int bj = 0; bj < 2; ++bj) { const size_t o = row * DM + col0 + bj * 128; const u32x4 xv = *(const u32x4*)(xin + o);
;                     f32x4 v0 = acc[ai][bj][m][0], v1 = acc[ai][bj][m][1];
;                     if (MODE == 1) { const u32x4 p = *(const u32x4*)(pe + o);
;                         v0[0] = sigmoidf_(v0[0] * rs) * bflo(p.x); v0[1] = sigmoidf_(v0[1] * rs) * bfhi(p.x); v0[2] = sigmoidf_(v0[2] * rs) * bflo(p.y); v0[3] = sigmoidf_(v0[3] * rs) * bfhi(p.y);
;                         v1[0] = sigmoidf_(v1[0] * rs) * bflo(p.z); v1[1] = sigmoidf_(v1[1] * rs) * bfhi(p.z); v1[2] = sigmoidf_(v1[2] * rs) * bflo(p.w); v1[3] = sigmoidf_(v1[3] * rs) * bfhi(p.w); }
;                     v0[0] += bflo(xv.x); v0[1] += bfhi(xv.x); v0[2] += bflo(xv.y); v0[3] += bfhi(xv.y); v1[0] += bflo(xv.z); v1[1] += bfhi(xv.z); v1[2] += bflo(xv.w); v1[3] += bfhi(xv.w);
;                     ss += (v0[0] * v0[0] + v0[1] * v0[1]) + (v0[2] * v0[2] + v0[3] * v0[3]) + (v1[0] * v1[0] + v1[1] * v1[1]) + (v1[2] * v1[2] + v1[3] * v1[3]);
;                     u32x4 w; w.x = cvt_pk_bf16(v0[0], v0[1]); w.y = cvt_pk_bf16(v0[2], v0[3]); w.z = cvt_pk_bf16(v1[0], v1[1]); w.w = cvt_pk_bf16(v1[2], v1[3]);
;                     __builtin_nontemporal_store(w, (u32x4*)(xout + o)); }
;                 ss += shx(ss, 16, lane); ss += shx(ss, 32, lane);
;                 if (fq == 0) ssq_out[row * 32 + u.pn * 4 + wc] = ss; }
	v_mfma_f32_16x16x32_bf16 v[16:19], v[156:159], v[202:205], v[16:19]
	v_mfma_f32_16x16x32_bf16 v[12:15], v[170:173], v[202:205], v[12:15]
	s_add_u32 s26, s26, 0x80000
	s_addc_u32 s27, s27, 0
	s_mov_b32 m0, s45
	s_nop 0
	global_load_lds_dwordx4 v138, s[26:27]
	s_mov_b32 m0, s46
	s_nop 0
	global_load_lds_dwordx4 v140, s[26:27]
	s_add_i32 s35, s35, 2
	s_add_u32 s24, s24, 0xffffff00
	s_addc_u32 s25, s25, -1
	s_add_u32 s59, s59, 0x100
	s_addc_u32 s60, s60, 0
	s_add_u32 s61, s61, 0x100
	s_addc_u32 s62, s62, 0
	s_add_u32 s63, s63, 0x100
	v_mfma_f32_16x16x32_bf16 v[56:59], v[206:209], v[174:177], v[56:59]
	s_addc_u32 s64, s64, 0
	s_add_u32 s65, s65, 0x100
	s_addc_u32 s66, s66, 0
	v_mfma_f32_16x16x32_bf16 v[52:55], v[214:217], v[174:177], v[52:55]
	s_add_u32 s67, s67, 0x100
	s_addc_u32 s68, s68, 0
	s_add_u32 s69, s69, 0x100
	v_mfma_f32_16x16x32_bf16 v[40:43], v[206:209], v[182:185], v[40:43]
	s_addc_u32 s70, s70, 0
	s_cmp_lt_u32 s35, 30
	v_mfma_f32_16x16x32_bf16 v[36:39], v[214:217], v[182:185], v[36:39]
	v_mfma_f32_16x16x32_bf16 v[24:27], v[206:209], v[190:193], v[24:27]
	v_mfma_f32_16x16x32_bf16 v[20:23], v[214:217], v[190:193], v[20:23]
	v_mfma_f32_16x16x32_bf16 v[8:11], v[206:209], v[198:201], v[8:11]
	v_mfma_f32_16x16x32_bf16 v[4:7], v[214:217], v[198:201], v[4:7]
	v_mfma_f32_16x16x32_bf16 v[56:59], v[210:213], v[178:181], v[56:59]
	v_mfma_f32_16x16x32_bf16 v[52:55], v[218:221], v[178:181], v[52:55]
	v_mfma_f32_16x16x32_bf16 v[40:43], v[210:213], v[186:189], v[40:43]
	v_mfma_f32_16x16x32_bf16 v[36:39], v[218:221], v[186:189], v[36:39]
	v_mfma_f32_16x16x32_bf16 v[24:27], v[210:213], v[194:197], v[24:27]
	v_mfma_f32_16x16x32_bf16 v[20:23], v[218:221], v[194:197], v[20:23]
	v_mfma_f32_16x16x32_bf16 v[8:11], v[210:213], v[202:205], v[8:11]
	v_mfma_f32_16x16x32_bf16 v[4:7], v[218:221], v[202:205], v[4:7]
	s_cbranch_scc1 .LBB0_119
	v_mov_b32_e32 v132, v141
	s_lshl_b32 s5, s22, 8
	v_mbcnt_lo_u32_b32 v132, -1, v132
	v_mbcnt_hi_u32_b32 v135, -1, v132
	v_and_b32_e32 v136, 15, v135
	s_add_i32 s5, s5, s37
	v_or_b32_e32 v134, s5, v136
	s_lshl_b32 s5, s20, 8
	v_ashrrev_i32_e32 v137, 4, v135
	s_or_b32 s5, s5, s38
	v_lshl_add_u32 v132, v137, 3, s5
	v_lshlrev_b32_e32 v137, 6, v137
	v_lshlrev_b32_e32 v136, 2, v136
	s_movk_i32 s5, 0x80
	v_cmp_gt_u32_e32 vcc, 16, v135
	v_ashrrev_i32_e32 v135, 31, v134
	v_bitop3_b32 v156, v137, 64, v136 bitop3:0x36
	v_bitop3_b32 v155, v137, s5, v136 bitop3:0x36
	v_lshlrev_b64 v[136:137], 12, v[134:135]
	v_ashrrev_i32_e32 v133, 31, v132
	v_lshl_add_u64 v[136:137], s[94:95], 0, v[136:137]
	v_lshl_add_u64 v[136:137], v[132:133], 1, v[136:137]
	v_lshlrev_b32_e32 v236, 12, v134
	v_lshl_add_u32 v236, v132, 1, v236
	global_load_dwordx4 v[172:175], v236, s[94:95]
	global_load_dwordx4 v[176:179], v236, s[94:95] offset:256
	v_add_u32_e32 v237, 0x10000, v236
	global_load_dwordx4 v[180:183], v237, s[94:95]
	global_load_dwordx4 v[184:187], v237, s[94:95] offset:256
	v_add_u32_e32 v237, 0x20000, v236
	global_load_dwordx4 v[188:191], v237, s[94:95]
	global_load_dwordx4 v[192:195], v237, s[94:95] offset:256
	v_add_u32_e32 v237, 0x30000, v236
	global_load_dwordx4 v[196:199], v237, s[94:95]
	global_load_dwordx4 v[200:203], v237, s[94:95] offset:256
	v_add_u32_e32 v237, 0x80000, v236
	global_load_dwordx4 v[204:207], v237, s[94:95]
	global_load_dwordx4 v[208:211], v237, s[94:95] offset:256
	v_add_u32_e32 v237, 0x90000, v236
	global_load_dwordx4 v[212:215], v237, s[94:95]
	global_load_dwordx4 v[216:219], v237, s[94:95] offset:256
	v_add_u32_e32 v237, 0xa0000, v236
	global_load_dwordx4 v[220:223], v237, s[94:95]
	global_load_dwordx4 v[224:227], v237, s[94:95] offset:256
	v_add_u32_e32 v237, 0xb0000, v236
	global_load_dwordx4 v[228:231], v237, s[94:95]
	global_load_dwordx4 v[232:235], v237, s[94:95] offset:256
	s_lshl_b32 s20, s20, 2
	s_ashr_i32 s21, s20, 31
	s_waitcnt vmcnt(15)
	s_nop 1
	v_mov_b64_e32 v[146:147], v[172:173]
	v_mov_b64_e32 v[148:149], v[174:175]
	v_lshlrev_b32_e32 v142, 16, v146
	v_add_f32_e32 v128, v128, v142
	v_and_b32_e32 v142, 0xffff0000, v146
	v_add_f32_e32 v129, v129, v142
	v_lshlrev_b32_e32 v142, 16, v147
	v_add_f32_e32 v130, v130, v142
	v_and_b32_e32 v142, 0xffff0000, v147
	v_add_f32_e32 v131, v131, v142
	v_lshlrev_b32_e32 v142, 16, v148
	v_add_f32_e32 v142, v124, v142
	v_and_b32_e32 v124, 0xffff0000, v148
	v_add_f32_e32 v143, v125, v124
	v_lshlrev_b32_e32 v124, 16, v149
	v_add_f32_e32 v144, v126, v124
	v_and_b32_e32 v124, 0xffff0000, v149
	v_add_f32_e32 v127, v127, v124
	v_mul_f32_e32 v124, v129, v129
	v_mul_f32_e32 v125, v131, v131
	v_fmac_f32_e32 v124, v128, v128
	v_fmac_f32_e32 v125, v130, v130
	v_add_f32_e32 v124, v124, v125
	v_mul_f32_e32 v125, v143, v143
	v_fmac_f32_e32 v125, v142, v142
	v_add_f32_e32 v124, v125, v124
	v_mul_f32_e32 v125, v127, v127
	v_fmac_f32_e32 v125, v144, v144
	v_add_f32_e32 v145, v125, v124
	v_cvt_pk_bf16_f32 v124, v128, v129
	v_cvt_pk_bf16_f32 v125, v130, v131
	v_cvt_pk_bf16_f32 v126, v142, v143
	v_cvt_pk_bf16_f32 v127, v144, v127
	global_store_dwordx4 v[136:137], v[124:127], off nt
	s_waitcnt vmcnt(15)
	s_nop 1
	v_mov_b64_e32 v[124:125], v[176:177]
	v_mov_b64_e32 v[126:127], v[178:179]
	v_lshlrev_b32_e32 v128, 16, v124
	v_and_b32_e32 v124, 0xffff0000, v124
	v_add_f32_e32 v121, v121, v124
	v_lshlrev_b32_e32 v124, 16, v125
	v_add_f32_e32 v122, v122, v124
	v_and_b32_e32 v124, 0xffff0000, v125
	v_add_f32_e32 v123, v123, v124
	v_lshlrev_b32_e32 v124, 16, v126
	v_add_f32_e32 v124, v116, v124
	v_and_b32_e32 v116, 0xffff0000, v126
	v_add_f32_e32 v125, v117, v116
	v_lshlrev_b32_e32 v116, 16, v127
	v_add_f32_e32 v126, v118, v116
	v_and_b32_e32 v116, 0xffff0000, v127
	v_add_f32_e32 v120, v120, v128
	v_add_f32_e32 v119, v119, v116
	v_mul_f32_e32 v116, v121, v121
	v_mul_f32_e32 v117, v123, v123
	v_fmac_f32_e32 v116, v120, v120
	v_fmac_f32_e32 v117, v122, v122
	v_add_f32_e32 v116, v116, v117
	v_mul_f32_e32 v117, v125, v125
	v_fmac_f32_e32 v117, v124, v124
	v_add_f32_e32 v116, v117, v116
	v_mul_f32_e32 v117, v119, v119
	v_fmac_f32_e32 v117, v126, v126
	v_add_f32_e32 v116, v117, v116
	v_add_f32_e32 v127, v145, v116
	v_cvt_pk_bf16_f32 v116, v120, v121
	v_cvt_pk_bf16_f32 v117, v122, v123
	v_cvt_pk_bf16_f32 v118, v124, v125
	v_cvt_pk_bf16_f32 v119, v126, v119
	global_store_dwordx4 v[136:137], v[116:119], off offset:256 nt
	ds_bpermute_b32 v116, v156, v127
	s_waitcnt lgkmcnt(0)
	v_add_f32_e32 v116, v127, v116
	ds_bpermute_b32 v117, v155, v116
	s_and_saveexec_b64 s[22:23], vcc
	s_cbranch_execz .LBB0_122
	v_lshlrev_b64 v[118:119], 7, v[134:135]
	v_lshl_add_u64 v[118:119], s[0:1], 0, v[118:119]
	v_lshl_add_u64 v[118:119], s[20:21], 2, v[118:119]
	s_lshl_b32 s84, s36, 2
	v_lshl_add_u64 v[118:119], v[118:119], 0, s[84:85]
	s_waitcnt lgkmcnt(0)
	v_add_f32_e32 v116, v116, v117
	global_store_dword v[118:119], v116, off

.LBB0_173:
	s_waitcnt vmcnt(2) lgkmcnt(0)
	s_barrier
	ds_read_b128 v[146:149], v132
	ds_read_b128 v[174:177], v152
	ds_read_b128 v[158:161], v132 offset:2048
	ds_read_b128 v[182:185], v152 offset:2048
	s_add_u32 s60, s20, s59
	s_addc_u32 s61, s21, 0
	s_add_u32 s26, s60, 0x80
	s_addc_u32 s27, s61, 0
	s_mov_b32 m0, s46
	s_nop 0
	global_load_lds_dwordx4 v137, s[26:27]
	s_mov_b32 m0, s50
	s_nop 0
	global_load_lds_dwordx4 v139, s[26:27]
	s_waitcnt lgkmcnt(2)
	v_mfma_f32_16x16x32_bf16 v[128:131], v[146:149], v[174:177], v[128:131]
	ds_read_b128 v[190:193], v152 offset:4096
	s_waitcnt lgkmcnt(2)
	v_mfma_f32_16x16x32_bf16 v[124:127], v[158:161], v[174:177], v[124:127]
	ds_read_b128 v[198:201], v152 offset:6144
	s_waitcnt lgkmcnt(2)
	v_mfma_f32_16x16x32_bf16 v[112:115], v[146:149], v[182:185], v[112:115]
	v_mfma_f32_16x16x32_bf16 v[108:111], v[158:161], v[182:185], v[108:111]
	ds_read_b128 v[154:157], v132 offset:1024
	ds_read_b128 v[178:181], v152 offset:1024
	s_waitcnt lgkmcnt(3)
	v_mfma_f32_16x16x32_bf16 v[96:99], v[146:149], v[190:193], v[96:99]
	ds_read_b128 v[170:173], v132 offset:3072
	v_mfma_f32_16x16x32_bf16 v[92:95], v[158:161], v[190:193], v[92:95]
	ds_read_b128 v[186:189], v152 offset:3072
	s_waitcnt lgkmcnt(4)
	v_mfma_f32_16x16x32_bf16 v[80:83], v[146:149], v[198:201], v[80:83]
	v_mfma_f32_16x16x32_bf16 v[76:79], v[158:161], v[198:201], v[76:79]
	ds_read_b128 v[194:197], v152 offset:5120
	s_waitcnt lgkmcnt(3)
	v_mfma_f32_16x16x32_bf16 v[128:131], v[154:157], v[178:181], v[128:131]
	s_waitcnt lgkmcnt(2)
	v_mfma_f32_16x16x32_bf16 v[124:127], v[170:173], v[178:181], v[124:127]
	ds_read_b128 v[202:205], v152 offset:7168
	s_waitcnt lgkmcnt(2)
	v_mfma_f32_16x16x32_bf16 v[112:115], v[154:157], v[186:189], v[112:115]
	v_mfma_f32_16x16x32_bf16 v[108:111], v[170:173], v[186:189], v[108:111]
	ds_read_b128 v[206:209], v133
	s_waitcnt lgkmcnt(2)
	v_mfma_f32_16x16x32_bf16 v[96:99], v[154:157], v[194:197], v[96:99]
	ds_read_b128 v[214:217], v133 offset:2048
	v_mfma_f32_16x16x32_bf16 v[92:95], v[170:173], v[194:197], v[92:95]
	s_waitcnt lgkmcnt(2)
	v_mfma_f32_16x16x32_bf16 v[80:83], v[154:157], v[202:205], v[80:83]
	v_mfma_f32_16x16x32_bf16 v[76:79], v[170:173], v[202:205], v[76:79]
	s_add_u32 s62, s22, s59
	s_addc_u32 s63, s23, 0
	s_add_u32 s26, s62, 0x80
	s_addc_u32 s27, s63, 0
	s_mov_b32 m0, s47
	s_nop 0
	global_load_lds_dwordx4 v136, s[26:27]
	s_mov_b32 m0, s51
	s_nop 0
	global_load_lds_dwordx4 v138, s[26:27]
	s_waitcnt lgkmcnt(1)
	v_mfma_f32_16x16x32_bf16 v[120:123], v[206:209], v[174:177], v[120:123]
	s_waitcnt lgkmcnt(0)
	v_mfma_f32_16x16x32_bf16 v[116:119], v[214:217], v[174:177], v[116:119]
	v_mfma_f32_16x16x32_bf16 v[104:107], v[206:209], v[182:185], v[104:107]
	v_mfma_f32_16x16x32_bf16 v[100:103], v[214:217], v[182:185], v[100:103]
	ds_read_b128 v[210:213], v133 offset:1024
	v_mfma_f32_16x16x32_bf16 v[88:91], v[206:209], v[190:193], v[88:91]
	ds_read_b128 v[218:221], v133 offset:3072
	v_mfma_f32_16x16x32_bf16 v[84:87], v[214:217], v[190:193], v[84:87]
	v_mfma_f32_16x16x32_bf16 v[72:75], v[206:209], v[198:201], v[72:75]
	v_mfma_f32_16x16x32_bf16 v[68:71], v[214:217], v[198:201], v[68:71]
	s_waitcnt lgkmcnt(1)
	v_mfma_f32_16x16x32_bf16 v[120:123], v[210:213], v[178:181], v[120:123]
	s_waitcnt lgkmcnt(0)
	v_mfma_f32_16x16x32_bf16 v[116:119], v[218:221], v[178:181], v[116:119]
	v_mfma_f32_16x16x32_bf16 v[104:107], v[210:213], v[186:189], v[104:107]
	v_mfma_f32_16x16x32_bf16 v[100:103], v[218:221], v[186:189], v[100:103]
	v_mfma_f32_16x16x32_bf16 v[88:91], v[210:213], v[194:197], v[88:91]
	v_mfma_f32_16x16x32_bf16 v[84:87], v[218:221], v[194:197], v[84:87]
	v_mfma_f32_16x16x32_bf16 v[72:75], v[210:213], v[202:205], v[72:75]
	v_mfma_f32_16x16x32_bf16 v[68:71], v[218:221], v[202:205], v[68:71]
	s_waitcnt vmcnt(4) lgkmcnt(0)
	s_barrier
	ds_read_b128 v[174:177], v152 offset:16384
	ds_read_b128 v[182:185], v152 offset:18432
	s_add_u32 s26, s60, 0x40080
	s_addc_u32 s27, s61, 0
	s_mov_b32 m0, s48
	s_nop 0
	global_load_lds_dwordx4 v137, s[26:27]
	s_mov_b32 m0, s52
	s_nop 0
	global_load_lds_dwordx4 v139, s[26:27]
	s_waitcnt lgkmcnt(1)
	v_mfma_f32_16x16x32_bf16 v[64:67], v[146:149], v[174:177], v[64:67]
	ds_read_b128 v[190:193], v152 offset:20480
	v_mfma_f32_16x16x32_bf16 v[60:63], v[158:161], v[174:177], v[60:63]
	ds_read_b128 v[198:201], v152 offset:22528
	s_waitcnt lgkmcnt(2)
	v_mfma_f32_16x16x32_bf16 v[48:51], v[146:149], v[182:185], v[48:51]
	v_mfma_f32_16x16x32_bf16 v[44:47], v[158:161], v[182:185], v[44:47]
	ds_read_b128 v[178:181], v152 offset:17408
	s_waitcnt lgkmcnt(2)
	v_mfma_f32_16x16x32_bf16 v[32:35], v[146:149], v[190:193], v[32:35]
	v_mfma_f32_16x16x32_bf16 v[28:31], v[158:161], v[190:193], v[28:31]
	ds_read_b128 v[186:189], v152 offset:19456
	s_waitcnt lgkmcnt(2)
	v_mfma_f32_16x16x32_bf16 v[16:19], v[146:149], v[198:201], v[16:19]
	v_mfma_f32_16x16x32_bf16 v[12:15], v[158:161], v[198:201], v[12:15]
	ds_read_b128 v[194:197], v152 offset:21504
	s_waitcnt lgkmcnt(2)
	v_mfma_f32_16x16x32_bf16 v[64:67], v[154:157], v[178:181], v[64:67]
	v_mfma_f32_16x16x32_bf16 v[60:63], v[170:173], v[178:181], v[60:63]
	ds_read_b128 v[202:205], v152 offset:23552
	s_waitcnt lgkmcnt(2)
	v_mfma_f32_16x16x32_bf16 v[48:51], v[154:157], v[186:189], v[48:51]
	v_mfma_f32_16x16x32_bf16 v[44:47], v[170:173], v[186:189], v[44:47]
	s_waitcnt lgkmcnt(1)
	v_mfma_f32_16x16x32_bf16 v[32:35], v[154:157], v[194:197], v[32:35]
	v_mfma_f32_16x16x32_bf16 v[28:31], v[170:173], v[194:197], v[28:31]
	s_waitcnt lgkmcnt(0)
	v_mfma_f32_16x16x32_bf16 v[16:19], v[154:157], v[202:205], v[16:19]
	v_mfma_f32_16x16x32_bf16 v[12:15], v[170:173], v[202:205], v[12:15]
	s_add_u32 s26, s62, 0x40080
	s_addc_u32 s27, s63, 0
	s_mov_b32 m0, s49
	s_nop 0
	global_load_lds_dwordx4 v136, s[26:27]
	s_mov_b32 m0, s53
	s_nop 0
	global_load_lds_dwordx4 v138, s[26:27]
	v_mfma_f32_16x16x32_bf16 v[56:59], v[206:209], v[174:177], v[56:59]
	s_add_u32 s26, s62, 0x100
	s_addc_u32 s27, s63, 0
	s_add_u32 s60, s60, 0x100
	v_mfma_f32_16x16x32_bf16 v[52:55], v[214:217], v[174:177], v[52:55]
	s_addc_u32 s61, s61, 0
	v_mfma_f32_16x16x32_bf16 v[40:43], v[206:209], v[182:185], v[40:43]
	v_mfma_f32_16x16x32_bf16 v[36:39], v[214:217], v[182:185], v[36:39]
	v_mfma_f32_16x16x32_bf16 v[24:27], v[206:209], v[190:193], v[24:27]
	v_mfma_f32_16x16x32_bf16 v[20:23], v[214:217], v[190:193], v[20:23]
	v_mfma_f32_16x16x32_bf16 v[4:7], v[206:209], v[198:201], v[4:7]
	v_mfma_f32_16x16x32_bf16 v[8:11], v[214:217], v[198:201], v[8:11]
	v_mfma_f32_16x16x32_bf16 v[56:59], v[210:213], v[178:181], v[56:59]
	v_mfma_f32_16x16x32_bf16 v[52:55], v[218:221], v[178:181], v[52:55]
	v_mfma_f32_16x16x32_bf16 v[40:43], v[210:213], v[186:189], v[40:43]
	v_mfma_f32_16x16x32_bf16 v[36:39], v[218:221], v[186:189], v[36:39]
	v_mfma_f32_16x16x32_bf16 v[24:27], v[210:213], v[194:197], v[24:27]
	v_mfma_f32_16x16x32_bf16 v[20:23], v[218:221], v[194:197], v[20:23]
	v_mfma_f32_16x16x32_bf16 v[4:7], v[210:213], v[202:205], v[4:7]
	v_mfma_f32_16x16x32_bf16 v[8:11], v[218:221], v[202:205], v[8:11]
	s_waitcnt vmcnt(2) lgkmcnt(0)
	s_barrier
; template <class Epi, class Sched>
; __device__ __forceinline__ void gemm_simple(PG8_LAS unsigned char* lds, const Gemm g, const Sched& S, const Epi& E, int wave_s) {
;     ...
;             const char* a2 = last ? nA : cA + (size_t)(t + 2) * kstep; const char* b2 = last ? nB : cB + (size_t)(t + 2) * kstep;
	ds_read_b128 v[146:149], v134
	ds_read_b128 v[174:177], v152 offset:32768
	ds_read_b128 v[158:161], v134 offset:2048
	ds_read_b128 v[182:185], v152 offset:34816
	s_cmp_eq_u32 s59, s24
	s_cselect_b32 s27, s9, s27
	s_cselect_b32 s26, s56, s26
	s_cselect_b32 s61, s5, s61
	s_cselect_b32 s60, s57, s60
	s_mov_b32 m0, s39
	s_nop 0
	global_load_lds_dwordx4 v137, s[60:61]
	s_mov_b32 m0, s40
	s_nop 0
	global_load_lds_dwordx4 v139, s[60:61]
	s_waitcnt lgkmcnt(2)
	v_mfma_f32_16x16x32_bf16 v[128:131], v[146:149], v[174:177], v[128:131]
	ds_read_b128 v[190:193], v152 offset:36864
	s_waitcnt lgkmcnt(2)
	v_mfma_f32_16x16x32_bf16 v[124:127], v[158:161], v[174:177], v[124:127]
	ds_read_b128 v[198:201], v152 offset:38912
	s_waitcnt lgkmcnt(2)
	v_mfma_f32_16x16x32_bf16 v[112:115], v[146:149], v[182:185], v[112:115]
	v_mfma_f32_16x16x32_bf16 v[108:111], v[158:161], v[182:185], v[108:111]
	ds_read_b128 v[154:157], v134 offset:1024
	ds_read_b128 v[178:181], v152 offset:33792
	s_waitcnt lgkmcnt(3)
	v_mfma_f32_16x16x32_bf16 v[96:99], v[146:149], v[190:193], v[96:99]
	ds_read_b128 v[170:173], v134 offset:3072
	v_mfma_f32_16x16x32_bf16 v[92:95], v[158:161], v[190:193], v[92:95]
	ds_read_b128 v[186:189], v152 offset:35840
	s_waitcnt lgkmcnt(4)
	v_mfma_f32_16x16x32_bf16 v[80:83], v[146:149], v[198:201], v[80:83]
	v_mfma_f32_16x16x32_bf16 v[76:79], v[158:161], v[198:201], v[76:79]
	ds_read_b128 v[194:197], v152 offset:37888
	s_waitcnt lgkmcnt(3)
	v_mfma_f32_16x16x32_bf16 v[128:131], v[154:157], v[178:181], v[128:131]
	s_waitcnt lgkmcnt(2)
	v_mfma_f32_16x16x32_bf16 v[124:127], v[170:173], v[178:181], v[124:127]
	ds_read_b128 v[202:205], v152 offset:39936
	s_waitcnt lgkmcnt(2)
	v_mfma_f32_16x16x32_bf16 v[112:115], v[154:157], v[186:189], v[112:115]
	v_mfma_f32_16x16x32_bf16 v[108:111], v[170:173], v[186:189], v[108:111]
	ds_read_b128 v[206:209], v135
	s_waitcnt lgkmcnt(2)
	v_mfma_f32_16x16x32_bf16 v[96:99], v[154:157], v[194:197], v[96:99]
	ds_read_b128 v[214:217], v135 offset:2048
	v_mfma_f32_16x16x32_bf16 v[92:95], v[170:173], v[194:197], v[92:95]
	s_waitcnt lgkmcnt(2)
	v_mfma_f32_16x16x32_bf16 v[80:83], v[154:157], v[202:205], v[80:83]
	v_mfma_f32_16x16x32_bf16 v[76:79], v[170:173], v[202:205], v[76:79]
	s_mov_b32 m0, s19
	s_nop 0
	global_load_lds_dwordx4 v136, s[26:27]
	s_mov_b32 m0, s41
	s_nop 0
	global_load_lds_dwordx4 v138, s[26:27]
	s_waitcnt lgkmcnt(1)
	v_mfma_f32_16x16x32_bf16 v[120:123], v[206:209], v[174:177], v[120:123]
	s_waitcnt lgkmcnt(0)
	v_mfma_f32_16x16x32_bf16 v[116:119], v[214:217], v[174:177], v[116:119]
	v_mfma_f32_16x16x32_bf16 v[104:107], v[206:209], v[182:185], v[104:107]
	v_mfma_f32_16x16x32_bf16 v[100:103], v[214:217], v[182:185], v[100:103]
	ds_read_b128 v[210:213], v135 offset:1024
	v_mfma_f32_16x16x32_bf16 v[88:91], v[206:209], v[190:193], v[88:91]
	ds_read_b128 v[218:221], v135 offset:3072
	v_mfma_f32_16x16x32_bf16 v[84:87], v[214:217], v[190:193], v[84:87]
	v_mfma_f32_16x16x32_bf16 v[72:75], v[206:209], v[198:201], v[72:75]
	v_mfma_f32_16x16x32_bf16 v[68:71], v[214:217], v[198:201], v[68:71]
	s_waitcnt lgkmcnt(1)
	v_mfma_f32_16x16x32_bf16 v[120:123], v[210:213], v[178:181], v[120:123]
	s_waitcnt lgkmcnt(0)
	v_mfma_f32_16x16x32_bf16 v[116:119], v[218:221], v[178:181], v[116:119]
	v_mfma_f32_16x16x32_bf16 v[104:107], v[210:213], v[186:189], v[104:107]
	v_mfma_f32_16x16x32_bf16 v[100:103], v[218:221], v[186:189], v[100:103]
	v_mfma_f32_16x16x32_bf16 v[88:91], v[210:213], v[194:197], v[88:91]
	v_mfma_f32_16x16x32_bf16 v[84:87], v[218:221], v[194:197], v[84:87]
	v_mfma_f32_16x16x32_bf16 v[72:75], v[210:213], v[202:205], v[72:75]
	v_mfma_f32_16x16x32_bf16 v[68:71], v[218:221], v[202:205], v[68:71]
	s_waitcnt vmcnt(4) lgkmcnt(0)
	s_barrier
	ds_read_b128 v[174:177], v152 offset:49152
	ds_read_b128 v[182:185], v152 offset:51200
	s_add_u32 s60, s60, 0x40000
	s_addc_u32 s61, s61, 0
	s_mov_b32 m0, s42
	s_nop 0
	global_load_lds_dwordx4 v137, s[60:61]
	s_mov_b32 m0, s43
	s_nop 0
	global_load_lds_dwordx4 v139, s[60:61]
	s_waitcnt lgkmcnt(1)
	v_mfma_f32_16x16x32_bf16 v[64:67], v[146:149], v[174:177], v[64:67]
	ds_read_b128 v[190:193], v152 offset:53248
	v_mfma_f32_16x16x32_bf16 v[60:63], v[158:161], v[174:177], v[60:63]
	ds_read_b128 v[198:201], v152 offset:55296
	s_waitcnt lgkmcnt(2)
	v_mfma_f32_16x16x32_bf16 v[48:51], v[146:149], v[182:185], v[48:51]
	v_mfma_f32_16x16x32_bf16 v[44:47], v[158:161], v[182:185], v[44:47]
	ds_read_b128 v[178:181], v152 offset:50176
	s_waitcnt lgkmcnt(2)
	v_mfma_f32_16x16x32_bf16 v[32:35], v[146:149], v[190:193], v[32:35]
	v_mfma_f32_16x16x32_bf16 v[28:31], v[158:161], v[190:193], v[28:31]
	ds_read_b128 v[186:189], v152 offset:52224
	s_waitcnt lgkmcnt(2)
	v_mfma_f32_16x16x32_bf16 v[16:19], v[146:149], v[198:201], v[16:19]
	v_mfma_f32_16x16x32_bf16 v[12:15], v[158:161], v[198:201], v[12:15]
	ds_read_b128 v[194:197], v152 offset:54272
	s_waitcnt lgkmcnt(2)
	v_mfma_f32_16x16x32_bf16 v[64:67], v[154:157], v[178:181], v[64:67]
	v_mfma_f32_16x16x32_bf16 v[60:63], v[170:173], v[178:181], v[60:63]
	ds_read_b128 v[202:205], v152 offset:56320
	s_waitcnt lgkmcnt(2)
	v_mfma_f32_16x16x32_bf16 v[48:51], v[154:157], v[186:189], v[48:51]
	v_mfma_f32_16x16x32_bf16 v[44:47], v[170:173], v[186:189], v[44:47]
	s_waitcnt lgkmcnt(1)
	v_mfma_f32_16x16x32_bf16 v[32:35], v[154:157], v[194:197], v[32:35]
	v_mfma_f32_16x16x32_bf16 v[28:31], v[170:173], v[194:197], v[28:31]
	s_waitcnt lgkmcnt(0)
	v_mfma_f32_16x16x32_bf16 v[16:19], v[154:157], v[202:205], v[16:19]
	v_mfma_f32_16x16x32_bf16 v[12:15], v[170:173], v[202:205], v[12:15]
	s_add_u32 s26, s26, 0x40000
	s_addc_u32 s27, s27, 0
	s_mov_b32 m0, s44
	s_nop 0
	global_load_lds_dwordx4 v136, s[26:27]
	s_mov_b32 m0, s45
	s_nop 0
	global_load_lds_dwordx4 v138, s[26:27]
	v_mfma_f32_16x16x32_bf16 v[56:59], v[206:209], v[174:177], v[56:59]
	s_add_i32 s58, s58, 2
	s_add_u32 s24, s24, 0xffffff00
	s_addc_u32 s25, s25, -1
	v_mfma_f32_16x16x32_bf16 v[52:55], v[214:217], v[174:177], v[52:55]
	s_add_u32 s20, s20, 0x100
	s_addc_u32 s21, s21, 0
	s_add_u32 s22, s22, 0x100
	v_mfma_f32_16x16x32_bf16 v[40:43], v[206:209], v[182:185], v[40:43]
	s_addc_u32 s23, s23, 0
	s_cmp_lt_u32 s58, 14
	v_mfma_f32_16x16x32_bf16 v[36:39], v[214:217], v[182:185], v[36:39]
	v_mfma_f32_16x16x32_bf16 v[24:27], v[206:209], v[190:193], v[24:27]
	v_mfma_f32_16x16x32_bf16 v[20:23], v[214:217], v[190:193], v[20:23]
	v_mfma_f32_16x16x32_bf16 v[4:7], v[206:209], v[198:201], v[4:7]
	v_mfma_f32_16x16x32_bf16 v[8:11], v[214:217], v[198:201], v[8:11]
	v_mfma_f32_16x16x32_bf16 v[56:59], v[210:213], v[178:181], v[56:59]
	v_mfma_f32_16x16x32_bf16 v[52:55], v[218:221], v[178:181], v[52:55]
	v_mfma_f32_16x16x32_bf16 v[40:43], v[210:213], v[186:189], v[40:43]
	v_mfma_f32_16x16x32_bf16 v[36:39], v[218:221], v[186:189], v[36:39]
	v_mfma_f32_16x16x32_bf16 v[24:27], v[210:213], v[194:197], v[24:27]
	v_mfma_f32_16x16x32_bf16 v[20:23], v[218:221], v[194:197], v[20:23]
	v_mfma_f32_16x16x32_bf16 v[4:7], v[210:213], v[202:205], v[4:7]
	v_mfma_f32_16x16x32_bf16 v[8:11], v[218:221], v[202:205], v[8:11]
	s_cbranch_scc1 .LBB0_173
; __device__ __forceinline__ unsigned cvt_pk_bf16(float lo, float hi) { unsigned r; asm volatile("v_cvt_pk_bf16_f32 %0, %1, %2" : "=v"(r) : "v"(lo), "v"(hi)); return r; }
; __device__ __forceinline__ float bflo(unsigned w) { return __uint_as_float(w << 16); }
; __device__ __forceinline__ float bfhi(unsigned w) { return __uint_as_float(w & 0xffff0000u); }
;     __device__ __forceinline__ void operator()(const f32x4 (&acc)[2][2][4][2], const Unit& u, int wr, int wc, int fr, int fq, const LAS float*) const {
;     ...
;             for (int m = 0; m < 4; ++m) { const size_t row = (size_t)(row0 + ai * 128 + m * 16);
; #pragma unroll
;                 for (int bj = 0; bj < 2; ++bj) { const int col = col0 + bj * 128;
;                     const u32x4 g = *(const u32x4*)(G + row * NGATE + MODE * DM + col);
;                     f32x4 v0 = acc[ai][bj][m][0], v1 = acc[ai][bj][m][1];
;                     v0[0] *= bflo(g.x); v0[1] *= bfhi(g.x); v0[2] *= bflo(g.y); v0[3] *= bfhi(g.y); v1[0] *= bflo(g.z); v1[1] *= bfhi(g.z); v1[2] *= bflo(g.w); v1[3] *= bfhi(g.w);
;                     bf16_t* tp = T + row * DM + col;
;                     if (MODE == 1) { const u32x4 t = *(const u32x4*)tp;
;                         v0[0] += bflo(t.x); v0[1] += bfhi(t.x); v0[2] += bflo(t.y); v0[3] += bfhi(t.y); v1[0] += bflo(t.z); v1[1] += bfhi(t.z); v1[2] += bflo(t.w); v1[3] += bfhi(t.w); }
;                     u32x4 w; w.x = cvt_pk_bf16(v0[0], v0[1]); w.y = cvt_pk_bf16(v0[2], v0[3]); w.z = cvt_pk_bf16(v1[0], v1[1]); w.w = cvt_pk_bf16(v1[2], v1[3]);
;                     *(u32x4*)tp = w; } }
	v_mov_b32_e32 v132, v141
	s_lshl_b32 s5, s18, 8
	v_mbcnt_lo_u32_b32 v132, -1, v132
	v_mbcnt_hi_u32_b32 v132, -1, v132
	s_add_i32 s5, s5, s37
	v_and_or_b32 v134, v132, 15, s5
	s_lshl_b32 s5, s35, 8
	v_ashrrev_i32_e32 v132, 1, v132
	s_or_b32 s5, s5, s38
	v_and_b32_e32 v132, -8, v132
	v_add_u32_e32 v132, s5, v132
	v_ashrrev_i32_e32 v135, 31, v134
	v_lshlrev_b64 v[142:143], 13, v[134:135]
	v_ashrrev_i32_e32 v133, 31, v132
	v_lshl_add_u64 v[142:143], s[2:3], 0, v[142:143]
	v_lshlrev_b64 v[132:133], 1, v[132:133]
	v_lshl_add_u64 v[142:143], v[142:143], 0, v[132:133]
	s_mov_b64 s[20:21], 0x1000
	v_lshl_add_u64 v[154:155], v[142:143], 0, s[20:21]
	v_add_co_u32_e32 v142, vcc, s76, v142
	v_lshlrev_b64 v[144:145], 12, v[134:135]
	s_nop 0
	v_addc_co_u32_e32 v143, vcc, 0, v143, vcc
	v_lshlrev_b32_e32 v236, 13, v134
	v_add_u32_e32 v236, v236, v132
	v_add_u32_e32 v236, 0x1000, v236
	v_lshlrev_b32_e32 v238, 12, v134
	v_add_u32_e32 v238, v238, v132
	global_load_dwordx4 v[172:175], v236, s[2:3]
	global_load_dwordx4 v[176:179], v238, s[12:13]
	global_load_dwordx4 v[180:183], v236, s[2:3] offset:256
	global_load_dwordx4 v[184:187], v238, s[12:13] offset:256
	v_add_u32_e32 v237, 0x20000, v236
	v_add_u32_e32 v239, 0x10000, v238
	global_load_dwordx4 v[188:191], v237, s[2:3]
	global_load_dwordx4 v[192:195], v239, s[12:13]
	global_load_dwordx4 v[196:199], v237, s[2:3] offset:256
	global_load_dwordx4 v[200:203], v239, s[12:13] offset:256
	v_add_u32_e32 v237, 0x40000, v236
	v_add_u32_e32 v239, 0x20000, v238
	global_load_dwordx4 v[204:207], v237, s[2:3]
	global_load_dwordx4 v[208:211], v239, s[12:13]
	global_load_dwordx4 v[212:215], v237, s[2:3] offset:256
	global_load_dwordx4 v[216:219], v239, s[12:13] offset:256
	v_add_u32_e32 v237, 0x60000, v236
	v_add_u32_e32 v239, 0x30000, v238
	global_load_dwordx4 v[220:223], v237, s[2:3]
	global_load_dwordx4 v[224:227], v239, s[12:13]
	global_load_dwordx4 v[228:231], v237, s[2:3] offset:256
	global_load_dwordx4 v[232:235], v239, s[12:13] offset:256
	v_lshl_add_u64 v[142:143], s[12:13], 0, v[144:145]
	v_lshl_add_u64 v[142:143], v[142:143], 0, v[132:133]
	s_mov_b32 s35, s4
	s_mov_b32 s18, s8
	s_mov_b64 s[22:23], s[10:11]
	s_mov_b32 s9, s55
	s_waitcnt vmcnt(15)
	s_nop 1
	v_mov_b64_e32 v[146:147], v[172:173]
	v_mov_b64_e32 v[148:149], v[174:175]
	v_lshlrev_b32_e32 v135, 16, v146
	v_and_b32_e32 v153, 0xffff0000, v146
	v_lshlrev_b32_e32 v156, 16, v147
	v_and_b32_e32 v157, 0xffff0000, v147
	v_lshlrev_b32_e32 v158, 16, v148
	v_and_b32_e32 v159, 0xffff0000, v148
	v_lshlrev_b32_e32 v160, 16, v149
	v_and_b32_e32 v161, 0xffff0000, v149
	s_waitcnt vmcnt(14)
	s_nop 1
	v_mov_b64_e32 v[146:147], v[176:177]
	v_mov_b64_e32 v[148:149], v[178:179]
	v_lshlrev_b32_e32 v144, 16, v146
	v_fmac_f32_e32 v144, v128, v135
	v_and_b32_e32 v128, 0xffff0000, v146
	v_fmac_f32_e32 v128, v129, v153
	v_lshlrev_b32_e32 v129, 16, v147
	v_fmac_f32_e32 v129, v130, v156
	v_and_b32_e32 v130, 0xffff0000, v147
	v_fmac_f32_e32 v130, v131, v157
	v_lshlrev_b32_e32 v131, 16, v148
	v_and_b32_e32 v135, 0xffff0000, v148
	v_lshlrev_b32_e32 v145, 16, v149
	v_and_b32_e32 v146, 0xffff0000, v149
	v_fmac_f32_e32 v131, v124, v158
	v_fmac_f32_e32 v135, v125, v159
	v_fmac_f32_e32 v145, v126, v160
	v_fmac_f32_e32 v146, v127, v161
	v_cvt_pk_bf16_f32 v124, v144, v128
	v_cvt_pk_bf16_f32 v125, v129, v130
	v_cvt_pk_bf16_f32 v126, v131, v135
	v_cvt_pk_bf16_f32 v127, v145, v146
	global_store_dwordx4 v[142:143], v[124:127], off
	s_waitcnt vmcnt(14)
	s_nop 1
	v_mov_b64_e32 v[124:125], v[180:181]
	v_mov_b64_e32 v[126:127], v[182:183]
	v_lshlrev_b32_e32 v128, 16, v124
	v_and_b32_e32 v129, 0xffff0000, v124
	v_lshlrev_b32_e32 v130, 16, v125
	v_and_b32_e32 v131, 0xffff0000, v125
	v_lshlrev_b32_e32 v135, 16, v126
	v_and_b32_e32 v144, 0xffff0000, v126
	v_lshlrev_b32_e32 v145, 16, v127
	v_and_b32_e32 v146, 0xffff0000, v127
	s_waitcnt vmcnt(13)
	s_nop 1
	v_mov_b64_e32 v[124:125], v[184:185]
	v_mov_b64_e32 v[126:127], v[186:187]
	v_lshlrev_b32_e32 v147, 16, v124
	v_fmac_f32_e32 v147, v120, v128
	v_and_b32_e32 v120, 0xffff0000, v124
	v_fmac_f32_e32 v120, v121, v129
	v_lshlrev_b32_e32 v121, 16, v125
	v_fmac_f32_e32 v121, v122, v130
	v_and_b32_e32 v122, 0xffff0000, v125
	v_fmac_f32_e32 v122, v123, v131
	v_lshlrev_b32_e32 v123, 16, v126
	v_fmac_f32_e32 v123, v116, v135
	v_and_b32_e32 v124, 0xffff0000, v126
	v_lshlrev_b32_e32 v125, 16, v127
	v_and_b32_e32 v126, 0xffff0000, v127
	v_cvt_pk_bf16_f32 v116, v147, v120
	v_fmac_f32_e32 v124, v117, v144
	v_fmac_f32_e32 v125, v118, v145
	v_fmac_f32_e32 v126, v119, v146
	v_cvt_pk_bf16_f32 v117, v121, v122
	v_cvt_pk_bf16_f32 v118, v123, v124
	v_cvt_pk_bf16_f32 v119, v125, v126
	global_store_dwordx4 v[142:143], v[116:119], off offset:256
	v_add_u32_e32 v237, 0x100000, v236
	v_add_u32_e32 v239, 0x80000, v238
	global_load_dwordx4 v[172:175], v237, s[2:3]
	global_load_dwordx4 v[176:179], v239, s[12:13]
	global_load_dwordx4 v[180:183], v237, s[2:3] offset:256
	global_load_dwordx4 v[184:187], v239, s[12:13] offset:256
	s_nop 1
	v_or_b32_e32 v116, 16, v134
	v_ashrrev_i32_e32 v117, 31, v116
	v_lshlrev_b64 v[118:119], 13, v[116:117]
	v_lshlrev_b64 v[122:123], 12, v[116:117]
	v_lshl_add_u64 v[116:117], s[2:3], 0, v[118:119]
	v_lshl_add_u64 v[118:119], v[116:117], 0, v[132:133]
	v_lshl_add_u64 v[116:117], v[118:119], 0, s[20:21]
	v_add_co_u32_e32 v118, vcc, s76, v118
	s_nop 1
	v_addc_co_u32_e32 v119, vcc, 0, v119, vcc
	s_waitcnt vmcnt(17)
; __device__ __forceinline__ unsigned cvt_pk_bf16(float lo, float hi) { unsigned r; asm volatile("v_cvt_pk_bf16_f32 %0, %1, %2" : "=v"(r) : "v"(lo), "v"(hi)); return r; }
; __device__ __forceinline__ float bflo(unsigned w) { return __uint_as_float(w << 16); }
; __device__ __forceinline__ float bfhi(unsigned w) { return __uint_as_float(w & 0xffff0000u); }
;     __device__ __forceinline__ void operator()(const f32x4 (&acc)[2][2][4][2], const Unit& u, int wr, int wc, int fr, int fq, const LAS float*) const {
;     ...
;             for (int m = 0; m < 4; ++m) { const size_t row = (size_t)(row0 + ai * 128 + m * 16);
; #pragma unroll
;                 for (int bj = 0; bj < 2; ++bj) { const int col = col0 + bj * 128;
;                     const u32x4 g = *(const u32x4*)(G + row * NGATE + MODE * DM + col);
;                     f32x4 v0 = acc[ai][bj][m][0], v1 = acc[ai][bj][m][1];
;                     v0[0] *= bflo(g.x); v0[1] *= bfhi(g.x); v0[2] *= bflo(g.y); v0[3] *= bfhi(g.y); v1[0] *= bflo(g.z); v1[1] *= bfhi(g.z); v1[2] *= bflo(g.w); v1[3] *= bfhi(g.w);
;                     bf16_t* tp = T + row * DM + col;
;                     if (MODE == 1) { const u32x4 t = *(const u32x4*)tp;
;                         v0[0] += bflo(t.x); v0[1] += bfhi(t.x); v0[2] += bflo(t.y); v0[3] += bfhi(t.y); v1[0] += bflo(t.z); v1[1] += bfhi(t.z); v1[2] += bflo(t.w); v1[3] += bfhi(t.w); }
;                     u32x4 w; w.x = cvt_pk_bf16(v0[0], v0[1]); w.y = cvt_pk_bf16(v0[2], v0[3]); w.z = cvt_pk_bf16(v1[0], v1[1]); w.w = cvt_pk_bf16(v1[2], v1[3]);
;                     *(u32x4*)tp = w; } }
	s_nop 1
	v_mov_b64_e32 v[118:119], v[188:189]
	v_mov_b64_e32 v[120:121], v[190:191]
	v_lshlrev_b32_e32 v124, 16, v118
	v_and_b32_e32 v125, 0xffff0000, v118
	v_lshlrev_b32_e32 v126, 16, v119
	v_and_b32_e32 v127, 0xffff0000, v119
	v_lshl_add_u64 v[118:119], s[12:13], 0, v[122:123]
	v_lshl_add_u64 v[122:123], v[118:119], 0, v[132:133]
	v_lshlrev_b32_e32 v128, 16, v120
	v_and_b32_e32 v129, 0xffff0000, v120
	v_lshlrev_b32_e32 v130, 16, v121
	v_and_b32_e32 v131, 0xffff0000, v121
	s_waitcnt vmcnt(16)
	s_nop 1
	v_mov_b64_e32 v[118:119], v[192:193]
	v_mov_b64_e32 v[120:121], v[194:195]
	v_lshlrev_b32_e32 v135, 16, v118
	v_fmac_f32_e32 v135, v112, v124
	v_and_b32_e32 v112, 0xffff0000, v118
	v_fmac_f32_e32 v112, v113, v125
	v_lshlrev_b32_e32 v113, 16, v119
	v_fmac_f32_e32 v113, v114, v126
	v_and_b32_e32 v114, 0xffff0000, v119
	v_fmac_f32_e32 v114, v115, v127
	v_lshlrev_b32_e32 v115, 16, v120
	v_and_b32_e32 v118, 0xffff0000, v120
	v_lshlrev_b32_e32 v119, 16, v121
	v_and_b32_e32 v120, 0xffff0000, v121
	v_fmac_f32_e32 v115, v108, v128
	v_fmac_f32_e32 v118, v109, v129
	v_fmac_f32_e32 v119, v110, v130
	v_fmac_f32_e32 v120, v111, v131
	v_cvt_pk_bf16_f32 v108, v135, v112
	v_cvt_pk_bf16_f32 v109, v113, v114
	v_cvt_pk_bf16_f32 v110, v115, v118
	v_cvt_pk_bf16_f32 v111, v119, v120
	global_store_dwordx4 v[122:123], v[108:111], off
	s_waitcnt vmcnt(16)
	s_nop 1
	v_mov_b64_e32 v[108:109], v[196:197]
	v_mov_b64_e32 v[110:111], v[198:199]
	v_lshlrev_b32_e32 v112, 16, v108
	v_and_b32_e32 v113, 0xffff0000, v108
	v_lshlrev_b32_e32 v114, 16, v109
	v_and_b32_e32 v115, 0xffff0000, v109
	v_lshlrev_b32_e32 v116, 16, v110
	v_and_b32_e32 v117, 0xffff0000, v110
	v_lshlrev_b32_e32 v118, 16, v111
	v_and_b32_e32 v119, 0xffff0000, v111
	s_waitcnt vmcnt(15)
	s_nop 1
	v_mov_b64_e32 v[108:109], v[200:201]
	v_mov_b64_e32 v[110:111], v[202:203]
	v_lshlrev_b32_e32 v120, 16, v108
	v_fmac_f32_e32 v120, v104, v112
	v_and_b32_e32 v104, 0xffff0000, v108
	v_fmac_f32_e32 v104, v105, v113
	v_lshlrev_b32_e32 v105, 16, v109
	v_fmac_f32_e32 v105, v106, v114
	v_and_b32_e32 v106, 0xffff0000, v109
	v_fmac_f32_e32 v106, v107, v115
	v_lshlrev_b32_e32 v107, 16, v110
	v_fmac_f32_e32 v107, v100, v116
	v_and_b32_e32 v108, 0xffff0000, v110
	v_lshlrev_b32_e32 v109, 16, v111
	v_and_b32_e32 v110, 0xffff0000, v111
	v_cvt_pk_bf16_f32 v100, v120, v104
	v_fmac_f32_e32 v108, v101, v117
	v_fmac_f32_e32 v109, v102, v118
	v_fmac_f32_e32 v110, v103, v119
	v_cvt_pk_bf16_f32 v101, v105, v106
	v_cvt_pk_bf16_f32 v102, v107, v108
	v_cvt_pk_bf16_f32 v103, v109, v110
	global_store_dwordx4 v[122:123], v[100:103], off offset:256
	v_add_u32_e32 v237, 0x120000, v236
	v_add_u32_e32 v239, 0x90000, v238
	global_load_dwordx4 v[188:191], v237, s[2:3]
	global_load_dwordx4 v[192:195], v239, s[12:13]
	global_load_dwordx4 v[196:199], v237, s[2:3] offset:256
	global_load_dwordx4 v[200:203], v239, s[12:13] offset:256
	s_nop 1
	v_or_b32_e32 v100, 32, v134
	v_ashrrev_i32_e32 v101, 31, v100
	v_lshlrev_b64 v[102:103], 13, v[100:101]
	v_lshlrev_b64 v[106:107], 12, v[100:101]
	v_lshl_add_u64 v[100:101], s[2:3], 0, v[102:103]
	v_lshl_add_u64 v[102:103], v[100:101], 0, v[132:133]
	v_lshl_add_u64 v[100:101], v[102:103], 0, s[20:21]
	v_add_co_u32_e32 v102, vcc, s76, v102
	s_nop 1
	v_addc_co_u32_e32 v103, vcc, 0, v103, vcc
	s_waitcnt vmcnt(19)
	s_nop 1
	v_mov_b64_e32 v[102:103], v[204:205]
	v_mov_b64_e32 v[104:105], v[206:207]
	v_lshlrev_b32_e32 v108, 16, v102
	v_and_b32_e32 v109, 0xffff0000, v102
	v_lshlrev_b32_e32 v110, 16, v103
	v_and_b32_e32 v111, 0xffff0000, v103
	v_lshl_add_u64 v[102:103], s[12:13], 0, v[106:107]
	v_lshl_add_u64 v[106:107], v[102:103], 0, v[132:133]
	v_lshlrev_b32_e32 v112, 16, v104
	v_and_b32_e32 v113, 0xffff0000, v104
	v_lshlrev_b32_e32 v114, 16, v105
	v_and_b32_e32 v115, 0xffff0000, v105
	s_waitcnt vmcnt(18)
	s_nop 1
	v_mov_b64_e32 v[102:103], v[208:209]
	v_mov_b64_e32 v[104:105], v[210:211]
	v_lshlrev_b32_e32 v116, 16, v102
	v_fmac_f32_e32 v116, v96, v108
	v_and_b32_e32 v96, 0xffff0000, v102
	v_fmac_f32_e32 v96, v97, v109
	v_lshlrev_b32_e32 v97, 16, v103
	v_fmac_f32_e32 v97, v98, v110
	v_and_b32_e32 v98, 0xffff0000, v103
	v_fmac_f32_e32 v98, v99, v111
	v_lshlrev_b32_e32 v99, 16, v104
	v_and_b32_e32 v102, 0xffff0000, v104
	v_lshlrev_b32_e32 v103, 16, v105
	v_and_b32_e32 v104, 0xffff0000, v105
	v_fmac_f32_e32 v99, v92, v112
	v_fmac_f32_e32 v102, v93, v113
	v_fmac_f32_e32 v103, v94, v114
	v_fmac_f32_e32 v104, v95, v115
	v_cvt_pk_bf16_f32 v92, v116, v96
	v_cvt_pk_bf16_f32 v93, v97, v98
	v_cvt_pk_bf16_f32 v94, v99, v102
	v_cvt_pk_bf16_f32 v95, v103, v104
	global_store_dwordx4 v[106:107], v[92:95], off
	s_waitcnt vmcnt(18)
	s_nop 1
	v_mov_b64_e32 v[92:93], v[212:213]
	v_mov_b64_e32 v[94:95], v[214:215]
	v_lshlrev_b32_e32 v96, 16, v92
	v_and_b32_e32 v97, 0xffff0000, v92
	v_lshlrev_b32_e32 v98, 16, v93
	v_and_b32_e32 v99, 0xffff0000, v93
	v_lshlrev_b32_e32 v100, 16, v94
	v_and_b32_e32 v101, 0xffff0000, v94
	v_lshlrev_b32_e32 v102, 16, v95
	v_and_b32_e32 v103, 0xffff0000, v95
	s_waitcnt vmcnt(17)
; __device__ __forceinline__ unsigned cvt_pk_bf16(float lo, float hi) { unsigned r; asm volatile("v_cvt_pk_bf16_f32 %0, %1, %2" : "=v"(r) : "v"(lo), "v"(hi)); return r; }
; __device__ __forceinline__ float bflo(unsigned w) { return __uint_as_float(w << 16); }
; __device__ __forceinline__ float bfhi(unsigned w) { return __uint_as_float(w & 0xffff0000u); }
;     __device__ __forceinline__ void operator()(const f32x4 (&acc)[2][2][4][2], const Unit& u, int wr, int wc, int fr, int fq, const LAS float*) const {
;     ...
;             for (int m = 0; m < 4; ++m) { const size_t row = (size_t)(row0 + ai * 128 + m * 16);
; #pragma unroll
;                 for (int bj = 0; bj < 2; ++bj) { const int col = col0 + bj * 128;
;                     const u32x4 g = *(const u32x4*)(G + row * NGATE + MODE * DM + col);
;                     f32x4 v0 = acc[ai][bj][m][0], v1 = acc[ai][bj][m][1];
;                     v0[0] *= bflo(g.x); v0[1] *= bfhi(g.x); v0[2] *= bflo(g.y); v0[3] *= bfhi(g.y); v1[0] *= bflo(g.z); v1[1] *= bfhi(g.z); v1[2] *= bflo(g.w); v1[3] *= bfhi(g.w);
;                     bf16_t* tp = T + row * DM + col;
;                     if (MODE == 1) { const u32x4 t = *(const u32x4*)tp;
;                         v0[0] += bflo(t.x); v0[1] += bfhi(t.x); v0[2] += bflo(t.y); v0[3] += bfhi(t.y); v1[0] += bflo(t.z); v1[1] += bfhi(t.z); v1[2] += bflo(t.w); v1[3] += bfhi(t.w); }
;                     u32x4 w; w.x = cvt_pk_bf16(v0[0], v0[1]); w.y = cvt_pk_bf16(v0[2], v0[3]); w.z = cvt_pk_bf16(v1[0], v1[1]); w.w = cvt_pk_bf16(v1[2], v1[3]);
;                     *(u32x4*)tp = w; } }
	s_nop 1
	v_mov_b64_e32 v[92:93], v[216:217]
	v_mov_b64_e32 v[94:95], v[218:219]
	v_lshlrev_b32_e32 v104, 16, v92
	v_fmac_f32_e32 v104, v88, v96
	v_and_b32_e32 v88, 0xffff0000, v92
	v_fmac_f32_e32 v88, v89, v97
	v_lshlrev_b32_e32 v89, 16, v93
	v_fmac_f32_e32 v89, v90, v98
	v_and_b32_e32 v90, 0xffff0000, v93
	v_fmac_f32_e32 v90, v91, v99
	v_lshlrev_b32_e32 v91, 16, v94
	v_fmac_f32_e32 v91, v84, v100
	v_and_b32_e32 v92, 0xffff0000, v94
	v_lshlrev_b32_e32 v93, 16, v95
	v_and_b32_e32 v94, 0xffff0000, v95
	v_cvt_pk_bf16_f32 v84, v104, v88
	v_fmac_f32_e32 v92, v85, v101
	v_fmac_f32_e32 v93, v86, v102
	v_fmac_f32_e32 v94, v87, v103
	v_cvt_pk_bf16_f32 v85, v89, v90
	v_cvt_pk_bf16_f32 v86, v91, v92
	v_cvt_pk_bf16_f32 v87, v93, v94
	global_store_dwordx4 v[106:107], v[84:87], off offset:256
	v_add_u32_e32 v237, 0x140000, v236
	v_add_u32_e32 v239, 0xa0000, v238
	global_load_dwordx4 v[204:207], v237, s[2:3]
	global_load_dwordx4 v[208:211], v239, s[12:13]
	global_load_dwordx4 v[212:215], v237, s[2:3] offset:256
	global_load_dwordx4 v[216:219], v239, s[12:13] offset:256
	s_nop 1
	v_or_b32_e32 v84, 48, v134
	v_ashrrev_i32_e32 v85, 31, v84
	v_lshlrev_b64 v[86:87], 13, v[84:85]
	v_lshlrev_b64 v[90:91], 12, v[84:85]
	v_lshl_add_u64 v[84:85], s[2:3], 0, v[86:87]
	v_lshl_add_u64 v[86:87], v[84:85], 0, v[132:133]
	v_lshl_add_u64 v[84:85], v[86:87], 0, s[20:21]
	v_add_co_u32_e32 v86, vcc, s76, v86
	s_nop 1
	v_addc_co_u32_e32 v87, vcc, 0, v87, vcc
	s_waitcnt vmcnt(21)
	s_nop 1
	v_mov_b64_e32 v[86:87], v[220:221]
	v_mov_b64_e32 v[88:89], v[222:223]
	v_lshlrev_b32_e32 v92, 16, v86
	v_and_b32_e32 v93, 0xffff0000, v86
	v_lshlrev_b32_e32 v94, 16, v87
	v_and_b32_e32 v95, 0xffff0000, v87
	v_lshl_add_u64 v[86:87], s[12:13], 0, v[90:91]
	v_lshl_add_u64 v[90:91], v[86:87], 0, v[132:133]
	v_lshlrev_b32_e32 v96, 16, v88
	v_and_b32_e32 v97, 0xffff0000, v88
	v_lshlrev_b32_e32 v98, 16, v89
	v_and_b32_e32 v99, 0xffff0000, v89
	s_waitcnt vmcnt(20)
	s_nop 1
	v_mov_b64_e32 v[86:87], v[224:225]
	v_mov_b64_e32 v[88:89], v[226:227]
	v_lshlrev_b32_e32 v100, 16, v86
	v_fmac_f32_e32 v100, v80, v92
	v_and_b32_e32 v80, 0xffff0000, v86
	v_fmac_f32_e32 v80, v81, v93
	v_lshlrev_b32_e32 v81, 16, v87
	v_fmac_f32_e32 v81, v82, v94
	v_and_b32_e32 v82, 0xffff0000, v87
	v_fmac_f32_e32 v82, v83, v95
	v_lshlrev_b32_e32 v83, 16, v88
	v_and_b32_e32 v86, 0xffff0000, v88
	v_lshlrev_b32_e32 v87, 16, v89
	v_and_b32_e32 v88, 0xffff0000, v89
	v_fmac_f32_e32 v83, v76, v96
	v_fmac_f32_e32 v86, v77, v97
	v_fmac_f32_e32 v87, v78, v98
	v_fmac_f32_e32 v88, v79, v99
	v_cvt_pk_bf16_f32 v76, v100, v80
	v_cvt_pk_bf16_f32 v77, v81, v82
	v_cvt_pk_bf16_f32 v78, v83, v86
	v_cvt_pk_bf16_f32 v79, v87, v88
	global_store_dwordx4 v[90:91], v[76:79], off
	s_waitcnt vmcnt(20)
	s_nop 1
	v_mov_b64_e32 v[76:77], v[228:229]
	v_mov_b64_e32 v[78:79], v[230:231]
	v_lshlrev_b32_e32 v80, 16, v76
	v_and_b32_e32 v81, 0xffff0000, v76
	v_lshlrev_b32_e32 v82, 16, v77
	v_and_b32_e32 v83, 0xffff0000, v77
	v_lshlrev_b32_e32 v84, 16, v78
	v_and_b32_e32 v85, 0xffff0000, v78
	v_lshlrev_b32_e32 v86, 16, v79
	v_and_b32_e32 v87, 0xffff0000, v79
	s_waitcnt vmcnt(19)
	s_nop 1
	v_mov_b64_e32 v[76:77], v[232:233]
	v_mov_b64_e32 v[78:79], v[234:235]
	v_lshlrev_b32_e32 v88, 16, v76
	v_fmac_f32_e32 v88, v72, v80
	v_and_b32_e32 v72, 0xffff0000, v76
	v_fmac_f32_e32 v72, v73, v81
	v_lshlrev_b32_e32 v73, 16, v77
	v_fmac_f32_e32 v73, v74, v82
	v_and_b32_e32 v74, 0xffff0000, v77
	v_fmac_f32_e32 v74, v75, v83
	v_lshlrev_b32_e32 v75, 16, v78
	v_fmac_f32_e32 v75, v68, v84
	v_and_b32_e32 v76, 0xffff0000, v78
	v_lshlrev_b32_e32 v77, 16, v79
	v_and_b32_e32 v78, 0xffff0000, v79
	v_cvt_pk_bf16_f32 v68, v88, v72
	v_fmac_f32_e32 v76, v69, v85
	v_fmac_f32_e32 v77, v70, v86
	v_fmac_f32_e32 v78, v71, v87
	v_cvt_pk_bf16_f32 v69, v73, v74
	v_cvt_pk_bf16_f32 v70, v75, v76
	v_cvt_pk_bf16_f32 v71, v77, v78
	global_store_dwordx4 v[90:91], v[68:71], off offset:256
	v_add_u32_e32 v237, 0x160000, v236
	v_add_u32_e32 v239, 0xb0000, v238
	global_load_dwordx4 v[220:223], v237, s[2:3]
	global_load_dwordx4 v[224:227], v239, s[12:13]
	global_load_dwordx4 v[228:231], v237, s[2:3] offset:256
	global_load_dwordx4 v[232:235], v239, s[12:13] offset:256
	s_nop 1
	v_add_u32_e32 v68, 0x80, v134
	v_ashrrev_i32_e32 v69, 31, v68
	v_lshlrev_b64 v[70:71], 13, v[68:69]
	v_lshlrev_b64 v[74:75], 12, v[68:69]
	v_lshl_add_u64 v[68:69], s[2:3], 0, v[70:71]
	v_lshl_add_u64 v[70:71], v[68:69], 0, v[132:133]
	v_lshl_add_u64 v[68:69], v[70:71], 0, s[20:21]
	v_add_co_u32_e32 v70, vcc, s76, v70
	s_nop 1
	v_addc_co_u32_e32 v71, vcc, 0, v71, vcc
	s_waitcnt vmcnt(21)
	s_nop 1
	v_mov_b64_e32 v[70:71], v[172:173]
	v_mov_b64_e32 v[72:73], v[174:175]
	v_lshlrev_b32_e32 v76, 16, v70
	v_and_b32_e32 v77, 0xffff0000, v70
	v_lshlrev_b32_e32 v78, 16, v71
	v_and_b32_e32 v79, 0xffff0000, v71
	v_lshl_add_u64 v[70:71], s[12:13], 0, v[74:75]
	v_lshl_add_u64 v[74:75], v[70:71], 0, v[132:133]
	v_lshlrev_b32_e32 v80, 16, v72
	v_and_b32_e32 v81, 0xffff0000, v72
	v_lshlrev_b32_e32 v82, 16, v73
	v_and_b32_e32 v83, 0xffff0000, v73
	s_waitcnt vmcnt(20)
	s_nop 1
	v_mov_b64_e32 v[70:71], v[176:177]
	v_mov_b64_e32 v[72:73], v[178:179]
	v_lshlrev_b32_e32 v84, 16, v70
	v_fmac_f32_e32 v84, v64, v76
	v_and_b32_e32 v64, 0xffff0000, v70
	v_fmac_f32_e32 v64, v65, v77
	v_lshlrev_b32_e32 v65, 16, v71
	v_fmac_f32_e32 v65, v66, v78
	v_and_b32_e32 v66, 0xffff0000, v71
	v_fmac_f32_e32 v66, v67, v79
	v_lshlrev_b32_e32 v67, 16, v72
	v_and_b32_e32 v70, 0xffff0000, v72
	v_lshlrev_b32_e32 v71, 16, v73
	v_and_b32_e32 v72, 0xffff0000, v73
	v_fmac_f32_e32 v67, v60, v80
	v_fmac_f32_e32 v70, v61, v81
	v_fmac_f32_e32 v71, v62, v82
	v_fmac_f32_e32 v72, v63, v83
	v_cvt_pk_bf16_f32 v60, v84, v64
	v_cvt_pk_bf16_f32 v61, v65, v66
	v_cvt_pk_bf16_f32 v62, v67, v70
	v_cvt_pk_bf16_f32 v63, v71, v72
	global_store_dwordx4 v[74:75], v[60:63], off
	s_waitcnt vmcnt(20)
; __device__ __forceinline__ unsigned cvt_pk_bf16(float lo, float hi) { unsigned r; asm volatile("v_cvt_pk_bf16_f32 %0, %1, %2" : "=v"(r) : "v"(lo), "v"(hi)); return r; }
; __device__ __forceinline__ float bflo(unsigned w) { return __uint_as_float(w << 16); }
; __device__ __forceinline__ float bfhi(unsigned w) { return __uint_as_float(w & 0xffff0000u); }
;     __device__ __forceinline__ void operator()(const f32x4 (&acc)[2][2][4][2], const Unit& u, int wr, int wc, int fr, int fq, const LAS float*) const {
;     ...
;             for (int m = 0; m < 4; ++m) { const size_t row = (size_t)(row0 + ai * 128 + m * 16);
; #pragma unroll
;                 for (int bj = 0; bj < 2; ++bj) { const int col = col0 + bj * 128;
;                     const u32x4 g = *(const u32x4*)(G + row * NGATE + MODE * DM + col);
;                     f32x4 v0 = acc[ai][bj][m][0], v1 = acc[ai][bj][m][1];
;                     v0[0] *= bflo(g.x); v0[1] *= bfhi(g.x); v0[2] *= bflo(g.y); v0[3] *= bfhi(g.y); v1[0] *= bflo(g.z); v1[1] *= bfhi(g.z); v1[2] *= bflo(g.w); v1[3] *= bfhi(g.w);
;                     bf16_t* tp = T + row * DM + col;
;                     if (MODE == 1) { const u32x4 t = *(const u32x4*)tp;
;                         v0[0] += bflo(t.x); v0[1] += bfhi(t.x); v0[2] += bflo(t.y); v0[3] += bfhi(t.y); v1[0] += bflo(t.z); v1[1] += bfhi(t.z); v1[2] += bflo(t.w); v1[3] += bfhi(t.w); }
;                     u32x4 w; w.x = cvt_pk_bf16(v0[0], v0[1]); w.y = cvt_pk_bf16(v0[2], v0[3]); w.z = cvt_pk_bf16(v1[0], v1[1]); w.w = cvt_pk_bf16(v1[2], v1[3]);
;                     *(u32x4*)tp = w; } }
	s_nop 1
	v_mov_b64_e32 v[60:61], v[180:181]
	v_mov_b64_e32 v[62:63], v[182:183]
	v_lshlrev_b32_e32 v64, 16, v60
	v_and_b32_e32 v65, 0xffff0000, v60
	v_lshlrev_b32_e32 v66, 16, v61
	v_and_b32_e32 v67, 0xffff0000, v61
	v_lshlrev_b32_e32 v68, 16, v62
	v_and_b32_e32 v69, 0xffff0000, v62
	v_lshlrev_b32_e32 v70, 16, v63
	v_and_b32_e32 v71, 0xffff0000, v63
	s_waitcnt vmcnt(19)
	s_nop 1
	v_mov_b64_e32 v[60:61], v[184:185]
	v_mov_b64_e32 v[62:63], v[186:187]
	v_lshlrev_b32_e32 v72, 16, v60
	v_fmac_f32_e32 v72, v56, v64
	v_and_b32_e32 v56, 0xffff0000, v60
	v_fmac_f32_e32 v56, v57, v65
	v_lshlrev_b32_e32 v57, 16, v61
	v_fmac_f32_e32 v57, v58, v66
	v_and_b32_e32 v58, 0xffff0000, v61
	v_fmac_f32_e32 v58, v59, v67
	v_lshlrev_b32_e32 v59, 16, v62
	v_fmac_f32_e32 v59, v52, v68
	v_and_b32_e32 v60, 0xffff0000, v62
	v_lshlrev_b32_e32 v61, 16, v63
	v_and_b32_e32 v62, 0xffff0000, v63
	v_cvt_pk_bf16_f32 v52, v72, v56
	v_fmac_f32_e32 v60, v53, v69
	v_fmac_f32_e32 v61, v54, v70
	v_fmac_f32_e32 v62, v55, v71
	v_cvt_pk_bf16_f32 v53, v57, v58
	v_cvt_pk_bf16_f32 v54, v59, v60
	v_cvt_pk_bf16_f32 v55, v61, v62
	global_store_dwordx4 v[74:75], v[52:55], off offset:256
	s_nop 1
	v_add_u32_e32 v52, 0x90, v134
	v_ashrrev_i32_e32 v53, 31, v52
	v_lshlrev_b64 v[54:55], 13, v[52:53]
	v_lshlrev_b64 v[58:59], 12, v[52:53]
	v_lshl_add_u64 v[52:53], s[2:3], 0, v[54:55]
	v_lshl_add_u64 v[54:55], v[52:53], 0, v[132:133]
	v_lshl_add_u64 v[52:53], v[54:55], 0, s[20:21]
	v_add_co_u32_e32 v54, vcc, s76, v54
	s_nop 1
	v_addc_co_u32_e32 v55, vcc, 0, v55, vcc
	s_waitcnt vmcnt(17)
	s_nop 1
	v_mov_b64_e32 v[54:55], v[188:189]
	v_mov_b64_e32 v[56:57], v[190:191]
	v_lshlrev_b32_e32 v60, 16, v54
	v_and_b32_e32 v61, 0xffff0000, v54
	v_lshlrev_b32_e32 v62, 16, v55
	v_and_b32_e32 v63, 0xffff0000, v55
	v_lshl_add_u64 v[54:55], s[12:13], 0, v[58:59]
	v_lshl_add_u64 v[58:59], v[54:55], 0, v[132:133]
	v_lshlrev_b32_e32 v64, 16, v56
	v_and_b32_e32 v65, 0xffff0000, v56
	v_lshlrev_b32_e32 v66, 16, v57
	v_and_b32_e32 v67, 0xffff0000, v57
	s_waitcnt vmcnt(16)
	s_nop 1
	v_mov_b64_e32 v[54:55], v[192:193]
	v_mov_b64_e32 v[56:57], v[194:195]
	v_lshlrev_b32_e32 v68, 16, v54
	v_fmac_f32_e32 v68, v48, v60
	v_and_b32_e32 v48, 0xffff0000, v54
	v_fmac_f32_e32 v48, v49, v61
	v_lshlrev_b32_e32 v49, 16, v55
	v_fmac_f32_e32 v49, v50, v62
	v_and_b32_e32 v50, 0xffff0000, v55
	v_fmac_f32_e32 v50, v51, v63
	v_lshlrev_b32_e32 v51, 16, v56
	v_and_b32_e32 v54, 0xffff0000, v56
	v_lshlrev_b32_e32 v55, 16, v57
	v_and_b32_e32 v56, 0xffff0000, v57
	v_fmac_f32_e32 v51, v44, v64
	v_fmac_f32_e32 v54, v45, v65
	v_fmac_f32_e32 v55, v46, v66
	v_fmac_f32_e32 v56, v47, v67
	v_cvt_pk_bf16_f32 v44, v68, v48
	v_cvt_pk_bf16_f32 v45, v49, v50
	v_cvt_pk_bf16_f32 v46, v51, v54
	v_cvt_pk_bf16_f32 v47, v55, v56
	global_store_dwordx4 v[58:59], v[44:47], off
	s_waitcnt vmcnt(16)
	s_nop 1
	v_mov_b64_e32 v[44:45], v[196:197]
	v_mov_b64_e32 v[46:47], v[198:199]
	v_lshlrev_b32_e32 v48, 16, v44
	v_and_b32_e32 v49, 0xffff0000, v44
	v_lshlrev_b32_e32 v50, 16, v45
	v_and_b32_e32 v51, 0xffff0000, v45
	v_lshlrev_b32_e32 v52, 16, v46
	v_and_b32_e32 v53, 0xffff0000, v46
	v_lshlrev_b32_e32 v54, 16, v47
	v_and_b32_e32 v55, 0xffff0000, v47
	s_waitcnt vmcnt(15)
	s_nop 1
	v_mov_b64_e32 v[44:45], v[200:201]
	v_mov_b64_e32 v[46:47], v[202:203]
	v_lshlrev_b32_e32 v56, 16, v44
	v_fmac_f32_e32 v56, v40, v48
	v_and_b32_e32 v40, 0xffff0000, v44
	v_fmac_f32_e32 v40, v41, v49
	v_lshlrev_b32_e32 v41, 16, v45
	v_fmac_f32_e32 v41, v42, v50
	v_and_b32_e32 v42, 0xffff0000, v45
	v_fmac_f32_e32 v42, v43, v51
	v_lshlrev_b32_e32 v43, 16, v46
	v_fmac_f32_e32 v43, v36, v52
	v_and_b32_e32 v44, 0xffff0000, v46
	v_lshlrev_b32_e32 v45, 16, v47
	v_and_b32_e32 v46, 0xffff0000, v47
	v_cvt_pk_bf16_f32 v36, v56, v40
	v_fmac_f32_e32 v44, v37, v53
	v_fmac_f32_e32 v45, v38, v54
	v_fmac_f32_e32 v46, v39, v55
	v_cvt_pk_bf16_f32 v37, v41, v42
	v_cvt_pk_bf16_f32 v38, v43, v44
	v_cvt_pk_bf16_f32 v39, v45, v46
	global_store_dwordx4 v[58:59], v[36:39], off offset:256
	s_nop 1
	v_add_u32_e32 v36, 0xa0, v134
	v_ashrrev_i32_e32 v37, 31, v36
	v_lshlrev_b64 v[38:39], 13, v[36:37]
	v_lshlrev_b64 v[42:43], 12, v[36:37]
	v_lshl_add_u64 v[36:37], s[2:3], 0, v[38:39]
	v_lshl_add_u64 v[38:39], v[36:37], 0, v[132:133]
	v_lshl_add_u64 v[36:37], v[38:39], 0, s[20:21]
	v_add_co_u32_e32 v38, vcc, s76, v38
	s_nop 1
	v_addc_co_u32_e32 v39, vcc, 0, v39, vcc
	s_waitcnt vmcnt(13)
	s_nop 1
	v_mov_b64_e32 v[38:39], v[204:205]
	v_mov_b64_e32 v[40:41], v[206:207]
	v_lshlrev_b32_e32 v44, 16, v38
	v_and_b32_e32 v45, 0xffff0000, v38
	v_lshlrev_b32_e32 v46, 16, v39
	v_and_b32_e32 v47, 0xffff0000, v39
	v_lshl_add_u64 v[38:39], s[12:13], 0, v[42:43]
	v_lshl_add_u64 v[42:43], v[38:39], 0, v[132:133]
	v_lshlrev_b32_e32 v48, 16, v40
	v_and_b32_e32 v49, 0xffff0000, v40
	v_lshlrev_b32_e32 v50, 16, v41
	v_and_b32_e32 v51, 0xffff0000, v41
	s_waitcnt vmcnt(12)
; __device__ __forceinline__ unsigned cvt_pk_bf16(float lo, float hi) { unsigned r; asm volatile("v_cvt_pk_bf16_f32 %0, %1, %2" : "=v"(r) : "v"(lo), "v"(hi)); return r; }
; __device__ __forceinline__ float bflo(unsigned w) { return __uint_as_float(w << 16); }
; __device__ __forceinline__ float bfhi(unsigned w) { return __uint_as_float(w & 0xffff0000u); }
;     __device__ __forceinline__ void operator()(const f32x4 (&acc)[2][2][4][2], const Unit& u, int wr, int wc, int fr, int fq, const LAS float*) const {
;     ...
;             for (int m = 0; m < 4; ++m) { const size_t row = (size_t)(row0 + ai * 128 + m * 16);
; #pragma unroll
;                 for (int bj = 0; bj < 2; ++bj) { const int col = col0 + bj * 128;
;                     const u32x4 g = *(const u32x4*)(G + row * NGATE + MODE * DM + col);
;                     f32x4 v0 = acc[ai][bj][m][0], v1 = acc[ai][bj][m][1];
;                     v0[0] *= bflo(g.x); v0[1] *= bfhi(g.x); v0[2] *= bflo(g.y); v0[3] *= bfhi(g.y); v1[0] *= bflo(g.z); v1[1] *= bfhi(g.z); v1[2] *= bflo(g.w); v1[3] *= bfhi(g.w);
;                     bf16_t* tp = T + row * DM + col;
;                     if (MODE == 1) { const u32x4 t = *(const u32x4*)tp;
;                         v0[0] += bflo(t.x); v0[1] += bfhi(t.x); v0[2] += bflo(t.y); v0[3] += bfhi(t.y); v1[0] += bflo(t.z); v1[1] += bfhi(t.z); v1[2] += bflo(t.w); v1[3] += bfhi(t.w); }
;                     u32x4 w; w.x = cvt_pk_bf16(v0[0], v0[1]); w.y = cvt_pk_bf16(v0[2], v0[3]); w.z = cvt_pk_bf16(v1[0], v1[1]); w.w = cvt_pk_bf16(v1[2], v1[3]);
;                     *(u32x4*)tp = w; } }
	s_nop 1
	v_mov_b64_e32 v[38:39], v[208:209]
	v_mov_b64_e32 v[40:41], v[210:211]
	v_lshlrev_b32_e32 v52, 16, v38
	v_fmac_f32_e32 v52, v32, v44
	v_and_b32_e32 v32, 0xffff0000, v38
	v_fmac_f32_e32 v32, v33, v45
	v_lshlrev_b32_e32 v33, 16, v39
	v_fmac_f32_e32 v33, v34, v46
	v_and_b32_e32 v34, 0xffff0000, v39
	v_fmac_f32_e32 v34, v35, v47
	v_lshlrev_b32_e32 v35, 16, v40
	v_and_b32_e32 v38, 0xffff0000, v40
	v_lshlrev_b32_e32 v39, 16, v41
	v_and_b32_e32 v40, 0xffff0000, v41
	v_fmac_f32_e32 v35, v28, v48
	v_fmac_f32_e32 v38, v29, v49
	v_fmac_f32_e32 v39, v30, v50
	v_fmac_f32_e32 v40, v31, v51
	v_cvt_pk_bf16_f32 v28, v52, v32
	v_cvt_pk_bf16_f32 v29, v33, v34
	v_cvt_pk_bf16_f32 v30, v35, v38
	v_cvt_pk_bf16_f32 v31, v39, v40
	global_store_dwordx4 v[42:43], v[28:31], off
	s_waitcnt vmcnt(12)
	s_nop 1
	v_mov_b64_e32 v[28:29], v[212:213]
	v_mov_b64_e32 v[30:31], v[214:215]
	v_lshlrev_b32_e32 v32, 16, v28
	v_and_b32_e32 v33, 0xffff0000, v28
	v_lshlrev_b32_e32 v34, 16, v29
	v_and_b32_e32 v35, 0xffff0000, v29
	v_lshlrev_b32_e32 v36, 16, v30
	v_and_b32_e32 v37, 0xffff0000, v30
	v_lshlrev_b32_e32 v38, 16, v31
	v_and_b32_e32 v39, 0xffff0000, v31
	s_waitcnt vmcnt(11)
	s_nop 1
	v_mov_b64_e32 v[28:29], v[216:217]
	v_mov_b64_e32 v[30:31], v[218:219]
	v_lshlrev_b32_e32 v40, 16, v28
	v_fmac_f32_e32 v40, v24, v32
	v_and_b32_e32 v24, 0xffff0000, v28
	v_fmac_f32_e32 v24, v25, v33
	v_lshlrev_b32_e32 v25, 16, v29
	v_fmac_f32_e32 v25, v26, v34
	v_and_b32_e32 v26, 0xffff0000, v29
	v_fmac_f32_e32 v26, v27, v35
	v_lshlrev_b32_e32 v27, 16, v30
	v_fmac_f32_e32 v27, v20, v36
	v_and_b32_e32 v28, 0xffff0000, v30
	v_lshlrev_b32_e32 v29, 16, v31
	v_and_b32_e32 v30, 0xffff0000, v31
	v_cvt_pk_bf16_f32 v20, v40, v24
	v_fmac_f32_e32 v28, v21, v37
	v_fmac_f32_e32 v29, v22, v38
	v_fmac_f32_e32 v30, v23, v39
	v_cvt_pk_bf16_f32 v21, v25, v26
	v_cvt_pk_bf16_f32 v22, v27, v28
	v_cvt_pk_bf16_f32 v23, v29, v30
	global_store_dwordx4 v[42:43], v[20:23], off offset:256
	s_nop 1
	v_add_u32_e32 v20, 0xb0, v134
	v_ashrrev_i32_e32 v21, 31, v20
	v_lshlrev_b64 v[22:23], 13, v[20:21]
	v_lshlrev_b64 v[26:27], 12, v[20:21]
	v_lshl_add_u64 v[20:21], s[2:3], 0, v[22:23]
	v_lshl_add_u64 v[22:23], v[20:21], 0, v[132:133]
	v_lshl_add_u64 v[20:21], v[22:23], 0, s[20:21]
	v_add_co_u32_e32 v22, vcc, s76, v22
	s_mov_b64 s[20:21], s[16:17]
	s_nop 0
	v_addc_co_u32_e32 v23, vcc, 0, v23, vcc
	s_andn2_b64 vcc, exec, s[6:7]
	s_waitcnt vmcnt(9)
	s_nop 1
	v_mov_b64_e32 v[22:23], v[220:221]
	v_mov_b64_e32 v[24:25], v[222:223]
	v_lshlrev_b32_e32 v28, 16, v22
	v_and_b32_e32 v29, 0xffff0000, v22
	v_lshlrev_b32_e32 v30, 16, v23
	v_and_b32_e32 v31, 0xffff0000, v23
	v_lshl_add_u64 v[22:23], s[12:13], 0, v[26:27]
	v_lshl_add_u64 v[26:27], v[22:23], 0, v[132:133]
	v_lshlrev_b32_e32 v32, 16, v24
	v_and_b32_e32 v33, 0xffff0000, v24
	v_lshlrev_b32_e32 v34, 16, v25
	v_and_b32_e32 v35, 0xffff0000, v25
	s_waitcnt vmcnt(8)
	s_nop 1
	v_mov_b64_e32 v[22:23], v[224:225]
	v_mov_b64_e32 v[24:25], v[226:227]
	v_lshlrev_b32_e32 v36, 16, v22
	v_fmac_f32_e32 v36, v16, v28
	v_and_b32_e32 v16, 0xffff0000, v22
	v_fmac_f32_e32 v16, v17, v29
	v_lshlrev_b32_e32 v17, 16, v23
	v_fmac_f32_e32 v17, v18, v30
	v_and_b32_e32 v18, 0xffff0000, v23
	v_fmac_f32_e32 v18, v19, v31
	v_lshlrev_b32_e32 v19, 16, v24
	v_and_b32_e32 v22, 0xffff0000, v24
	v_lshlrev_b32_e32 v23, 16, v25
	v_and_b32_e32 v24, 0xffff0000, v25
	v_fmac_f32_e32 v19, v12, v32
	v_fmac_f32_e32 v22, v13, v33
	v_fmac_f32_e32 v23, v14, v34
	v_fmac_f32_e32 v24, v15, v35
	v_cvt_pk_bf16_f32 v12, v36, v16
	v_cvt_pk_bf16_f32 v13, v17, v18
	v_cvt_pk_bf16_f32 v14, v19, v22
	v_cvt_pk_bf16_f32 v15, v23, v24
	global_store_dwordx4 v[26:27], v[12:15], off
	s_waitcnt vmcnt(8)
	s_nop 1
	v_mov_b64_e32 v[12:13], v[228:229]
	v_mov_b64_e32 v[14:15], v[230:231]
	v_lshlrev_b32_e32 v16, 16, v12
	v_and_b32_e32 v17, 0xffff0000, v12
	v_lshlrev_b32_e32 v18, 16, v13
	v_and_b32_e32 v19, 0xffff0000, v13
	v_lshlrev_b32_e32 v20, 16, v14
	v_and_b32_e32 v21, 0xffff0000, v14
	v_lshlrev_b32_e32 v22, 16, v15
	v_and_b32_e32 v23, 0xffff0000, v15
	s_waitcnt vmcnt(7)
	s_nop 1
	v_mov_b64_e32 v[12:13], v[232:233]
	v_mov_b64_e32 v[14:15], v[234:235]
	v_lshlrev_b32_e32 v24, 16, v12
	v_fmac_f32_e32 v24, v4, v16
	v_and_b32_e32 v4, 0xffff0000, v12
	v_fmac_f32_e32 v4, v5, v17
	v_lshlrev_b32_e32 v5, 16, v13
	v_fmac_f32_e32 v5, v6, v18
	v_and_b32_e32 v6, 0xffff0000, v13
	v_fmac_f32_e32 v6, v7, v19
	v_lshlrev_b32_e32 v7, 16, v14
	v_fmac_f32_e32 v7, v8, v20
	v_and_b32_e32 v8, 0xffff0000, v14
	v_fmac_f32_e32 v8, v9, v21
	v_lshlrev_b32_e32 v9, 16, v15
	v_fmac_f32_e32 v9, v10, v22
	v_and_b32_e32 v10, 0xffff0000, v15
	v_fmac_f32_e32 v10, v11, v23
	v_cvt_pk_bf16_f32 v4, v24, v4
	v_cvt_pk_bf16_f32 v5, v5, v6
	v_cvt_pk_bf16_f32 v6, v7, v8
	v_cvt_pk_bf16_f32 v7, v9, v10
	global_store_dwordx4 v[26:27], v[4:7], off offset:256
	s_cbranch_vccnz .LBB0_164
	s_waitcnt vmcnt(0) lgkmcnt(0)
	s_barrier

.LBB0_195:
	s_waitcnt vmcnt(2) lgkmcnt(0)
	s_barrier
	ds_read_b128 v[146:149], v132
	ds_read_b128 v[174:177], v152
	ds_read_b128 v[158:161], v132 offset:2048
	ds_read_b128 v[182:185], v152 offset:2048
	s_add_u32 s58, s18, s57
	s_addc_u32 s59, s19, 0
	s_add_u32 s24, s58, 0x80
	s_addc_u32 s25, s59, 0
	s_mov_b32 m0, s43
	s_nop 0
	global_load_lds_dwordx4 v137, s[24:25]
	s_mov_b32 m0, s47
	s_nop 0
	global_load_lds_dwordx4 v139, s[24:25]
	s_waitcnt lgkmcnt(2)
	v_mfma_f32_16x16x32_bf16 v[128:131], v[146:149], v[174:177], v[128:131]
	ds_read_b128 v[190:193], v152 offset:4096
	s_waitcnt lgkmcnt(2)
	v_mfma_f32_16x16x32_bf16 v[124:127], v[158:161], v[174:177], v[124:127]
	ds_read_b128 v[198:201], v152 offset:6144
	s_waitcnt lgkmcnt(2)
	v_mfma_f32_16x16x32_bf16 v[112:115], v[146:149], v[182:185], v[112:115]
	v_mfma_f32_16x16x32_bf16 v[108:111], v[158:161], v[182:185], v[108:111]
	ds_read_b128 v[154:157], v132 offset:1024
	ds_read_b128 v[178:181], v152 offset:1024
	s_waitcnt lgkmcnt(3)
	v_mfma_f32_16x16x32_bf16 v[96:99], v[146:149], v[190:193], v[96:99]
	ds_read_b128 v[170:173], v132 offset:3072
	v_mfma_f32_16x16x32_bf16 v[92:95], v[158:161], v[190:193], v[92:95]
	ds_read_b128 v[186:189], v152 offset:3072
	s_waitcnt lgkmcnt(4)
	v_mfma_f32_16x16x32_bf16 v[80:83], v[146:149], v[198:201], v[80:83]
	v_mfma_f32_16x16x32_bf16 v[76:79], v[158:161], v[198:201], v[76:79]
	ds_read_b128 v[194:197], v152 offset:5120
	s_waitcnt lgkmcnt(3)
	v_mfma_f32_16x16x32_bf16 v[128:131], v[154:157], v[178:181], v[128:131]
	s_waitcnt lgkmcnt(2)
	v_mfma_f32_16x16x32_bf16 v[124:127], v[170:173], v[178:181], v[124:127]
	ds_read_b128 v[202:205], v152 offset:7168
	s_waitcnt lgkmcnt(2)
	v_mfma_f32_16x16x32_bf16 v[112:115], v[154:157], v[186:189], v[112:115]
	v_mfma_f32_16x16x32_bf16 v[108:111], v[170:173], v[186:189], v[108:111]
	ds_read_b128 v[206:209], v133
	s_waitcnt lgkmcnt(2)
	v_mfma_f32_16x16x32_bf16 v[96:99], v[154:157], v[194:197], v[96:99]
	ds_read_b128 v[214:217], v133 offset:2048
	v_mfma_f32_16x16x32_bf16 v[92:95], v[170:173], v[194:197], v[92:95]
	s_waitcnt lgkmcnt(2)
	v_mfma_f32_16x16x32_bf16 v[80:83], v[154:157], v[202:205], v[80:83]
	v_mfma_f32_16x16x32_bf16 v[76:79], v[170:173], v[202:205], v[76:79]
	s_add_u32 s60, s20, s57
	s_addc_u32 s61, s21, 0
	s_add_u32 s24, s60, 0x80
	s_addc_u32 s25, s61, 0
	s_mov_b32 m0, s44
	s_nop 0
	global_load_lds_dwordx4 v136, s[24:25]
	s_mov_b32 m0, s48
	s_nop 0
	global_load_lds_dwordx4 v138, s[24:25]
	s_waitcnt lgkmcnt(1)
	v_mfma_f32_16x16x32_bf16 v[120:123], v[206:209], v[174:177], v[120:123]
	s_waitcnt lgkmcnt(0)
	v_mfma_f32_16x16x32_bf16 v[116:119], v[214:217], v[174:177], v[116:119]
	v_mfma_f32_16x16x32_bf16 v[104:107], v[206:209], v[182:185], v[104:107]
	v_mfma_f32_16x16x32_bf16 v[100:103], v[214:217], v[182:185], v[100:103]
	ds_read_b128 v[210:213], v133 offset:1024
	v_mfma_f32_16x16x32_bf16 v[88:91], v[206:209], v[190:193], v[88:91]
	ds_read_b128 v[218:221], v133 offset:3072
	v_mfma_f32_16x16x32_bf16 v[84:87], v[214:217], v[190:193], v[84:87]
	v_mfma_f32_16x16x32_bf16 v[72:75], v[206:209], v[198:201], v[72:75]
	v_mfma_f32_16x16x32_bf16 v[68:71], v[214:217], v[198:201], v[68:71]
	s_waitcnt lgkmcnt(1)
	v_mfma_f32_16x16x32_bf16 v[120:123], v[210:213], v[178:181], v[120:123]
	s_waitcnt lgkmcnt(0)
	v_mfma_f32_16x16x32_bf16 v[116:119], v[218:221], v[178:181], v[116:119]
	v_mfma_f32_16x16x32_bf16 v[104:107], v[210:213], v[186:189], v[104:107]
	v_mfma_f32_16x16x32_bf16 v[100:103], v[218:221], v[186:189], v[100:103]
	v_mfma_f32_16x16x32_bf16 v[88:91], v[210:213], v[194:197], v[88:91]
	v_mfma_f32_16x16x32_bf16 v[84:87], v[218:221], v[194:197], v[84:87]
	v_mfma_f32_16x16x32_bf16 v[72:75], v[210:213], v[202:205], v[72:75]
	v_mfma_f32_16x16x32_bf16 v[68:71], v[218:221], v[202:205], v[68:71]
	s_waitcnt vmcnt(4) lgkmcnt(0)
	s_barrier
	ds_read_b128 v[174:177], v152 offset:16384
	ds_read_b128 v[182:185], v152 offset:18432
	s_add_u32 s24, s58, 0x20080
	s_addc_u32 s25, s59, 0
	s_mov_b32 m0, s45
	s_nop 0
	global_load_lds_dwordx4 v137, s[24:25]
	s_mov_b32 m0, s49
	s_nop 0
	global_load_lds_dwordx4 v139, s[24:25]
	s_waitcnt lgkmcnt(1)
	v_mfma_f32_16x16x32_bf16 v[64:67], v[146:149], v[174:177], v[64:67]
	ds_read_b128 v[190:193], v152 offset:20480
	v_mfma_f32_16x16x32_bf16 v[60:63], v[158:161], v[174:177], v[60:63]
	ds_read_b128 v[198:201], v152 offset:22528
	s_waitcnt lgkmcnt(2)
	v_mfma_f32_16x16x32_bf16 v[48:51], v[146:149], v[182:185], v[48:51]
	v_mfma_f32_16x16x32_bf16 v[44:47], v[158:161], v[182:185], v[44:47]
	ds_read_b128 v[178:181], v152 offset:17408
	s_waitcnt lgkmcnt(2)
	v_mfma_f32_16x16x32_bf16 v[32:35], v[146:149], v[190:193], v[32:35]
	v_mfma_f32_16x16x32_bf16 v[28:31], v[158:161], v[190:193], v[28:31]
	ds_read_b128 v[186:189], v152 offset:19456
	s_waitcnt lgkmcnt(2)
	v_mfma_f32_16x16x32_bf16 v[16:19], v[146:149], v[198:201], v[16:19]
	v_mfma_f32_16x16x32_bf16 v[12:15], v[158:161], v[198:201], v[12:15]
	ds_read_b128 v[194:197], v152 offset:21504
	s_waitcnt lgkmcnt(2)
	v_mfma_f32_16x16x32_bf16 v[64:67], v[154:157], v[178:181], v[64:67]
	v_mfma_f32_16x16x32_bf16 v[60:63], v[170:173], v[178:181], v[60:63]
	ds_read_b128 v[202:205], v152 offset:23552
	s_waitcnt lgkmcnt(2)
	v_mfma_f32_16x16x32_bf16 v[48:51], v[154:157], v[186:189], v[48:51]
	v_mfma_f32_16x16x32_bf16 v[44:47], v[170:173], v[186:189], v[44:47]
	s_waitcnt lgkmcnt(1)
	v_mfma_f32_16x16x32_bf16 v[32:35], v[154:157], v[194:197], v[32:35]
	v_mfma_f32_16x16x32_bf16 v[28:31], v[170:173], v[194:197], v[28:31]
	s_waitcnt lgkmcnt(0)
	v_mfma_f32_16x16x32_bf16 v[16:19], v[154:157], v[202:205], v[16:19]
	v_mfma_f32_16x16x32_bf16 v[12:15], v[170:173], v[202:205], v[12:15]
	s_add_u32 s24, s60, 0x20080
	s_addc_u32 s25, s61, 0
	s_mov_b32 m0, s46
	s_nop 0
	global_load_lds_dwordx4 v136, s[24:25]
	s_mov_b32 m0, s50
	s_nop 0
	global_load_lds_dwordx4 v138, s[24:25]
	v_mfma_f32_16x16x32_bf16 v[56:59], v[206:209], v[174:177], v[56:59]
	s_add_u32 s24, s60, 0x100
	s_addc_u32 s25, s61, 0
	s_add_u32 s58, s58, 0x100
	v_mfma_f32_16x16x32_bf16 v[52:55], v[214:217], v[174:177], v[52:55]
	s_addc_u32 s59, s59, 0
	v_mfma_f32_16x16x32_bf16 v[40:43], v[206:209], v[182:185], v[40:43]
	v_mfma_f32_16x16x32_bf16 v[36:39], v[214:217], v[182:185], v[36:39]
	v_mfma_f32_16x16x32_bf16 v[24:27], v[206:209], v[190:193], v[24:27]
	v_mfma_f32_16x16x32_bf16 v[20:23], v[214:217], v[190:193], v[20:23]
	v_mfma_f32_16x16x32_bf16 v[4:7], v[206:209], v[198:201], v[4:7]
	v_mfma_f32_16x16x32_bf16 v[8:11], v[214:217], v[198:201], v[8:11]
	v_mfma_f32_16x16x32_bf16 v[56:59], v[210:213], v[178:181], v[56:59]
	v_mfma_f32_16x16x32_bf16 v[52:55], v[218:221], v[178:181], v[52:55]
	v_mfma_f32_16x16x32_bf16 v[40:43], v[210:213], v[186:189], v[40:43]
	v_mfma_f32_16x16x32_bf16 v[36:39], v[218:221], v[186:189], v[36:39]
	v_mfma_f32_16x16x32_bf16 v[24:27], v[210:213], v[194:197], v[24:27]
	v_mfma_f32_16x16x32_bf16 v[20:23], v[218:221], v[194:197], v[20:23]
	v_mfma_f32_16x16x32_bf16 v[4:7], v[210:213], v[202:205], v[4:7]
	v_mfma_f32_16x16x32_bf16 v[8:11], v[218:221], v[202:205], v[8:11]
	s_waitcnt vmcnt(2) lgkmcnt(0)
	s_barrier
; template <class Epi, class Sched>
; __device__ __forceinline__ void gemm_simple(PG8_LAS unsigned char* lds, const Gemm g, const Sched& S, const Epi& E, int wave_s) {
;     ...
;         for (; t < nt; t += 2) {
;             const bool last = (t == nt - 2);
;             PG8_TILE(0, cA + (size_t)(t + 1) * kstep, cB + (size_t)(t + 1) * kstep, true);
;             const char* a2 = last ? nA : cA + (size_t)(t + 2) * kstep; const char* b2 = last ? nB : cB + (size_t)(t + 2) * kstep;
;             PG8_TILE(1, a2, b2, (!last || has_next));
;         }
	ds_read_b128 v[146:149], v134
	ds_read_b128 v[174:177], v152 offset:32768
	ds_read_b128 v[158:161], v134 offset:2048
	ds_read_b128 v[182:185], v152 offset:34816
	s_cmp_eq_u32 s57, s22
	s_cselect_b32 s25, s9, s25
	s_cselect_b32 s24, s54, s24
	s_cselect_b32 s59, s5, s59
	s_cselect_b32 s58, s55, s58
	s_mov_b32 m0, s36
	s_nop 0
	global_load_lds_dwordx4 v137, s[58:59]
	s_mov_b32 m0, s37
	s_nop 0
	global_load_lds_dwordx4 v139, s[58:59]
	s_waitcnt lgkmcnt(2)
	v_mfma_f32_16x16x32_bf16 v[128:131], v[146:149], v[174:177], v[128:131]
	ds_read_b128 v[190:193], v152 offset:36864
	s_waitcnt lgkmcnt(2)
	v_mfma_f32_16x16x32_bf16 v[124:127], v[158:161], v[174:177], v[124:127]
	ds_read_b128 v[198:201], v152 offset:38912
	s_waitcnt lgkmcnt(2)
	v_mfma_f32_16x16x32_bf16 v[112:115], v[146:149], v[182:185], v[112:115]
	v_mfma_f32_16x16x32_bf16 v[108:111], v[158:161], v[182:185], v[108:111]
	ds_read_b128 v[154:157], v134 offset:1024
	ds_read_b128 v[178:181], v152 offset:33792
	s_waitcnt lgkmcnt(3)
	v_mfma_f32_16x16x32_bf16 v[96:99], v[146:149], v[190:193], v[96:99]
	ds_read_b128 v[170:173], v134 offset:3072
	v_mfma_f32_16x16x32_bf16 v[92:95], v[158:161], v[190:193], v[92:95]
	ds_read_b128 v[186:189], v152 offset:35840
	s_waitcnt lgkmcnt(4)
	v_mfma_f32_16x16x32_bf16 v[80:83], v[146:149], v[198:201], v[80:83]
	v_mfma_f32_16x16x32_bf16 v[76:79], v[158:161], v[198:201], v[76:79]
	ds_read_b128 v[194:197], v152 offset:37888
	s_waitcnt lgkmcnt(3)
	v_mfma_f32_16x16x32_bf16 v[128:131], v[154:157], v[178:181], v[128:131]
	s_waitcnt lgkmcnt(2)
	v_mfma_f32_16x16x32_bf16 v[124:127], v[170:173], v[178:181], v[124:127]
	ds_read_b128 v[202:205], v152 offset:39936
	s_waitcnt lgkmcnt(2)
	v_mfma_f32_16x16x32_bf16 v[112:115], v[154:157], v[186:189], v[112:115]
	v_mfma_f32_16x16x32_bf16 v[108:111], v[170:173], v[186:189], v[108:111]
	ds_read_b128 v[206:209], v135
	s_waitcnt lgkmcnt(2)
	v_mfma_f32_16x16x32_bf16 v[96:99], v[154:157], v[194:197], v[96:99]
	ds_read_b128 v[214:217], v135 offset:2048
	v_mfma_f32_16x16x32_bf16 v[92:95], v[170:173], v[194:197], v[92:95]
	s_waitcnt lgkmcnt(2)
	v_mfma_f32_16x16x32_bf16 v[80:83], v[154:157], v[202:205], v[80:83]
	v_mfma_f32_16x16x32_bf16 v[76:79], v[170:173], v[202:205], v[76:79]
	s_mov_b32 m0, s17
	s_nop 0
	global_load_lds_dwordx4 v136, s[24:25]
	s_mov_b32 m0, s38
	s_nop 0
	global_load_lds_dwordx4 v138, s[24:25]
	s_waitcnt lgkmcnt(1)
	v_mfma_f32_16x16x32_bf16 v[120:123], v[206:209], v[174:177], v[120:123]
	s_waitcnt lgkmcnt(0)
	v_mfma_f32_16x16x32_bf16 v[116:119], v[214:217], v[174:177], v[116:119]
	v_mfma_f32_16x16x32_bf16 v[104:107], v[206:209], v[182:185], v[104:107]
	v_mfma_f32_16x16x32_bf16 v[100:103], v[214:217], v[182:185], v[100:103]
	ds_read_b128 v[210:213], v135 offset:1024
	v_mfma_f32_16x16x32_bf16 v[88:91], v[206:209], v[190:193], v[88:91]
	ds_read_b128 v[218:221], v135 offset:3072
	v_mfma_f32_16x16x32_bf16 v[84:87], v[214:217], v[190:193], v[84:87]
	v_mfma_f32_16x16x32_bf16 v[72:75], v[206:209], v[198:201], v[72:75]
	v_mfma_f32_16x16x32_bf16 v[68:71], v[214:217], v[198:201], v[68:71]
	s_waitcnt lgkmcnt(1)
	v_mfma_f32_16x16x32_bf16 v[120:123], v[210:213], v[178:181], v[120:123]
	s_waitcnt lgkmcnt(0)
	v_mfma_f32_16x16x32_bf16 v[116:119], v[218:221], v[178:181], v[116:119]
	v_mfma_f32_16x16x32_bf16 v[104:107], v[210:213], v[186:189], v[104:107]
	v_mfma_f32_16x16x32_bf16 v[100:103], v[218:221], v[186:189], v[100:103]
	v_mfma_f32_16x16x32_bf16 v[88:91], v[210:213], v[194:197], v[88:91]
	v_mfma_f32_16x16x32_bf16 v[84:87], v[218:221], v[194:197], v[84:87]
	v_mfma_f32_16x16x32_bf16 v[72:75], v[210:213], v[202:205], v[72:75]
	v_mfma_f32_16x16x32_bf16 v[68:71], v[218:221], v[202:205], v[68:71]
	s_waitcnt vmcnt(4) lgkmcnt(0)
	s_barrier
	ds_read_b128 v[174:177], v152 offset:49152
	ds_read_b128 v[182:185], v152 offset:51200
	s_add_u32 s58, s58, 0x20000
	s_addc_u32 s59, s59, 0
	s_mov_b32 m0, s39
	s_nop 0
	global_load_lds_dwordx4 v137, s[58:59]
	s_mov_b32 m0, s40
	s_nop 0
	global_load_lds_dwordx4 v139, s[58:59]
	s_waitcnt lgkmcnt(1)
	v_mfma_f32_16x16x32_bf16 v[64:67], v[146:149], v[174:177], v[64:67]
	ds_read_b128 v[190:193], v152 offset:53248
	v_mfma_f32_16x16x32_bf16 v[60:63], v[158:161], v[174:177], v[60:63]
	ds_read_b128 v[198:201], v152 offset:55296
	s_waitcnt lgkmcnt(2)
	v_mfma_f32_16x16x32_bf16 v[48:51], v[146:149], v[182:185], v[48:51]
	v_mfma_f32_16x16x32_bf16 v[44:47], v[158:161], v[182:185], v[44:47]
	ds_read_b128 v[178:181], v152 offset:50176
	s_waitcnt lgkmcnt(2)
	v_mfma_f32_16x16x32_bf16 v[32:35], v[146:149], v[190:193], v[32:35]
	v_mfma_f32_16x16x32_bf16 v[28:31], v[158:161], v[190:193], v[28:31]
	ds_read_b128 v[186:189], v152 offset:52224
	s_waitcnt lgkmcnt(2)
	v_mfma_f32_16x16x32_bf16 v[16:19], v[146:149], v[198:201], v[16:19]
	v_mfma_f32_16x16x32_bf16 v[12:15], v[158:161], v[198:201], v[12:15]
	ds_read_b128 v[194:197], v152 offset:54272
	s_waitcnt lgkmcnt(2)
	v_mfma_f32_16x16x32_bf16 v[64:67], v[154:157], v[178:181], v[64:67]
	v_mfma_f32_16x16x32_bf16 v[60:63], v[170:173], v[178:181], v[60:63]
	ds_read_b128 v[202:205], v152 offset:56320
	s_waitcnt lgkmcnt(2)
	v_mfma_f32_16x16x32_bf16 v[48:51], v[154:157], v[186:189], v[48:51]
	v_mfma_f32_16x16x32_bf16 v[44:47], v[170:173], v[186:189], v[44:47]
	s_waitcnt lgkmcnt(1)
	v_mfma_f32_16x16x32_bf16 v[32:35], v[154:157], v[194:197], v[32:35]
	v_mfma_f32_16x16x32_bf16 v[28:31], v[170:173], v[194:197], v[28:31]
	s_waitcnt lgkmcnt(0)
	v_mfma_f32_16x16x32_bf16 v[16:19], v[154:157], v[202:205], v[16:19]
	v_mfma_f32_16x16x32_bf16 v[12:15], v[170:173], v[202:205], v[12:15]
	s_add_u32 s24, s24, 0x20000
	s_addc_u32 s25, s25, 0
	s_mov_b32 m0, s41
	s_nop 0
	global_load_lds_dwordx4 v136, s[24:25]
	s_mov_b32 m0, s42
	s_nop 0
	global_load_lds_dwordx4 v138, s[24:25]
	v_mfma_f32_16x16x32_bf16 v[56:59], v[206:209], v[174:177], v[56:59]
	s_add_i32 s56, s56, 2
	s_add_u32 s22, s22, 0xffffff00
	s_addc_u32 s23, s23, -1
	v_mfma_f32_16x16x32_bf16 v[52:55], v[214:217], v[174:177], v[52:55]
	s_add_u32 s18, s18, 0x100
	s_addc_u32 s19, s19, 0
	s_add_u32 s20, s20, 0x100
	v_mfma_f32_16x16x32_bf16 v[40:43], v[206:209], v[182:185], v[40:43]
	s_addc_u32 s21, s21, 0
	s_cmp_lt_u32 s56, 6
	v_mfma_f32_16x16x32_bf16 v[36:39], v[214:217], v[182:185], v[36:39]
	v_mfma_f32_16x16x32_bf16 v[24:27], v[206:209], v[190:193], v[24:27]
	v_mfma_f32_16x16x32_bf16 v[20:23], v[214:217], v[190:193], v[20:23]
	v_mfma_f32_16x16x32_bf16 v[4:7], v[206:209], v[198:201], v[4:7]
	v_mfma_f32_16x16x32_bf16 v[8:11], v[214:217], v[198:201], v[8:11]
	v_mfma_f32_16x16x32_bf16 v[56:59], v[210:213], v[178:181], v[56:59]
	v_mfma_f32_16x16x32_bf16 v[52:55], v[218:221], v[178:181], v[52:55]
	v_mfma_f32_16x16x32_bf16 v[40:43], v[210:213], v[186:189], v[40:43]
	v_mfma_f32_16x16x32_bf16 v[36:39], v[218:221], v[186:189], v[36:39]
	v_mfma_f32_16x16x32_bf16 v[24:27], v[210:213], v[194:197], v[24:27]
	v_mfma_f32_16x16x32_bf16 v[20:23], v[218:221], v[194:197], v[20:23]
	v_mfma_f32_16x16x32_bf16 v[4:7], v[210:213], v[202:205], v[4:7]
	v_mfma_f32_16x16x32_bf16 v[8:11], v[218:221], v[202:205], v[8:11]
	s_cbranch_scc1 .LBB0_195
; #define PG8_LAS __attribute__((address_space(3)))
; __device__ __forceinline__ unsigned cvt_pk_bf16(float lo, float hi) { unsigned r; asm volatile("v_cvt_pk_bf16_f32 %0, %1, %2" : "=v"(r) : "v"(lo), "v"(hi)); return r; }
; #define LAS __attribute__((address_space(3)))
; __device__ __forceinline__ float bflo(unsigned w) { return __uint_as_float(w << 16); }
; __device__ __forceinline__ float bfhi(unsigned w) { return __uint_as_float(w & 0xffff0000u); }
; template <class Epi, class Sched>
; __device__ __forceinline__ void gemm_simple(PG8_LAS unsigned char* lds, const Gemm g, const Sched& S, const Epi& E, int wave_s) {
;     ...
;         {   unsigned z2 = 0u; asm volatile("" : "+v"(z2)); const int lane2 = (int)__builtin_amdgcn_mbcnt_hi(~0u, __builtin_amdgcn_mbcnt_lo(~0u, z2));
;             E(acc, cur, wr, wc, lane2 & 15, lane2 >> 4, (const PG8_LAS float*)(lds + STAGE_BYTES + (ui & 1) * 1024)); }
;     __device__ __forceinline__ void operator()(const f32x4 (&acc)[2][2][4][2], const Unit& u, int wr, int wc, int fr, int fq, const LAS float*) const {
;         const int row0 = u.pm * 256 + wr * 64 + fr, col0 = u.pn * 256 + wc * 32 + 8 * fq;
; #pragma unroll
;         for (int ai = 0; ai < 2; ++ai)
; #pragma unroll
;             for (int m = 0; m < 4; ++m) { const size_t row = (size_t)(row0 + ai * 128 + m * 16);
; #pragma unroll
;                 for (int bj = 0; bj < 2; ++bj) { const int col = col0 + bj * 128;
;                     const u32x4 g = *(const u32x4*)(G + row * NGATE + MODE * DM + col);
;                     f32x4 v0 = acc[ai][bj][m][0], v1 = acc[ai][bj][m][1];
;                     v0[0] *= bflo(g.x); v0[1] *= bfhi(g.x); v0[2] *= bflo(g.y); v0[3] *= bfhi(g.y); v1[0] *= bflo(g.z); v1[1] *= bfhi(g.z); v1[2] *= bflo(g.w); v1[3] *= bfhi(g.w);
;                     bf16_t* tp = T + row * DM + col;
;                     if (MODE == 1) { const u32x4 t = *(const u32x4*)tp;
;                         v0[0] += bflo(t.x); v0[1] += bfhi(t.x); v0[2] += bflo(t.y); v0[3] += bfhi(t.y); v1[0] += bflo(t.z); v1[1] += bfhi(t.z); v1[2] += bflo(t.w); v1[3] += bfhi(t.w); }
;                     u32x4 w; w.x = cvt_pk_bf16(v0[0], v0[1]); w.y = cvt_pk_bf16(v0[2], v0[3]); w.z = cvt_pk_bf16(v1[0], v1[1]); w.w = cvt_pk_bf16(v1[2], v1[3]);
;                     *(u32x4*)tp = w; } }
	v_mov_b32_e32 v132, v141
	s_lshl_b32 s5, s16, 8
	v_mbcnt_lo_u32_b32 v132, -1, v132
	v_mbcnt_hi_u32_b32 v132, -1, v132
	s_add_i32 s5, s5, s29
	v_and_or_b32 v134, v132, 15, s5
	s_lshl_b32 s5, s53, 8
	v_ashrrev_i32_e32 v132, 1, v132
	s_or_b32 s5, s5, s35
	v_and_b32_e32 v132, -8, v132
	v_add_u32_e32 v132, s5, v132
	v_ashrrev_i32_e32 v135, 31, v134
	v_lshlrev_b64 v[142:143], 13, v[134:135]
	v_ashrrev_i32_e32 v133, 31, v132
	v_lshl_add_u64 v[142:143], s[2:3], 0, v[142:143]
	v_lshlrev_b64 v[132:133], 1, v[132:133]
	v_lshl_add_u64 v[142:143], v[142:143], 0, v[132:133]
	v_lshlrev_b32_e32 v236, 13, v134
	v_add_u32_e32 v236, v236, v132
	global_load_dwordx4 v[172:175], v236, s[2:3]
	global_load_dwordx4 v[176:179], v236, s[2:3] offset:256
	v_add_u32_e32 v237, 0x20000, v236
	global_load_dwordx4 v[180:183], v237, s[2:3]
	global_load_dwordx4 v[184:187], v237, s[2:3] offset:256
	v_add_u32_e32 v237, 0x40000, v236
	global_load_dwordx4 v[188:191], v237, s[2:3]
	global_load_dwordx4 v[192:195], v237, s[2:3] offset:256
	v_add_u32_e32 v237, 0x60000, v236
	global_load_dwordx4 v[196:199], v237, s[2:3]
	global_load_dwordx4 v[200:203], v237, s[2:3] offset:256
	v_add_u32_e32 v237, 0x100000, v236
	global_load_dwordx4 v[204:207], v237, s[2:3]
	global_load_dwordx4 v[208:211], v237, s[2:3] offset:256
	v_add_u32_e32 v237, 0x120000, v236
	global_load_dwordx4 v[212:215], v237, s[2:3]
	global_load_dwordx4 v[216:219], v237, s[2:3] offset:256
	v_add_u32_e32 v237, 0x140000, v236
	global_load_dwordx4 v[220:223], v237, s[2:3]
	global_load_dwordx4 v[224:227], v237, s[2:3] offset:256
	v_add_u32_e32 v237, 0x160000, v236
	global_load_dwordx4 v[228:231], v237, s[2:3]
	global_load_dwordx4 v[232:235], v237, s[2:3] offset:256
	v_lshlrev_b64 v[144:145], 12, v[134:135]
	s_andn2_b64 vcc, exec, s[6:7]
	s_mov_b32 s53, s4
	s_mov_b32 s16, s8
	s_mov_b64 s[18:19], s[14:15]
	s_mov_b64 s[20:21], s[10:11]
	s_mov_b32 s9, s52
	s_waitcnt vmcnt(15)
	s_nop 1
	v_mov_b64_e32 v[146:147], v[172:173]
	v_mov_b64_e32 v[148:149], v[174:175]
	v_lshlrev_b32_e32 v135, 16, v146
	v_mul_f32_e32 v135, v128, v135
	v_and_b32_e32 v128, 0xffff0000, v146
	v_mul_f32_e32 v146, v129, v128
	v_lshlrev_b32_e32 v128, 16, v147
	v_mul_f32_e32 v130, v130, v128
	v_and_b32_e32 v128, 0xffff0000, v147
	v_mul_f32_e32 v131, v131, v128
	v_lshlrev_b32_e32 v128, 16, v148
	v_mul_f32_e32 v147, v124, v128
	v_and_b32_e32 v124, 0xffff0000, v148
	v_mul_f32_e32 v148, v125, v124
	v_lshlrev_b32_e32 v124, 16, v149
	v_mul_f32_e32 v153, v126, v124
	v_and_b32_e32 v124, 0xffff0000, v149
	v_mul_f32_e32 v127, v127, v124
	v_lshl_add_u64 v[124:125], s[12:13], 0, v[144:145]
	v_lshl_add_u64 v[128:129], v[124:125], 0, v[132:133]
	v_cvt_pk_bf16_f32 v124, v135, v146
	v_cvt_pk_bf16_f32 v125, v130, v131
	v_cvt_pk_bf16_f32 v126, v147, v148
	v_cvt_pk_bf16_f32 v127, v153, v127
	global_store_dwordx4 v[128:129], v[124:127], off
	s_waitcnt vmcnt(15)
	s_nop 1
	v_mov_b64_e32 v[124:125], v[176:177]
	v_mov_b64_e32 v[126:127], v[178:179]
	v_lshlrev_b32_e32 v130, 16, v124
	v_and_b32_e32 v124, 0xffff0000, v124
	v_mul_f32_e32 v121, v121, v124
	v_lshlrev_b32_e32 v124, 16, v125
	v_mul_f32_e32 v122, v122, v124
	v_and_b32_e32 v124, 0xffff0000, v125
	v_mul_f32_e32 v123, v123, v124
	v_lshlrev_b32_e32 v124, 16, v126
	v_mul_f32_e32 v124, v116, v124
	v_and_b32_e32 v116, 0xffff0000, v126
	v_mul_f32_e32 v125, v117, v116
	v_lshlrev_b32_e32 v116, 16, v127
	v_mul_f32_e32 v126, v118, v116
	v_and_b32_e32 v116, 0xffff0000, v127
	v_mul_f32_e32 v120, v120, v130
	v_mul_f32_e32 v119, v119, v116
	v_cvt_pk_bf16_f32 v116, v120, v121
	v_cvt_pk_bf16_f32 v117, v122, v123
	v_cvt_pk_bf16_f32 v118, v124, v125
	v_cvt_pk_bf16_f32 v119, v126, v119
	global_store_dwordx4 v[128:129], v[116:119], off offset:256
	s_nop 1
	v_or_b32_e32 v116, 16, v134
	v_ashrrev_i32_e32 v117, 31, v116
	v_lshlrev_b64 v[118:119], 13, v[116:117]
	v_lshlrev_b64 v[120:121], 12, v[116:117]
	v_lshl_add_u64 v[116:117], s[2:3], 0, v[118:119]
	v_lshl_add_u64 v[122:123], v[116:117], 0, v[132:133]
	s_waitcnt vmcnt(15)
	s_nop 1
	v_mov_b64_e32 v[116:117], v[180:181]
	v_mov_b64_e32 v[118:119], v[182:183]
	v_lshlrev_b32_e32 v124, 16, v116
	v_mul_f32_e32 v124, v112, v124
	v_and_b32_e32 v112, 0xffff0000, v116
	v_mul_f32_e32 v116, v113, v112
	v_lshlrev_b32_e32 v112, 16, v117
	v_mul_f32_e32 v114, v114, v112
	v_and_b32_e32 v112, 0xffff0000, v117
	v_mul_f32_e32 v115, v115, v112
	v_lshlrev_b32_e32 v112, 16, v118
	v_mul_f32_e32 v117, v108, v112
	v_and_b32_e32 v108, 0xffff0000, v118
	v_mul_f32_e32 v118, v109, v108
	v_lshlrev_b32_e32 v108, 16, v119
	v_mul_f32_e32 v125, v110, v108
	v_and_b32_e32 v108, 0xffff0000, v119
	v_mul_f32_e32 v111, v111, v108
	v_lshl_add_u64 v[108:109], s[12:13], 0, v[120:121]
	v_lshl_add_u64 v[112:113], v[108:109], 0, v[132:133]
	v_cvt_pk_bf16_f32 v108, v124, v116
	v_cvt_pk_bf16_f32 v109, v114, v115
	v_cvt_pk_bf16_f32 v110, v117, v118
	v_cvt_pk_bf16_f32 v111, v125, v111
	global_store_dwordx4 v[112:113], v[108:111], off
	s_waitcnt vmcnt(15)
	s_nop 1
	v_mov_b64_e32 v[108:109], v[184:185]
	v_mov_b64_e32 v[110:111], v[186:187]
	v_lshlrev_b32_e32 v114, 16, v108
	v_and_b32_e32 v108, 0xffff0000, v108
	v_mul_f32_e32 v105, v105, v108
	v_lshlrev_b32_e32 v108, 16, v109
	v_mul_f32_e32 v106, v106, v108
	v_and_b32_e32 v108, 0xffff0000, v109
	v_mul_f32_e32 v107, v107, v108
	v_lshlrev_b32_e32 v108, 16, v110
	v_mul_f32_e32 v108, v100, v108
	v_and_b32_e32 v100, 0xffff0000, v110
	v_mul_f32_e32 v109, v101, v100
	v_lshlrev_b32_e32 v100, 16, v111
	v_mul_f32_e32 v110, v102, v100
	v_and_b32_e32 v100, 0xffff0000, v111
	v_mul_f32_e32 v104, v104, v114
	v_mul_f32_e32 v103, v103, v100
	v_cvt_pk_bf16_f32 v100, v104, v105
	v_cvt_pk_bf16_f32 v101, v106, v107
	v_cvt_pk_bf16_f32 v102, v108, v109
	v_cvt_pk_bf16_f32 v103, v110, v103
	global_store_dwordx4 v[112:113], v[100:103], off offset:256
	s_nop 1
	v_or_b32_e32 v100, 32, v134
	v_ashrrev_i32_e32 v101, 31, v100
	v_lshlrev_b64 v[102:103], 13, v[100:101]
	v_lshlrev_b64 v[104:105], 12, v[100:101]
	v_lshl_add_u64 v[100:101], s[2:3], 0, v[102:103]
	v_lshl_add_u64 v[106:107], v[100:101], 0, v[132:133]
	s_waitcnt vmcnt(15)
; __device__ __forceinline__ unsigned cvt_pk_bf16(float lo, float hi) { unsigned r; asm volatile("v_cvt_pk_bf16_f32 %0, %1, %2" : "=v"(r) : "v"(lo), "v"(hi)); return r; }
; __device__ __forceinline__ float bflo(unsigned w) { return __uint_as_float(w << 16); }
; __device__ __forceinline__ float bfhi(unsigned w) { return __uint_as_float(w & 0xffff0000u); }
;     __device__ __forceinline__ void operator()(const f32x4 (&acc)[2][2][4][2], const Unit& u, int wr, int wc, int fr, int fq, const LAS float*) const {
;     ...
;             for (int m = 0; m < 4; ++m) { const size_t row = (size_t)(row0 + ai * 128 + m * 16);
; #pragma unroll
;                 for (int bj = 0; bj < 2; ++bj) { const int col = col0 + bj * 128;
;                     const u32x4 g = *(const u32x4*)(G + row * NGATE + MODE * DM + col);
;                     f32x4 v0 = acc[ai][bj][m][0], v1 = acc[ai][bj][m][1];
;                     v0[0] *= bflo(g.x); v0[1] *= bfhi(g.x); v0[2] *= bflo(g.y); v0[3] *= bfhi(g.y); v1[0] *= bflo(g.z); v1[1] *= bfhi(g.z); v1[2] *= bflo(g.w); v1[3] *= bfhi(g.w);
;                     bf16_t* tp = T + row * DM + col;
;                     if (MODE == 1) { const u32x4 t = *(const u32x4*)tp;
;                         v0[0] += bflo(t.x); v0[1] += bfhi(t.x); v0[2] += bflo(t.y); v0[3] += bfhi(t.y); v1[0] += bflo(t.z); v1[1] += bfhi(t.z); v1[2] += bflo(t.w); v1[3] += bfhi(t.w); }
;                     u32x4 w; w.x = cvt_pk_bf16(v0[0], v0[1]); w.y = cvt_pk_bf16(v0[2], v0[3]); w.z = cvt_pk_bf16(v1[0], v1[1]); w.w = cvt_pk_bf16(v1[2], v1[3]);
;                     *(u32x4*)tp = w; } }
	s_nop 1
	v_mov_b64_e32 v[100:101], v[188:189]
	v_mov_b64_e32 v[102:103], v[190:191]
	v_lshlrev_b32_e32 v108, 16, v100
	v_mul_f32_e32 v108, v96, v108
	v_and_b32_e32 v96, 0xffff0000, v100
	v_mul_f32_e32 v100, v97, v96
	v_lshlrev_b32_e32 v96, 16, v101
	v_mul_f32_e32 v98, v98, v96
	v_and_b32_e32 v96, 0xffff0000, v101
	v_mul_f32_e32 v99, v99, v96
	v_lshlrev_b32_e32 v96, 16, v102
	v_mul_f32_e32 v101, v92, v96
	v_and_b32_e32 v92, 0xffff0000, v102
	v_mul_f32_e32 v102, v93, v92
	v_lshlrev_b32_e32 v92, 16, v103
	v_mul_f32_e32 v109, v94, v92
	v_and_b32_e32 v92, 0xffff0000, v103
	v_mul_f32_e32 v95, v95, v92
	v_lshl_add_u64 v[92:93], s[12:13], 0, v[104:105]
	v_lshl_add_u64 v[96:97], v[92:93], 0, v[132:133]
	v_cvt_pk_bf16_f32 v92, v108, v100
	v_cvt_pk_bf16_f32 v93, v98, v99
	v_cvt_pk_bf16_f32 v94, v101, v102
	v_cvt_pk_bf16_f32 v95, v109, v95
	global_store_dwordx4 v[96:97], v[92:95], off
	s_waitcnt vmcnt(15)
	s_nop 1
	v_mov_b64_e32 v[92:93], v[192:193]
	v_mov_b64_e32 v[94:95], v[194:195]
	v_lshlrev_b32_e32 v98, 16, v92
	v_and_b32_e32 v92, 0xffff0000, v92
	v_mul_f32_e32 v89, v89, v92
	v_lshlrev_b32_e32 v92, 16, v93
	v_mul_f32_e32 v90, v90, v92
	v_and_b32_e32 v92, 0xffff0000, v93
	v_mul_f32_e32 v91, v91, v92
	v_lshlrev_b32_e32 v92, 16, v94
	v_mul_f32_e32 v92, v84, v92
	v_and_b32_e32 v84, 0xffff0000, v94
	v_mul_f32_e32 v93, v85, v84
	v_lshlrev_b32_e32 v84, 16, v95
	v_mul_f32_e32 v94, v86, v84
	v_and_b32_e32 v84, 0xffff0000, v95
	v_mul_f32_e32 v88, v88, v98
	v_mul_f32_e32 v87, v87, v84
	v_cvt_pk_bf16_f32 v84, v88, v89
	v_cvt_pk_bf16_f32 v85, v90, v91
	v_cvt_pk_bf16_f32 v86, v92, v93
	v_cvt_pk_bf16_f32 v87, v94, v87
	global_store_dwordx4 v[96:97], v[84:87], off offset:256
	s_nop 1
	v_or_b32_e32 v84, 48, v134
	v_ashrrev_i32_e32 v85, 31, v84
	v_lshlrev_b64 v[86:87], 13, v[84:85]
	v_lshlrev_b64 v[88:89], 12, v[84:85]
	v_lshl_add_u64 v[84:85], s[2:3], 0, v[86:87]
	v_lshl_add_u64 v[90:91], v[84:85], 0, v[132:133]
	s_waitcnt vmcnt(15)
	s_nop 1
	v_mov_b64_e32 v[84:85], v[196:197]
	v_mov_b64_e32 v[86:87], v[198:199]
	v_lshlrev_b32_e32 v92, 16, v84
	v_mul_f32_e32 v92, v80, v92
	v_and_b32_e32 v80, 0xffff0000, v84
	v_mul_f32_e32 v84, v81, v80
	v_lshlrev_b32_e32 v80, 16, v85
	v_mul_f32_e32 v82, v82, v80
	v_and_b32_e32 v80, 0xffff0000, v85
	v_mul_f32_e32 v83, v83, v80
	v_lshlrev_b32_e32 v80, 16, v86
	v_mul_f32_e32 v85, v76, v80
	v_and_b32_e32 v76, 0xffff0000, v86
	v_mul_f32_e32 v86, v77, v76
	v_lshlrev_b32_e32 v76, 16, v87
	v_mul_f32_e32 v93, v78, v76
	v_and_b32_e32 v76, 0xffff0000, v87
	v_mul_f32_e32 v79, v79, v76
	v_lshl_add_u64 v[76:77], s[12:13], 0, v[88:89]
	v_lshl_add_u64 v[80:81], v[76:77], 0, v[132:133]
	v_cvt_pk_bf16_f32 v76, v92, v84
	v_cvt_pk_bf16_f32 v77, v82, v83
	v_cvt_pk_bf16_f32 v78, v85, v86
	v_cvt_pk_bf16_f32 v79, v93, v79
	global_store_dwordx4 v[80:81], v[76:79], off
	s_waitcnt vmcnt(15)
	s_nop 1
	v_mov_b64_e32 v[76:77], v[200:201]
	v_mov_b64_e32 v[78:79], v[202:203]
	v_lshlrev_b32_e32 v82, 16, v76
	v_and_b32_e32 v76, 0xffff0000, v76
	v_mul_f32_e32 v73, v73, v76
	v_lshlrev_b32_e32 v76, 16, v77
	v_mul_f32_e32 v74, v74, v76
	v_and_b32_e32 v76, 0xffff0000, v77
	v_mul_f32_e32 v75, v75, v76
	v_lshlrev_b32_e32 v76, 16, v78
	v_mul_f32_e32 v76, v68, v76
	v_and_b32_e32 v68, 0xffff0000, v78
	v_mul_f32_e32 v77, v69, v68
	v_lshlrev_b32_e32 v68, 16, v79
	v_mul_f32_e32 v78, v70, v68
	v_and_b32_e32 v68, 0xffff0000, v79
	v_mul_f32_e32 v72, v72, v82
	v_mul_f32_e32 v71, v71, v68
	v_cvt_pk_bf16_f32 v68, v72, v73
	v_cvt_pk_bf16_f32 v69, v74, v75
	v_cvt_pk_bf16_f32 v70, v76, v77
	v_cvt_pk_bf16_f32 v71, v78, v71
	global_store_dwordx4 v[80:81], v[68:71], off offset:256
	s_nop 1
	v_add_u32_e32 v68, 0x80, v134
	v_ashrrev_i32_e32 v69, 31, v68
	v_lshlrev_b64 v[70:71], 13, v[68:69]
	v_lshlrev_b64 v[72:73], 12, v[68:69]
	v_lshl_add_u64 v[68:69], s[2:3], 0, v[70:71]
	v_lshl_add_u64 v[74:75], v[68:69], 0, v[132:133]
	s_waitcnt vmcnt(15)
	s_nop 1
	v_mov_b64_e32 v[68:69], v[204:205]
	v_mov_b64_e32 v[70:71], v[206:207]
	v_lshlrev_b32_e32 v76, 16, v68
	v_mul_f32_e32 v76, v64, v76
	v_and_b32_e32 v64, 0xffff0000, v68
	v_mul_f32_e32 v68, v65, v64
	v_lshlrev_b32_e32 v64, 16, v69
	v_mul_f32_e32 v66, v66, v64
	v_and_b32_e32 v64, 0xffff0000, v69
	v_mul_f32_e32 v67, v67, v64
	v_lshlrev_b32_e32 v64, 16, v70
	v_mul_f32_e32 v69, v60, v64
	v_and_b32_e32 v60, 0xffff0000, v70
	v_mul_f32_e32 v70, v61, v60
	v_lshlrev_b32_e32 v60, 16, v71
	v_mul_f32_e32 v77, v62, v60
	v_and_b32_e32 v60, 0xffff0000, v71
	v_mul_f32_e32 v63, v63, v60
	v_lshl_add_u64 v[60:61], s[12:13], 0, v[72:73]
	v_lshl_add_u64 v[64:65], v[60:61], 0, v[132:133]
	v_cvt_pk_bf16_f32 v60, v76, v68
	v_cvt_pk_bf16_f32 v61, v66, v67
	v_cvt_pk_bf16_f32 v62, v69, v70
	v_cvt_pk_bf16_f32 v63, v77, v63
	global_store_dwordx4 v[64:65], v[60:63], off
	s_waitcnt vmcnt(15)
	s_nop 1
	v_mov_b64_e32 v[60:61], v[208:209]
	v_mov_b64_e32 v[62:63], v[210:211]
	v_lshlrev_b32_e32 v66, 16, v60
	v_and_b32_e32 v60, 0xffff0000, v60
	v_mul_f32_e32 v57, v57, v60
	v_lshlrev_b32_e32 v60, 16, v61
	v_mul_f32_e32 v58, v58, v60
	v_and_b32_e32 v60, 0xffff0000, v61
	v_mul_f32_e32 v59, v59, v60
	v_lshlrev_b32_e32 v60, 16, v62
	v_mul_f32_e32 v60, v52, v60
	v_and_b32_e32 v52, 0xffff0000, v62
	v_mul_f32_e32 v61, v53, v52
	v_lshlrev_b32_e32 v52, 16, v63
	v_mul_f32_e32 v62, v54, v52
	v_and_b32_e32 v52, 0xffff0000, v63
	v_mul_f32_e32 v56, v56, v66
	v_mul_f32_e32 v55, v55, v52
	v_cvt_pk_bf16_f32 v52, v56, v57
	v_cvt_pk_bf16_f32 v53, v58, v59
	v_cvt_pk_bf16_f32 v54, v60, v61
	v_cvt_pk_bf16_f32 v55, v62, v55
	global_store_dwordx4 v[64:65], v[52:55], off offset:256
	s_nop 1
	v_add_u32_e32 v52, 0x90, v134
	v_ashrrev_i32_e32 v53, 31, v52
	v_lshlrev_b64 v[54:55], 13, v[52:53]
	v_lshlrev_b64 v[56:57], 12, v[52:53]
	v_lshl_add_u64 v[52:53], s[2:3], 0, v[54:55]
	v_lshl_add_u64 v[58:59], v[52:53], 0, v[132:133]
	s_waitcnt vmcnt(15)
; __device__ __forceinline__ unsigned cvt_pk_bf16(float lo, float hi) { unsigned r; asm volatile("v_cvt_pk_bf16_f32 %0, %1, %2" : "=v"(r) : "v"(lo), "v"(hi)); return r; }
; #define PG8_SYNC() do { asm volatile("s_waitcnt vmcnt(0) lgkmcnt(0)" ::: "memory"); __builtin_amdgcn_s_barrier(); asm volatile("" ::: "memory"); } while (0)
; __device__ __forceinline__ float bflo(unsigned w) { return __uint_as_float(w << 16); }
; __device__ __forceinline__ float bfhi(unsigned w) { return __uint_as_float(w & 0xffff0000u); }
; template <class Epi, class Sched>
; __device__ __forceinline__ void gemm_simple(PG8_LAS unsigned char* lds, const Gemm g, const Sched& S, const Epi& E, int wave_s) {
;     ...
;         cur = nxt; cA = nA; cB = nB; ++ui;
;     }
;     PG8_SYNC();
;     __device__ __forceinline__ void operator()(const f32x4 (&acc)[2][2][4][2], const Unit& u, int wr, int wc, int fr, int fq, const LAS float*) const {
;     ...
;             for (int m = 0; m < 4; ++m) { const size_t row = (size_t)(row0 + ai * 128 + m * 16);
; #pragma unroll
;                 for (int bj = 0; bj < 2; ++bj) { const int col = col0 + bj * 128;
;                     const u32x4 g = *(const u32x4*)(G + row * NGATE + MODE * DM + col);
;                     f32x4 v0 = acc[ai][bj][m][0], v1 = acc[ai][bj][m][1];
;                     v0[0] *= bflo(g.x); v0[1] *= bfhi(g.x); v0[2] *= bflo(g.y); v0[3] *= bfhi(g.y); v1[0] *= bflo(g.z); v1[1] *= bfhi(g.z); v1[2] *= bflo(g.w); v1[3] *= bfhi(g.w);
;                     bf16_t* tp = T + row * DM + col;
;                     if (MODE == 1) { const u32x4 t = *(const u32x4*)tp;
;                         v0[0] += bflo(t.x); v0[1] += bfhi(t.x); v0[2] += bflo(t.y); v0[3] += bfhi(t.y); v1[0] += bflo(t.z); v1[1] += bfhi(t.z); v1[2] += bflo(t.w); v1[3] += bfhi(t.w); }
;                     u32x4 w; w.x = cvt_pk_bf16(v0[0], v0[1]); w.y = cvt_pk_bf16(v0[2], v0[3]); w.z = cvt_pk_bf16(v1[0], v1[1]); w.w = cvt_pk_bf16(v1[2], v1[3]);
;                     *(u32x4*)tp = w; } }
	s_nop 1
	v_mov_b64_e32 v[52:53], v[212:213]
	v_mov_b64_e32 v[54:55], v[214:215]
	v_lshlrev_b32_e32 v60, 16, v52
	v_mul_f32_e32 v60, v48, v60
	v_and_b32_e32 v48, 0xffff0000, v52
	v_mul_f32_e32 v52, v49, v48
	v_lshlrev_b32_e32 v48, 16, v53
	v_mul_f32_e32 v50, v50, v48
	v_and_b32_e32 v48, 0xffff0000, v53
	v_mul_f32_e32 v51, v51, v48
	v_lshlrev_b32_e32 v48, 16, v54
	v_mul_f32_e32 v53, v44, v48
	v_and_b32_e32 v44, 0xffff0000, v54
	v_mul_f32_e32 v54, v45, v44
	v_lshlrev_b32_e32 v44, 16, v55
	v_mul_f32_e32 v61, v46, v44
	v_and_b32_e32 v44, 0xffff0000, v55
	v_mul_f32_e32 v47, v47, v44
	v_lshl_add_u64 v[44:45], s[12:13], 0, v[56:57]
	v_lshl_add_u64 v[48:49], v[44:45], 0, v[132:133]
	v_cvt_pk_bf16_f32 v44, v60, v52
	v_cvt_pk_bf16_f32 v45, v50, v51
	v_cvt_pk_bf16_f32 v46, v53, v54
	v_cvt_pk_bf16_f32 v47, v61, v47
	global_store_dwordx4 v[48:49], v[44:47], off
	s_waitcnt vmcnt(15)
	s_nop 1
	v_mov_b64_e32 v[44:45], v[216:217]
	v_mov_b64_e32 v[46:47], v[218:219]
	v_lshlrev_b32_e32 v50, 16, v44
	v_and_b32_e32 v44, 0xffff0000, v44
	v_mul_f32_e32 v41, v41, v44
	v_lshlrev_b32_e32 v44, 16, v45
	v_mul_f32_e32 v42, v42, v44
	v_and_b32_e32 v44, 0xffff0000, v45
	v_mul_f32_e32 v43, v43, v44
	v_lshlrev_b32_e32 v44, 16, v46
	v_mul_f32_e32 v44, v36, v44
	v_and_b32_e32 v36, 0xffff0000, v46
	v_mul_f32_e32 v45, v37, v36
	v_lshlrev_b32_e32 v36, 16, v47
	v_mul_f32_e32 v46, v38, v36
	v_and_b32_e32 v36, 0xffff0000, v47
	v_mul_f32_e32 v40, v40, v50
	v_mul_f32_e32 v39, v39, v36
	v_cvt_pk_bf16_f32 v36, v40, v41
	v_cvt_pk_bf16_f32 v37, v42, v43
	v_cvt_pk_bf16_f32 v38, v44, v45
	v_cvt_pk_bf16_f32 v39, v46, v39
	global_store_dwordx4 v[48:49], v[36:39], off offset:256
	s_nop 1
	v_add_u32_e32 v36, 0xa0, v134
	v_ashrrev_i32_e32 v37, 31, v36
	v_lshlrev_b64 v[38:39], 13, v[36:37]
	v_lshlrev_b64 v[40:41], 12, v[36:37]
	v_lshl_add_u64 v[36:37], s[2:3], 0, v[38:39]
	v_lshl_add_u64 v[42:43], v[36:37], 0, v[132:133]
	s_waitcnt vmcnt(15)
	s_nop 1
	v_mov_b64_e32 v[36:37], v[220:221]
	v_mov_b64_e32 v[38:39], v[222:223]
	v_lshlrev_b32_e32 v44, 16, v36
	v_mul_f32_e32 v44, v32, v44
	v_and_b32_e32 v32, 0xffff0000, v36
	v_mul_f32_e32 v36, v33, v32
	v_lshlrev_b32_e32 v32, 16, v37
	v_mul_f32_e32 v34, v34, v32
	v_and_b32_e32 v32, 0xffff0000, v37
	v_mul_f32_e32 v35, v35, v32
	v_lshlrev_b32_e32 v32, 16, v38
	v_mul_f32_e32 v37, v28, v32
	v_and_b32_e32 v28, 0xffff0000, v38
	v_mul_f32_e32 v38, v29, v28
	v_lshlrev_b32_e32 v28, 16, v39
	v_mul_f32_e32 v45, v30, v28
	v_and_b32_e32 v28, 0xffff0000, v39
	v_mul_f32_e32 v31, v31, v28
	v_lshl_add_u64 v[28:29], s[12:13], 0, v[40:41]
	v_lshl_add_u64 v[32:33], v[28:29], 0, v[132:133]
	v_cvt_pk_bf16_f32 v28, v44, v36
	v_cvt_pk_bf16_f32 v29, v34, v35
	v_cvt_pk_bf16_f32 v30, v37, v38
	v_cvt_pk_bf16_f32 v31, v45, v31
	global_store_dwordx4 v[32:33], v[28:31], off
	s_waitcnt vmcnt(15)
	s_nop 1
	v_mov_b64_e32 v[28:29], v[224:225]
	v_mov_b64_e32 v[30:31], v[226:227]
	v_lshlrev_b32_e32 v34, 16, v28
	v_and_b32_e32 v28, 0xffff0000, v28
	v_mul_f32_e32 v25, v25, v28
	v_lshlrev_b32_e32 v28, 16, v29
	v_mul_f32_e32 v26, v26, v28
	v_and_b32_e32 v28, 0xffff0000, v29
	v_mul_f32_e32 v27, v27, v28
	v_lshlrev_b32_e32 v28, 16, v30
	v_mul_f32_e32 v28, v20, v28
	v_and_b32_e32 v20, 0xffff0000, v30
	v_mul_f32_e32 v29, v21, v20
	v_lshlrev_b32_e32 v20, 16, v31
	v_mul_f32_e32 v30, v22, v20
	v_and_b32_e32 v20, 0xffff0000, v31
	v_mul_f32_e32 v24, v24, v34
	v_mul_f32_e32 v23, v23, v20
	v_cvt_pk_bf16_f32 v20, v24, v25
	v_cvt_pk_bf16_f32 v21, v26, v27
	v_cvt_pk_bf16_f32 v22, v28, v29
	v_cvt_pk_bf16_f32 v23, v30, v23
	global_store_dwordx4 v[32:33], v[20:23], off offset:256
	s_nop 1
	v_add_u32_e32 v20, 0xb0, v134
	v_ashrrev_i32_e32 v21, 31, v20
	v_lshlrev_b64 v[22:23], 13, v[20:21]
	v_lshlrev_b64 v[24:25], 12, v[20:21]
	v_lshl_add_u64 v[20:21], s[2:3], 0, v[22:23]
	v_lshl_add_u64 v[26:27], v[20:21], 0, v[132:133]
	s_waitcnt vmcnt(15)
	s_nop 1
	v_mov_b64_e32 v[20:21], v[228:229]
	v_mov_b64_e32 v[22:23], v[230:231]
	v_lshlrev_b32_e32 v28, 16, v20
	v_mul_f32_e32 v28, v16, v28
	v_and_b32_e32 v16, 0xffff0000, v20
	v_mul_f32_e32 v20, v17, v16
	v_lshlrev_b32_e32 v16, 16, v21
	v_mul_f32_e32 v18, v18, v16
	v_and_b32_e32 v16, 0xffff0000, v21
	v_mul_f32_e32 v19, v19, v16
	v_lshlrev_b32_e32 v16, 16, v22
	v_mul_f32_e32 v21, v12, v16
	v_and_b32_e32 v12, 0xffff0000, v22
	v_mul_f32_e32 v22, v13, v12
	v_lshlrev_b32_e32 v12, 16, v23
	v_mul_f32_e32 v29, v14, v12
	v_and_b32_e32 v12, 0xffff0000, v23
	v_mul_f32_e32 v15, v15, v12
	v_lshl_add_u64 v[12:13], s[12:13], 0, v[24:25]
	v_lshl_add_u64 v[16:17], v[12:13], 0, v[132:133]
	v_cvt_pk_bf16_f32 v12, v28, v20
	v_cvt_pk_bf16_f32 v13, v18, v19
	v_cvt_pk_bf16_f32 v14, v21, v22
	v_cvt_pk_bf16_f32 v15, v29, v15
	global_store_dwordx4 v[16:17], v[12:15], off
	s_waitcnt vmcnt(15)
	s_nop 1
	v_mov_b64_e32 v[12:13], v[232:233]
	v_mov_b64_e32 v[14:15], v[234:235]
	v_lshlrev_b32_e32 v18, 16, v12
	v_and_b32_e32 v12, 0xffff0000, v12
	v_mul_f32_e32 v5, v5, v12
	v_lshlrev_b32_e32 v12, 16, v13
	v_mul_f32_e32 v6, v6, v12
	v_and_b32_e32 v12, 0xffff0000, v13
	v_mul_f32_e32 v7, v7, v12
	v_lshlrev_b32_e32 v12, 16, v14
	v_mul_f32_e32 v8, v8, v12
	v_and_b32_e32 v12, 0xffff0000, v14
	v_mul_f32_e32 v9, v9, v12
	v_lshlrev_b32_e32 v12, 16, v15
	v_mul_f32_e32 v4, v4, v18
	v_mul_f32_e32 v10, v10, v12
	v_and_b32_e32 v12, 0xffff0000, v15
	v_mul_f32_e32 v11, v11, v12
	v_cvt_pk_bf16_f32 v4, v4, v5
	v_cvt_pk_bf16_f32 v5, v6, v7
	v_cvt_pk_bf16_f32 v6, v8, v9
	v_cvt_pk_bf16_f32 v7, v10, v11
	global_store_dwordx4 v[16:17], v[4:7], off offset:256
	s_cbranch_vccnz .LBB0_186
	s_waitcnt vmcnt(0) lgkmcnt(0)
	s_barrier

; template <class Epi, class Sched>
; __device__ __forceinline__ void gemm_simple(PG8_LAS unsigned char* lds, const Gemm g, const Sched& S, const Epi& E, int wave_s) {
;     ...
;         for (; t < nt; t += 2) {
;             const bool last = (t == nt - 2);
;             PG8_TILE(0, cA + (size_t)(t + 1) * kstep, cB + (size_t)(t + 1) * kstep, true);
.LBB0_221:
	s_waitcnt vmcnt(2) lgkmcnt(0)
	s_barrier
	ds_read_b128 v[146:149], v132
	ds_read_b128 v[178:181], v156
	ds_read_b128 v[170:173], v132 offset:2048
	ds_read_b128 v[186:189], v156 offset:2048
	s_add_u32 s60, s10, s59
	s_addc_u32 s61, s11, 0
	s_add_u32 s24, s60, 0x80
	s_addc_u32 s25, s61, 0
	s_mov_b32 m0, s44
	s_nop 0
	global_load_lds_dwordx4 v140, s[24:25]
	s_mov_b32 m0, s48
	s_nop 0
	global_load_lds_dwordx4 v153, s[24:25]
	s_waitcnt lgkmcnt(2)
	v_mfma_f32_16x16x32_bf16 v[128:131], v[146:149], v[178:181], v[128:131]
	ds_read_b128 v[194:197], v156 offset:4096
	s_waitcnt lgkmcnt(2)
	v_mfma_f32_16x16x32_bf16 v[124:127], v[170:173], v[178:181], v[124:127]
	ds_read_b128 v[202:205], v156 offset:6144
	s_waitcnt lgkmcnt(2)
	v_mfma_f32_16x16x32_bf16 v[112:115], v[146:149], v[186:189], v[112:115]
	v_mfma_f32_16x16x32_bf16 v[108:111], v[170:173], v[186:189], v[108:111]
	ds_read_b128 v[158:161], v132 offset:1024
	ds_read_b128 v[182:185], v156 offset:1024
	s_waitcnt lgkmcnt(3)
	v_mfma_f32_16x16x32_bf16 v[96:99], v[146:149], v[194:197], v[96:99]
	ds_read_b128 v[174:177], v132 offset:3072
	v_mfma_f32_16x16x32_bf16 v[92:95], v[170:173], v[194:197], v[92:95]
	ds_read_b128 v[190:193], v156 offset:3072
	s_waitcnt lgkmcnt(4)
	v_mfma_f32_16x16x32_bf16 v[80:83], v[146:149], v[202:205], v[80:83]
	v_mfma_f32_16x16x32_bf16 v[76:79], v[170:173], v[202:205], v[76:79]
	ds_read_b128 v[198:201], v156 offset:5120
	s_waitcnt lgkmcnt(3)
	v_mfma_f32_16x16x32_bf16 v[128:131], v[158:161], v[182:185], v[128:131]
	s_waitcnt lgkmcnt(2)
	v_mfma_f32_16x16x32_bf16 v[124:127], v[174:177], v[182:185], v[124:127]
	ds_read_b128 v[206:209], v156 offset:7168
	s_waitcnt lgkmcnt(2)
	v_mfma_f32_16x16x32_bf16 v[112:115], v[158:161], v[190:193], v[112:115]
	v_mfma_f32_16x16x32_bf16 v[108:111], v[174:177], v[190:193], v[108:111]
	ds_read_b128 v[210:213], v133
	s_waitcnt lgkmcnt(2)
	v_mfma_f32_16x16x32_bf16 v[96:99], v[158:161], v[198:201], v[96:99]
	ds_read_b128 v[218:221], v133 offset:2048
	v_mfma_f32_16x16x32_bf16 v[92:95], v[174:177], v[198:201], v[92:95]
	s_waitcnt lgkmcnt(2)
	v_mfma_f32_16x16x32_bf16 v[80:83], v[158:161], v[206:209], v[80:83]
	v_mfma_f32_16x16x32_bf16 v[76:79], v[174:177], v[206:209], v[76:79]
	s_add_u32 s62, s20, s59
	s_addc_u32 s63, s21, 0
	s_add_u32 s24, s62, 0x80
	s_addc_u32 s25, s63, 0
	s_mov_b32 m0, s45
	s_nop 0
	global_load_lds_dwordx4 v139, s[24:25]
	s_mov_b32 m0, s49
	s_nop 0
	global_load_lds_dwordx4 v152, s[24:25]
	s_waitcnt lgkmcnt(1)
	v_mfma_f32_16x16x32_bf16 v[120:123], v[210:213], v[178:181], v[120:123]
	s_waitcnt lgkmcnt(0)
	v_mfma_f32_16x16x32_bf16 v[116:119], v[218:221], v[178:181], v[116:119]
	v_mfma_f32_16x16x32_bf16 v[104:107], v[210:213], v[186:189], v[104:107]
	v_mfma_f32_16x16x32_bf16 v[100:103], v[218:221], v[186:189], v[100:103]
	ds_read_b128 v[214:217], v133 offset:1024
	v_mfma_f32_16x16x32_bf16 v[88:91], v[210:213], v[194:197], v[88:91]
	ds_read_b128 v[222:225], v133 offset:3072
	v_mfma_f32_16x16x32_bf16 v[84:87], v[218:221], v[194:197], v[84:87]
	v_mfma_f32_16x16x32_bf16 v[72:75], v[210:213], v[202:205], v[72:75]
	v_mfma_f32_16x16x32_bf16 v[68:71], v[218:221], v[202:205], v[68:71]
	s_waitcnt lgkmcnt(1)
	v_mfma_f32_16x16x32_bf16 v[120:123], v[214:217], v[182:185], v[120:123]
	s_waitcnt lgkmcnt(0)
	v_mfma_f32_16x16x32_bf16 v[116:119], v[222:225], v[182:185], v[116:119]
	v_mfma_f32_16x16x32_bf16 v[104:107], v[214:217], v[190:193], v[104:107]
	v_mfma_f32_16x16x32_bf16 v[100:103], v[222:225], v[190:193], v[100:103]
	v_mfma_f32_16x16x32_bf16 v[88:91], v[214:217], v[198:201], v[88:91]
	v_mfma_f32_16x16x32_bf16 v[84:87], v[222:225], v[198:201], v[84:87]
	v_mfma_f32_16x16x32_bf16 v[72:75], v[214:217], v[206:209], v[72:75]
	v_mfma_f32_16x16x32_bf16 v[68:71], v[222:225], v[206:209], v[68:71]
	s_waitcnt vmcnt(4) lgkmcnt(0)
	s_barrier
	ds_read_b128 v[178:181], v156 offset:16384
	ds_read_b128 v[186:189], v156 offset:18432
	s_add_u32 s24, s60, 0x80080
	s_addc_u32 s25, s61, 0
	s_mov_b32 m0, s46
	s_nop 0
	global_load_lds_dwordx4 v140, s[24:25]
	s_mov_b32 m0, s50
	s_nop 0
	global_load_lds_dwordx4 v153, s[24:25]
	s_waitcnt lgkmcnt(1)
	v_mfma_f32_16x16x32_bf16 v[64:67], v[146:149], v[178:181], v[64:67]
	ds_read_b128 v[194:197], v156 offset:20480
	v_mfma_f32_16x16x32_bf16 v[60:63], v[170:173], v[178:181], v[60:63]
	ds_read_b128 v[202:205], v156 offset:22528
	s_waitcnt lgkmcnt(2)
	v_mfma_f32_16x16x32_bf16 v[48:51], v[146:149], v[186:189], v[48:51]
	v_mfma_f32_16x16x32_bf16 v[44:47], v[170:173], v[186:189], v[44:47]
	ds_read_b128 v[182:185], v156 offset:17408
	s_waitcnt lgkmcnt(2)
	v_mfma_f32_16x16x32_bf16 v[32:35], v[146:149], v[194:197], v[32:35]
	v_mfma_f32_16x16x32_bf16 v[28:31], v[170:173], v[194:197], v[28:31]
	ds_read_b128 v[190:193], v156 offset:19456
	s_waitcnt lgkmcnt(2)
	v_mfma_f32_16x16x32_bf16 v[16:19], v[146:149], v[202:205], v[16:19]
	v_mfma_f32_16x16x32_bf16 v[12:15], v[170:173], v[202:205], v[12:15]
	ds_read_b128 v[198:201], v156 offset:21504
	s_waitcnt lgkmcnt(2)
	v_mfma_f32_16x16x32_bf16 v[64:67], v[158:161], v[182:185], v[64:67]
	v_mfma_f32_16x16x32_bf16 v[60:63], v[174:177], v[182:185], v[60:63]
	ds_read_b128 v[206:209], v156 offset:23552
	s_waitcnt lgkmcnt(2)
	v_mfma_f32_16x16x32_bf16 v[48:51], v[158:161], v[190:193], v[48:51]
	v_mfma_f32_16x16x32_bf16 v[44:47], v[174:177], v[190:193], v[44:47]
	s_waitcnt lgkmcnt(1)
	v_mfma_f32_16x16x32_bf16 v[32:35], v[158:161], v[198:201], v[32:35]
	v_mfma_f32_16x16x32_bf16 v[28:31], v[174:177], v[198:201], v[28:31]
	s_waitcnt lgkmcnt(0)
	v_mfma_f32_16x16x32_bf16 v[16:19], v[158:161], v[206:209], v[16:19]
	v_mfma_f32_16x16x32_bf16 v[12:15], v[174:177], v[206:209], v[12:15]
	s_add_u32 s24, s62, 0x80080
	s_addc_u32 s25, s63, 0
	s_mov_b32 m0, s47
	s_nop 0
	global_load_lds_dwordx4 v139, s[24:25]
	s_mov_b32 m0, s51
	s_nop 0
	global_load_lds_dwordx4 v152, s[24:25]
	v_mfma_f32_16x16x32_bf16 v[56:59], v[210:213], v[178:181], v[56:59]
	s_add_u32 s24, s62, 0x100
	s_addc_u32 s25, s63, 0
	s_add_u32 s60, s60, 0x100
	v_mfma_f32_16x16x32_bf16 v[52:55], v[218:221], v[178:181], v[52:55]
	s_addc_u32 s61, s61, 0
	v_mfma_f32_16x16x32_bf16 v[40:43], v[210:213], v[186:189], v[40:43]
	v_mfma_f32_16x16x32_bf16 v[36:39], v[218:221], v[186:189], v[36:39]
	v_mfma_f32_16x16x32_bf16 v[24:27], v[210:213], v[194:197], v[24:27]
	v_mfma_f32_16x16x32_bf16 v[20:23], v[218:221], v[194:197], v[20:23]
	v_mfma_f32_16x16x32_bf16 v[4:7], v[210:213], v[202:205], v[4:7]
	v_mfma_f32_16x16x32_bf16 v[8:11], v[218:221], v[202:205], v[8:11]
	v_mfma_f32_16x16x32_bf16 v[56:59], v[214:217], v[182:185], v[56:59]
	v_mfma_f32_16x16x32_bf16 v[52:55], v[222:225], v[182:185], v[52:55]
	v_mfma_f32_16x16x32_bf16 v[40:43], v[214:217], v[190:193], v[40:43]
	v_mfma_f32_16x16x32_bf16 v[36:39], v[222:225], v[190:193], v[36:39]
	v_mfma_f32_16x16x32_bf16 v[24:27], v[214:217], v[198:201], v[24:27]
	v_mfma_f32_16x16x32_bf16 v[20:23], v[222:225], v[198:201], v[20:23]
	v_mfma_f32_16x16x32_bf16 v[4:7], v[214:217], v[206:209], v[4:7]
	v_mfma_f32_16x16x32_bf16 v[8:11], v[222:225], v[206:209], v[8:11]
	s_waitcnt vmcnt(2) lgkmcnt(0)
	s_barrier
; template <class Epi, class Sched>
; __device__ __forceinline__ void gemm_simple(PG8_LAS unsigned char* lds, const Gemm g, const Sched& S, const Epi& E, int wave_s) {
;     ...
;             const char* a2 = last ? nA : cA + (size_t)(t + 2) * kstep; const char* b2 = last ? nB : cB + (size_t)(t + 2) * kstep;
;             PG8_TILE(1, a2, b2, (!last || has_next));
	ds_read_b128 v[146:149], v134
	ds_read_b128 v[178:181], v156 offset:32768
	ds_read_b128 v[170:173], v134 offset:2048
	ds_read_b128 v[186:189], v156 offset:34816
	s_cmp_eq_u32 s59, s22
	s_cselect_b32 s25, s13, s25
	s_cselect_b32 s24, s56, s24
	s_cselect_b32 s61, s5, s61
	s_cselect_b32 s60, s57, s60
	s_mov_b32 m0, s29
	s_nop 0
	global_load_lds_dwordx4 v140, s[60:61]
	s_mov_b32 m0, s35
	s_nop 0
	global_load_lds_dwordx4 v153, s[60:61]
	s_waitcnt lgkmcnt(2)
	v_mfma_f32_16x16x32_bf16 v[128:131], v[146:149], v[178:181], v[128:131]
	ds_read_b128 v[194:197], v156 offset:36864
	s_waitcnt lgkmcnt(2)
	v_mfma_f32_16x16x32_bf16 v[124:127], v[170:173], v[178:181], v[124:127]
	ds_read_b128 v[202:205], v156 offset:38912
	s_waitcnt lgkmcnt(2)
	v_mfma_f32_16x16x32_bf16 v[112:115], v[146:149], v[186:189], v[112:115]
	v_mfma_f32_16x16x32_bf16 v[108:111], v[170:173], v[186:189], v[108:111]
	ds_read_b128 v[158:161], v134 offset:1024
	ds_read_b128 v[182:185], v156 offset:33792
	s_waitcnt lgkmcnt(3)
	v_mfma_f32_16x16x32_bf16 v[96:99], v[146:149], v[194:197], v[96:99]
	ds_read_b128 v[174:177], v134 offset:3072
	v_mfma_f32_16x16x32_bf16 v[92:95], v[170:173], v[194:197], v[92:95]
	ds_read_b128 v[190:193], v156 offset:35840
	s_waitcnt lgkmcnt(4)
	v_mfma_f32_16x16x32_bf16 v[80:83], v[146:149], v[202:205], v[80:83]
	v_mfma_f32_16x16x32_bf16 v[76:79], v[170:173], v[202:205], v[76:79]
	ds_read_b128 v[198:201], v156 offset:37888
	s_waitcnt lgkmcnt(3)
	v_mfma_f32_16x16x32_bf16 v[128:131], v[158:161], v[182:185], v[128:131]
	s_waitcnt lgkmcnt(2)
	v_mfma_f32_16x16x32_bf16 v[124:127], v[174:177], v[182:185], v[124:127]
	ds_read_b128 v[206:209], v156 offset:39936
	s_waitcnt lgkmcnt(2)
	v_mfma_f32_16x16x32_bf16 v[112:115], v[158:161], v[190:193], v[112:115]
	v_mfma_f32_16x16x32_bf16 v[108:111], v[174:177], v[190:193], v[108:111]
	ds_read_b128 v[210:213], v135
	s_waitcnt lgkmcnt(2)
	v_mfma_f32_16x16x32_bf16 v[96:99], v[158:161], v[198:201], v[96:99]
	ds_read_b128 v[218:221], v135 offset:2048
	v_mfma_f32_16x16x32_bf16 v[92:95], v[174:177], v[198:201], v[92:95]
	s_waitcnt lgkmcnt(2)
	v_mfma_f32_16x16x32_bf16 v[80:83], v[158:161], v[206:209], v[80:83]
	v_mfma_f32_16x16x32_bf16 v[76:79], v[174:177], v[206:209], v[76:79]
	s_mov_b32 m0, s19
	s_nop 0
	global_load_lds_dwordx4 v139, s[24:25]
	s_mov_b32 m0, s36
	s_nop 0
	global_load_lds_dwordx4 v152, s[24:25]
	s_waitcnt lgkmcnt(1)
	v_mfma_f32_16x16x32_bf16 v[120:123], v[210:213], v[178:181], v[120:123]
	s_waitcnt lgkmcnt(0)
	v_mfma_f32_16x16x32_bf16 v[116:119], v[218:221], v[178:181], v[116:119]
	v_mfma_f32_16x16x32_bf16 v[104:107], v[210:213], v[186:189], v[104:107]
	v_mfma_f32_16x16x32_bf16 v[100:103], v[218:221], v[186:189], v[100:103]
	ds_read_b128 v[214:217], v135 offset:1024
	v_mfma_f32_16x16x32_bf16 v[88:91], v[210:213], v[194:197], v[88:91]
	ds_read_b128 v[222:225], v135 offset:3072
	v_mfma_f32_16x16x32_bf16 v[84:87], v[218:221], v[194:197], v[84:87]
	v_mfma_f32_16x16x32_bf16 v[72:75], v[210:213], v[202:205], v[72:75]
	v_mfma_f32_16x16x32_bf16 v[68:71], v[218:221], v[202:205], v[68:71]
	s_waitcnt lgkmcnt(1)
	v_mfma_f32_16x16x32_bf16 v[120:123], v[214:217], v[182:185], v[120:123]
	s_waitcnt lgkmcnt(0)
	v_mfma_f32_16x16x32_bf16 v[116:119], v[222:225], v[182:185], v[116:119]
	v_mfma_f32_16x16x32_bf16 v[104:107], v[214:217], v[190:193], v[104:107]
	v_mfma_f32_16x16x32_bf16 v[100:103], v[222:225], v[190:193], v[100:103]
	v_mfma_f32_16x16x32_bf16 v[88:91], v[214:217], v[198:201], v[88:91]
	v_mfma_f32_16x16x32_bf16 v[84:87], v[222:225], v[198:201], v[84:87]
	v_mfma_f32_16x16x32_bf16 v[72:75], v[214:217], v[206:209], v[72:75]
	v_mfma_f32_16x16x32_bf16 v[68:71], v[222:225], v[206:209], v[68:71]
	s_waitcnt vmcnt(4) lgkmcnt(0)
	s_barrier
; #define LAS __attribute__((address_space(3)))
; __device__ __forceinline__ void rstd_table(const float* ssq, LAS unsigned char* lds, const Unit& u, int tid, int par) {
;     if (tid < 256) { const f32x4* p = (const f32x4*)(ssq + (size_t)(u.pm * 256 + tid) * 32); f32x4 a = p[0];
; #pragma unroll
;         for (int i = 1; i < 8; ++i) a += p[i];
;         ((LAS float*)(lds + 131072 + par * 1024))[tid] = 1.0f / sqrtf(((a[0] + a[1]) + (a[2] + a[3])) * (1.0f / DM) + 1e-6f); }
	ds_read_b128 v[178:181], v156 offset:49152
	ds_read_b128 v[186:189], v156 offset:51200
	s_add_u32 s60, s60, 0x80000
	s_addc_u32 s61, s61, 0
	s_mov_b32 m0, s37
	s_nop 0
	global_load_lds_dwordx4 v140, s[60:61]
	s_mov_b32 m0, s38
	s_nop 0
	global_load_lds_dwordx4 v153, s[60:61]
	s_waitcnt lgkmcnt(1)
	v_mfma_f32_16x16x32_bf16 v[64:67], v[146:149], v[178:181], v[64:67]
	ds_read_b128 v[194:197], v156 offset:53248
	v_mfma_f32_16x16x32_bf16 v[60:63], v[170:173], v[178:181], v[60:63]
	ds_read_b128 v[202:205], v156 offset:55296
	s_waitcnt lgkmcnt(2)
	v_mfma_f32_16x16x32_bf16 v[48:51], v[146:149], v[186:189], v[48:51]
	v_mfma_f32_16x16x32_bf16 v[44:47], v[170:173], v[186:189], v[44:47]
	ds_read_b128 v[182:185], v156 offset:50176
	s_waitcnt lgkmcnt(2)
	v_mfma_f32_16x16x32_bf16 v[32:35], v[146:149], v[194:197], v[32:35]
	v_mfma_f32_16x16x32_bf16 v[28:31], v[170:173], v[194:197], v[28:31]
	ds_read_b128 v[190:193], v156 offset:52224
	s_waitcnt lgkmcnt(2)
	v_mfma_f32_16x16x32_bf16 v[16:19], v[146:149], v[202:205], v[16:19]
	v_mfma_f32_16x16x32_bf16 v[12:15], v[170:173], v[202:205], v[12:15]
	ds_read_b128 v[198:201], v156 offset:54272
	s_waitcnt lgkmcnt(2)
	v_mfma_f32_16x16x32_bf16 v[64:67], v[158:161], v[182:185], v[64:67]
	v_mfma_f32_16x16x32_bf16 v[60:63], v[174:177], v[182:185], v[60:63]
	ds_read_b128 v[206:209], v156 offset:56320
	s_waitcnt lgkmcnt(2)
	v_mfma_f32_16x16x32_bf16 v[48:51], v[158:161], v[190:193], v[48:51]
	v_mfma_f32_16x16x32_bf16 v[44:47], v[174:177], v[190:193], v[44:47]
	s_waitcnt lgkmcnt(1)
	v_mfma_f32_16x16x32_bf16 v[32:35], v[158:161], v[198:201], v[32:35]
	v_mfma_f32_16x16x32_bf16 v[28:31], v[174:177], v[198:201], v[28:31]
	s_waitcnt lgkmcnt(0)
	v_mfma_f32_16x16x32_bf16 v[16:19], v[158:161], v[206:209], v[16:19]
	v_mfma_f32_16x16x32_bf16 v[12:15], v[174:177], v[206:209], v[12:15]
	s_add_u32 s24, s24, 0x80000
	s_addc_u32 s25, s25, 0
	s_mov_b32 m0, s39
	s_nop 0
	global_load_lds_dwordx4 v139, s[24:25]
	s_mov_b32 m0, s40
	s_nop 0
	global_load_lds_dwordx4 v152, s[24:25]
	v_mfma_f32_16x16x32_bf16 v[56:59], v[210:213], v[178:181], v[56:59]
	s_add_i32 s58, s58, 2
	s_add_u32 s22, s22, 0xffffff00
	s_addc_u32 s23, s23, -1
	v_mfma_f32_16x16x32_bf16 v[52:55], v[218:221], v[178:181], v[52:55]
	s_add_u32 s20, s20, 0x100
	s_addc_u32 s21, s21, 0
	s_add_u32 s10, s10, 0x100
	v_mfma_f32_16x16x32_bf16 v[40:43], v[210:213], v[186:189], v[40:43]
	s_addc_u32 s11, s11, 0
	s_cmp_lt_u32 s58, 30
	v_mfma_f32_16x16x32_bf16 v[36:39], v[218:221], v[186:189], v[36:39]
	v_mfma_f32_16x16x32_bf16 v[24:27], v[210:213], v[194:197], v[24:27]
	v_mfma_f32_16x16x32_bf16 v[20:23], v[218:221], v[194:197], v[20:23]
	v_mfma_f32_16x16x32_bf16 v[4:7], v[210:213], v[202:205], v[4:7]
	v_mfma_f32_16x16x32_bf16 v[8:11], v[218:221], v[202:205], v[8:11]
	v_mfma_f32_16x16x32_bf16 v[56:59], v[214:217], v[182:185], v[56:59]
	v_mfma_f32_16x16x32_bf16 v[52:55], v[222:225], v[182:185], v[52:55]
	v_mfma_f32_16x16x32_bf16 v[40:43], v[214:217], v[190:193], v[40:43]
	v_mfma_f32_16x16x32_bf16 v[36:39], v[222:225], v[190:193], v[36:39]
	v_mfma_f32_16x16x32_bf16 v[24:27], v[214:217], v[198:201], v[24:27]
	v_mfma_f32_16x16x32_bf16 v[20:23], v[222:225], v[198:201], v[20:23]
	v_mfma_f32_16x16x32_bf16 v[4:7], v[214:217], v[206:209], v[4:7]
	v_mfma_f32_16x16x32_bf16 v[8:11], v[222:225], v[206:209], v[8:11]
	s_cbranch_scc1 .LBB0_221
	s_nor_b64 s[10:11], s[6:7], s[8:9]
	s_and_saveexec_b64 s[20:21], s[10:11]
	s_cbranch_execz .LBB0_211
	v_lshl_add_u32 v132, s12, 8, v138
	v_ashrrev_i32_e32 v133, 31, v132
	v_readlane_b32 s10, v255, 2
	v_lshlrev_b64 v[132:133], 7, v[132:133]
	v_readlane_b32 s11, v255, 3
	s_lshl_b32 s5, s53, 10
	s_and_b32 s5, s5, 0x400
	v_lshl_add_u64 v[136:137], s[10:11], 0, v[132:133]
	global_load_dwordx4 v[132:135], v[136:137], off offset:48
	global_load_dwordx4 v[146:149], v[136:137], off offset:32
	global_load_dwordx4 v[158:161], v[136:137], off
	global_load_dwordx4 v[170:173], v[136:137], off offset:16
	s_waitcnt vmcnt(0)
	v_pk_add_f32 v[142:143], v[160:161], v[172:173]
	v_pk_add_f32 v[144:145], v[158:159], v[170:171]
	v_pk_add_f32 v[142:143], v[142:143], v[148:149]
	v_pk_add_f32 v[144:145], v[144:145], v[146:147]
	v_pk_add_f32 v[142:143], v[142:143], v[134:135]
	v_pk_add_f32 v[144:145], v[144:145], v[132:133]
	global_load_dwordx4 v[132:135], v[136:137], off offset:112
	global_load_dwordx4 v[146:149], v[136:137], off offset:96
	global_load_dwordx4 v[158:161], v[136:137], off offset:80
	global_load_dwordx4 v[170:173], v[136:137], off offset:64
	s_waitcnt vmcnt(0)
	v_pk_add_f32 v[136:137], v[142:143], v[172:173]
	v_pk_add_f32 v[142:143], v[144:145], v[170:171]
	v_pk_add_f32 v[136:137], v[136:137], v[160:161]
	v_pk_add_f32 v[142:143], v[142:143], v[158:159]
	v_pk_add_f32 v[136:137], v[136:137], v[148:149]
	v_pk_add_f32 v[142:143], v[142:143], v[146:147]
	v_pk_add_f32 v[134:135], v[136:137], v[134:135]
	v_pk_add_f32 v[132:133], v[142:143], v[132:133]
	s_nop 0
	v_pk_mov_b32 v[136:137], v[132:133], v[134:135] op_sel:[1,0]
	v_mov_b32_e32 v133, v135
	v_pk_add_f32 v[132:133], v[136:137], v[132:133]
	s_nop 0
	v_add_f32_e32 v132, v132, v133
	v_fmamk_f32 v132, v132, 0x3a000000, v164
	v_cmp_gt_f32_e32 vcc, s69, v132
	v_mul_f32_e32 v133, 0x4f800000, v132
	s_nop 0
	v_cndmask_b32_e32 v132, v132, v133, vcc
	v_sqrt_f32_e32 v133, v132
	s_nop 0
	v_add_u32_e32 v134, -1, v133
	v_fma_f32 v135, -v134, v133, v132
	v_cmp_ge_f32_e64 s[10:11], 0, v135
	v_add_u32_e32 v135, 1, v133
	s_nop 0
	v_cndmask_b32_e64 v134, v133, v134, s[10:11]
	v_fma_f32 v133, -v135, v133, v132
	v_cmp_lt_f32_e64 s[10:11], 0, v133
	s_nop 1
	v_cndmask_b32_e64 v133, v134, v135, s[10:11]
	v_mul_f32_e32 v134, 0x37800000, v133
	v_cndmask_b32_e32 v133, v133, v134, vcc
	v_cmp_class_f32_e32 vcc, v132, v165
	s_nop 1
	v_cndmask_b32_e32 v132, v133, v132, vcc
	v_div_scale_f32 v133, s[10:11], v132, v132, 1.0
	v_rcp_f32_e32 v134, v133
	s_nop 0
	v_fma_f32 v135, -v133, v134, 1.0
	v_fmac_f32_e32 v134, v135, v134
	v_div_scale_f32 v135, vcc, 1.0, v132, 1.0
	v_mul_f32_e32 v136, v135, v134
	v_fma_f32 v137, -v133, v136, v135
	v_fmac_f32_e32 v136, v137, v134
	v_fma_f32 v133, -v133, v136, v135
	v_div_fmas_f32 v133, v133, v134, v136
	v_div_fixup_f32 v132, v133, v132, 1.0
	v_add_u32_e32 v133, s5, v154
	ds_write_b32 v133, v132
	s_branch .LBB0_211

; template <class Epi, class Sched>
; __device__ __forceinline__ void gemm_simple(PG8_LAS unsigned char* lds, const Gemm g, const Sched& S, const Epi& E, int wave_s) {
;     ...
;         for (; t < nt; t += 2) {
;             const bool last = (t == nt - 2);
;             PG8_TILE(0, cA + (size_t)(t + 1) * kstep, cB + (size_t)(t + 1) * kstep, true);
.LBB0_275:
	s_waitcnt vmcnt(2) lgkmcnt(0)
	s_barrier
	ds_read_b128 v[136:139], v132
	ds_read_b128 v[156:159], v174
	ds_read_b128 v[146:149], v132 offset:2048
	ds_read_b128 v[180:183], v174 offset:2048
	s_add_u32 s63, s10, s62
	s_addc_u32 s64, s11, 0
	s_add_u32 s28, s63, 0x80
	s_addc_u32 s29, s64, 0
	s_mov_b32 m0, s49
	s_nop 0
	global_load_lds_dwordx4 v163, s[28:29]
	s_mov_b32 m0, s53
	s_nop 0
	global_load_lds_dwordx4 v171, s[28:29]
	s_waitcnt lgkmcnt(2)
	v_mfma_f32_16x16x32_bf16 v[128:131], v[136:139], v[156:159], v[128:131]
	ds_read_b128 v[188:191], v174 offset:4096
	s_waitcnt lgkmcnt(2)
	v_mfma_f32_16x16x32_bf16 v[124:127], v[146:149], v[156:159], v[124:127]
	ds_read_b128 v[196:199], v174 offset:6144
	s_waitcnt lgkmcnt(2)
	v_mfma_f32_16x16x32_bf16 v[112:115], v[136:139], v[180:183], v[112:115]
	v_mfma_f32_16x16x32_bf16 v[108:111], v[146:149], v[180:183], v[108:111]
	ds_read_b128 v[142:145], v132 offset:1024
	ds_read_b128 v[176:179], v174 offset:1024
	s_waitcnt lgkmcnt(3)
	v_mfma_f32_16x16x32_bf16 v[96:99], v[136:139], v[188:191], v[96:99]
	ds_read_b128 v[152:155], v132 offset:3072
	v_mfma_f32_16x16x32_bf16 v[92:95], v[146:149], v[188:191], v[92:95]
	ds_read_b128 v[184:187], v174 offset:3072
	s_waitcnt lgkmcnt(4)
	v_mfma_f32_16x16x32_bf16 v[80:83], v[136:139], v[196:199], v[80:83]
	v_mfma_f32_16x16x32_bf16 v[76:79], v[146:149], v[196:199], v[76:79]
	ds_read_b128 v[192:195], v174 offset:5120
	s_waitcnt lgkmcnt(3)
	v_mfma_f32_16x16x32_bf16 v[128:131], v[142:145], v[176:179], v[128:131]
	s_waitcnt lgkmcnt(2)
	v_mfma_f32_16x16x32_bf16 v[124:127], v[152:155], v[176:179], v[124:127]
	ds_read_b128 v[200:203], v174 offset:7168
	s_waitcnt lgkmcnt(2)
	v_mfma_f32_16x16x32_bf16 v[112:115], v[142:145], v[184:187], v[112:115]
	v_mfma_f32_16x16x32_bf16 v[108:111], v[152:155], v[184:187], v[108:111]
	ds_read_b128 v[204:207], v133
	s_waitcnt lgkmcnt(2)
	v_mfma_f32_16x16x32_bf16 v[96:99], v[142:145], v[192:195], v[96:99]
	ds_read_b128 v[212:215], v133 offset:2048
	v_mfma_f32_16x16x32_bf16 v[92:95], v[152:155], v[192:195], v[92:95]
	s_waitcnt lgkmcnt(2)
	v_mfma_f32_16x16x32_bf16 v[80:83], v[142:145], v[200:203], v[80:83]
	v_mfma_f32_16x16x32_bf16 v[76:79], v[152:155], v[200:203], v[76:79]
	s_add_u32 s65, s24, s62
	s_addc_u32 s66, s25, 0
	s_add_u32 s28, s65, 0x80
	s_addc_u32 s29, s66, 0
	s_mov_b32 m0, s50
	s_nop 0
	global_load_lds_dwordx4 v162, s[28:29]
	s_mov_b32 m0, s54
	s_nop 0
	global_load_lds_dwordx4 v170, s[28:29]
	s_waitcnt lgkmcnt(1)
	v_mfma_f32_16x16x32_bf16 v[120:123], v[204:207], v[156:159], v[120:123]
	s_waitcnt lgkmcnt(0)
	v_mfma_f32_16x16x32_bf16 v[116:119], v[212:215], v[156:159], v[116:119]
	v_mfma_f32_16x16x32_bf16 v[104:107], v[204:207], v[180:183], v[104:107]
	v_mfma_f32_16x16x32_bf16 v[100:103], v[212:215], v[180:183], v[100:103]
	ds_read_b128 v[208:211], v133 offset:1024
	v_mfma_f32_16x16x32_bf16 v[88:91], v[204:207], v[188:191], v[88:91]
	ds_read_b128 v[216:219], v133 offset:3072
	v_mfma_f32_16x16x32_bf16 v[84:87], v[212:215], v[188:191], v[84:87]
	v_mfma_f32_16x16x32_bf16 v[72:75], v[204:207], v[196:199], v[72:75]
	v_mfma_f32_16x16x32_bf16 v[68:71], v[212:215], v[196:199], v[68:71]
	s_waitcnt lgkmcnt(1)
	v_mfma_f32_16x16x32_bf16 v[120:123], v[208:211], v[176:179], v[120:123]
	s_waitcnt lgkmcnt(0)
	v_mfma_f32_16x16x32_bf16 v[116:119], v[216:219], v[176:179], v[116:119]
	v_mfma_f32_16x16x32_bf16 v[104:107], v[208:211], v[184:187], v[104:107]
	v_mfma_f32_16x16x32_bf16 v[100:103], v[216:219], v[184:187], v[100:103]
	v_mfma_f32_16x16x32_bf16 v[88:91], v[208:211], v[192:195], v[88:91]
	v_mfma_f32_16x16x32_bf16 v[84:87], v[216:219], v[192:195], v[84:87]
	v_mfma_f32_16x16x32_bf16 v[72:75], v[208:211], v[200:203], v[72:75]
	v_mfma_f32_16x16x32_bf16 v[68:71], v[216:219], v[200:203], v[68:71]
	s_waitcnt vmcnt(4) lgkmcnt(0)
	s_barrier
	ds_read_b128 v[156:159], v174 offset:16384
	ds_read_b128 v[180:183], v174 offset:18432
	s_add_u32 s28, s63, 0x80080
	s_addc_u32 s29, s64, 0
	s_mov_b32 m0, s51
	s_nop 0
	global_load_lds_dwordx4 v163, s[28:29]
	s_mov_b32 m0, s55
	s_nop 0
	global_load_lds_dwordx4 v171, s[28:29]
	s_waitcnt lgkmcnt(1)
	v_mfma_f32_16x16x32_bf16 v[64:67], v[136:139], v[156:159], v[64:67]
	ds_read_b128 v[188:191], v174 offset:20480
	v_mfma_f32_16x16x32_bf16 v[60:63], v[146:149], v[156:159], v[60:63]
	ds_read_b128 v[196:199], v174 offset:22528
	s_waitcnt lgkmcnt(2)
	v_mfma_f32_16x16x32_bf16 v[48:51], v[136:139], v[180:183], v[48:51]
	v_mfma_f32_16x16x32_bf16 v[44:47], v[146:149], v[180:183], v[44:47]
	ds_read_b128 v[176:179], v174 offset:17408
	s_waitcnt lgkmcnt(2)
	v_mfma_f32_16x16x32_bf16 v[32:35], v[136:139], v[188:191], v[32:35]
	v_mfma_f32_16x16x32_bf16 v[28:31], v[146:149], v[188:191], v[28:31]
	ds_read_b128 v[184:187], v174 offset:19456
	s_waitcnt lgkmcnt(2)
	v_mfma_f32_16x16x32_bf16 v[16:19], v[136:139], v[196:199], v[16:19]
	v_mfma_f32_16x16x32_bf16 v[12:15], v[146:149], v[196:199], v[12:15]
	ds_read_b128 v[192:195], v174 offset:21504
	s_waitcnt lgkmcnt(2)
	v_mfma_f32_16x16x32_bf16 v[64:67], v[142:145], v[176:179], v[64:67]
	v_mfma_f32_16x16x32_bf16 v[60:63], v[152:155], v[176:179], v[60:63]
	ds_read_b128 v[200:203], v174 offset:23552
	s_waitcnt lgkmcnt(2)
	v_mfma_f32_16x16x32_bf16 v[48:51], v[142:145], v[184:187], v[48:51]
	v_mfma_f32_16x16x32_bf16 v[44:47], v[152:155], v[184:187], v[44:47]
	s_waitcnt lgkmcnt(1)
	v_mfma_f32_16x16x32_bf16 v[32:35], v[142:145], v[192:195], v[32:35]
	v_mfma_f32_16x16x32_bf16 v[28:31], v[152:155], v[192:195], v[28:31]
	s_waitcnt lgkmcnt(0)
	v_mfma_f32_16x16x32_bf16 v[16:19], v[142:145], v[200:203], v[16:19]
	v_mfma_f32_16x16x32_bf16 v[12:15], v[152:155], v[200:203], v[12:15]
	s_add_u32 s28, s65, 0x80080
	s_addc_u32 s29, s66, 0
	s_mov_b32 m0, s52
	s_nop 0
	global_load_lds_dwordx4 v162, s[28:29]
	s_mov_b32 m0, s56
	s_nop 0
	global_load_lds_dwordx4 v170, s[28:29]
	v_mfma_f32_16x16x32_bf16 v[56:59], v[204:207], v[156:159], v[56:59]
	s_add_u32 s28, s65, 0x100
	s_addc_u32 s29, s66, 0
	s_add_u32 s63, s63, 0x100
	v_mfma_f32_16x16x32_bf16 v[52:55], v[212:215], v[156:159], v[52:55]
	s_addc_u32 s64, s64, 0
	v_mfma_f32_16x16x32_bf16 v[40:43], v[204:207], v[180:183], v[40:43]
	v_mfma_f32_16x16x32_bf16 v[36:39], v[212:215], v[180:183], v[36:39]
	v_mfma_f32_16x16x32_bf16 v[24:27], v[204:207], v[188:191], v[24:27]
	v_mfma_f32_16x16x32_bf16 v[20:23], v[212:215], v[188:191], v[20:23]
	v_mfma_f32_16x16x32_bf16 v[8:11], v[204:207], v[196:199], v[8:11]
	v_mfma_f32_16x16x32_bf16 v[4:7], v[212:215], v[196:199], v[4:7]
	v_mfma_f32_16x16x32_bf16 v[56:59], v[208:211], v[176:179], v[56:59]
	v_mfma_f32_16x16x32_bf16 v[52:55], v[216:219], v[176:179], v[52:55]
	v_mfma_f32_16x16x32_bf16 v[40:43], v[208:211], v[184:187], v[40:43]
	v_mfma_f32_16x16x32_bf16 v[36:39], v[216:219], v[184:187], v[36:39]
	v_mfma_f32_16x16x32_bf16 v[24:27], v[208:211], v[192:195], v[24:27]
	v_mfma_f32_16x16x32_bf16 v[20:23], v[216:219], v[192:195], v[20:23]
	v_mfma_f32_16x16x32_bf16 v[8:11], v[208:211], v[200:203], v[8:11]
	v_mfma_f32_16x16x32_bf16 v[4:7], v[216:219], v[200:203], v[4:7]
	s_waitcnt vmcnt(2) lgkmcnt(0)
	s_barrier
; template <class Epi, class Sched>
; __device__ __forceinline__ void gemm_simple(PG8_LAS unsigned char* lds, const Gemm g, const Sched& S, const Epi& E, int wave_s) {
;     ...
;             const char* a2 = last ? nA : cA + (size_t)(t + 2) * kstep; const char* b2 = last ? nB : cB + (size_t)(t + 2) * kstep;
;             PG8_TILE(1, a2, b2, (!last || has_next));
	ds_read_b128 v[136:139], v134
	ds_read_b128 v[156:159], v174 offset:32768
	ds_read_b128 v[146:149], v134 offset:2048
	ds_read_b128 v[180:183], v174 offset:34816
	s_cmp_eq_u32 s62, s26
	s_cselect_b32 s29, s15, s29
	s_cselect_b32 s28, s35, s28
	s_cselect_b32 s65, s13, s64
	s_cselect_b32 s64, s60, s63
	s_mov_b32 m0, s38
	s_nop 0
	global_load_lds_dwordx4 v163, s[64:65]
	s_mov_b32 m0, s39
	s_nop 0
	global_load_lds_dwordx4 v171, s[64:65]
	s_waitcnt lgkmcnt(2)
	v_mfma_f32_16x16x32_bf16 v[128:131], v[136:139], v[156:159], v[128:131]
	ds_read_b128 v[188:191], v174 offset:36864
	s_waitcnt lgkmcnt(2)
	v_mfma_f32_16x16x32_bf16 v[124:127], v[146:149], v[156:159], v[124:127]
	ds_read_b128 v[196:199], v174 offset:38912
	s_waitcnt lgkmcnt(2)
	v_mfma_f32_16x16x32_bf16 v[112:115], v[136:139], v[180:183], v[112:115]
	v_mfma_f32_16x16x32_bf16 v[108:111], v[146:149], v[180:183], v[108:111]
	ds_read_b128 v[142:145], v134 offset:1024
	ds_read_b128 v[176:179], v174 offset:33792
	s_waitcnt lgkmcnt(3)
	v_mfma_f32_16x16x32_bf16 v[96:99], v[136:139], v[188:191], v[96:99]
	ds_read_b128 v[152:155], v134 offset:3072
	v_mfma_f32_16x16x32_bf16 v[92:95], v[146:149], v[188:191], v[92:95]
	ds_read_b128 v[184:187], v174 offset:35840
	s_waitcnt lgkmcnt(4)
	v_mfma_f32_16x16x32_bf16 v[80:83], v[136:139], v[196:199], v[80:83]
	v_mfma_f32_16x16x32_bf16 v[76:79], v[146:149], v[196:199], v[76:79]
	ds_read_b128 v[192:195], v174 offset:37888
	s_waitcnt lgkmcnt(3)
	v_mfma_f32_16x16x32_bf16 v[128:131], v[142:145], v[176:179], v[128:131]
	s_waitcnt lgkmcnt(2)
	v_mfma_f32_16x16x32_bf16 v[124:127], v[152:155], v[176:179], v[124:127]
	ds_read_b128 v[200:203], v174 offset:39936
	s_waitcnt lgkmcnt(2)
	v_mfma_f32_16x16x32_bf16 v[112:115], v[142:145], v[184:187], v[112:115]
	v_mfma_f32_16x16x32_bf16 v[108:111], v[152:155], v[184:187], v[108:111]
	ds_read_b128 v[204:207], v135
	s_waitcnt lgkmcnt(2)
	v_mfma_f32_16x16x32_bf16 v[96:99], v[142:145], v[192:195], v[96:99]
	ds_read_b128 v[212:215], v135 offset:2048
	v_mfma_f32_16x16x32_bf16 v[92:95], v[152:155], v[192:195], v[92:95]
	s_waitcnt lgkmcnt(2)
	v_mfma_f32_16x16x32_bf16 v[80:83], v[142:145], v[200:203], v[80:83]
	v_mfma_f32_16x16x32_bf16 v[76:79], v[152:155], v[200:203], v[76:79]
	s_mov_b32 m0, s23
	s_nop 0
	global_load_lds_dwordx4 v162, s[28:29]
	s_mov_b32 m0, s40
	s_nop 0
	global_load_lds_dwordx4 v170, s[28:29]
	s_waitcnt lgkmcnt(1)
	v_mfma_f32_16x16x32_bf16 v[120:123], v[204:207], v[156:159], v[120:123]
	s_waitcnt lgkmcnt(0)
	v_mfma_f32_16x16x32_bf16 v[116:119], v[212:215], v[156:159], v[116:119]
	v_mfma_f32_16x16x32_bf16 v[104:107], v[204:207], v[180:183], v[104:107]
	v_mfma_f32_16x16x32_bf16 v[100:103], v[212:215], v[180:183], v[100:103]
	ds_read_b128 v[208:211], v135 offset:1024
	v_mfma_f32_16x16x32_bf16 v[88:91], v[204:207], v[188:191], v[88:91]
	ds_read_b128 v[216:219], v135 offset:3072
	v_mfma_f32_16x16x32_bf16 v[84:87], v[212:215], v[188:191], v[84:87]
	v_mfma_f32_16x16x32_bf16 v[72:75], v[204:207], v[196:199], v[72:75]
	v_mfma_f32_16x16x32_bf16 v[68:71], v[212:215], v[196:199], v[68:71]
	s_waitcnt lgkmcnt(1)
	v_mfma_f32_16x16x32_bf16 v[120:123], v[208:211], v[176:179], v[120:123]
	s_waitcnt lgkmcnt(0)
	v_mfma_f32_16x16x32_bf16 v[116:119], v[216:219], v[176:179], v[116:119]
	v_mfma_f32_16x16x32_bf16 v[104:107], v[208:211], v[184:187], v[104:107]
	v_mfma_f32_16x16x32_bf16 v[100:103], v[216:219], v[184:187], v[100:103]
	v_mfma_f32_16x16x32_bf16 v[88:91], v[208:211], v[192:195], v[88:91]
	v_mfma_f32_16x16x32_bf16 v[84:87], v[216:219], v[192:195], v[84:87]
	v_mfma_f32_16x16x32_bf16 v[72:75], v[208:211], v[200:203], v[72:75]
	v_mfma_f32_16x16x32_bf16 v[68:71], v[216:219], v[200:203], v[68:71]
	s_waitcnt vmcnt(4) lgkmcnt(0)
	s_barrier
; #define LAS __attribute__((address_space(3)))
; __device__ __forceinline__ void rstd_table(const float* ssq, LAS unsigned char* lds, const Unit& u, int tid, int par) {
;     if (tid < 256) { const f32x4* p = (const f32x4*)(ssq + (size_t)(u.pm * 256 + tid) * 32); f32x4 a = p[0];
; #pragma unroll
;         for (int i = 1; i < 8; ++i) a += p[i];
;         ((LAS float*)(lds + 131072 + par * 1024))[tid] = 1.0f / sqrtf(((a[0] + a[1]) + (a[2] + a[3])) * (1.0f / DM) + 1e-6f); }
	ds_read_b128 v[156:159], v174 offset:49152
	ds_read_b128 v[180:183], v174 offset:51200
	s_add_u32 s64, s64, 0x80000
	s_addc_u32 s65, s65, 0
	s_mov_b32 m0, s41
	s_nop 0
	global_load_lds_dwordx4 v163, s[64:65]
	s_mov_b32 m0, s42
	s_nop 0
	global_load_lds_dwordx4 v171, s[64:65]
	s_waitcnt lgkmcnt(1)
	v_mfma_f32_16x16x32_bf16 v[64:67], v[136:139], v[156:159], v[64:67]
	ds_read_b128 v[188:191], v174 offset:53248
	v_mfma_f32_16x16x32_bf16 v[60:63], v[146:149], v[156:159], v[60:63]
	ds_read_b128 v[196:199], v174 offset:55296
	s_waitcnt lgkmcnt(2)
	v_mfma_f32_16x16x32_bf16 v[48:51], v[136:139], v[180:183], v[48:51]
	v_mfma_f32_16x16x32_bf16 v[44:47], v[146:149], v[180:183], v[44:47]
	ds_read_b128 v[176:179], v174 offset:50176
	s_waitcnt lgkmcnt(2)
	v_mfma_f32_16x16x32_bf16 v[32:35], v[136:139], v[188:191], v[32:35]
	v_mfma_f32_16x16x32_bf16 v[28:31], v[146:149], v[188:191], v[28:31]
	ds_read_b128 v[184:187], v174 offset:52224
	s_waitcnt lgkmcnt(2)
	v_mfma_f32_16x16x32_bf16 v[16:19], v[136:139], v[196:199], v[16:19]
	v_mfma_f32_16x16x32_bf16 v[12:15], v[146:149], v[196:199], v[12:15]
	ds_read_b128 v[192:195], v174 offset:54272
	s_waitcnt lgkmcnt(2)
	v_mfma_f32_16x16x32_bf16 v[64:67], v[142:145], v[176:179], v[64:67]
	v_mfma_f32_16x16x32_bf16 v[60:63], v[152:155], v[176:179], v[60:63]
	ds_read_b128 v[200:203], v174 offset:56320
	s_waitcnt lgkmcnt(2)
	v_mfma_f32_16x16x32_bf16 v[48:51], v[142:145], v[184:187], v[48:51]
	v_mfma_f32_16x16x32_bf16 v[44:47], v[152:155], v[184:187], v[44:47]
	s_waitcnt lgkmcnt(1)
	v_mfma_f32_16x16x32_bf16 v[32:35], v[142:145], v[192:195], v[32:35]
	v_mfma_f32_16x16x32_bf16 v[28:31], v[152:155], v[192:195], v[28:31]
	s_waitcnt lgkmcnt(0)
	v_mfma_f32_16x16x32_bf16 v[16:19], v[142:145], v[200:203], v[16:19]
	v_mfma_f32_16x16x32_bf16 v[12:15], v[152:155], v[200:203], v[12:15]
	s_add_u32 s28, s28, 0x80000
	s_addc_u32 s29, s29, 0
	s_mov_b32 m0, s43
	s_nop 0
	global_load_lds_dwordx4 v162, s[28:29]
	s_mov_b32 m0, s44
	s_nop 0
	global_load_lds_dwordx4 v170, s[28:29]
	v_mfma_f32_16x16x32_bf16 v[56:59], v[204:207], v[156:159], v[56:59]
	s_add_i32 s61, s61, 2
	s_add_u32 s26, s26, 0xffffff00
	s_addc_u32 s27, s27, -1
	v_mfma_f32_16x16x32_bf16 v[52:55], v[212:215], v[156:159], v[52:55]
	s_add_u32 s24, s24, 0x100
	s_addc_u32 s25, s25, 0
	s_add_u32 s10, s10, 0x100
	v_mfma_f32_16x16x32_bf16 v[40:43], v[204:207], v[180:183], v[40:43]
	s_addc_u32 s11, s11, 0
	s_cmp_lt_u32 s61, 30
	v_mfma_f32_16x16x32_bf16 v[36:39], v[212:215], v[180:183], v[36:39]
	v_mfma_f32_16x16x32_bf16 v[24:27], v[204:207], v[188:191], v[24:27]
	v_mfma_f32_16x16x32_bf16 v[20:23], v[212:215], v[188:191], v[20:23]
	v_mfma_f32_16x16x32_bf16 v[8:11], v[204:207], v[196:199], v[8:11]
	v_mfma_f32_16x16x32_bf16 v[4:7], v[212:215], v[196:199], v[4:7]
	v_mfma_f32_16x16x32_bf16 v[56:59], v[208:211], v[176:179], v[56:59]
	v_mfma_f32_16x16x32_bf16 v[52:55], v[216:219], v[176:179], v[52:55]
	v_mfma_f32_16x16x32_bf16 v[40:43], v[208:211], v[184:187], v[40:43]
	v_mfma_f32_16x16x32_bf16 v[36:39], v[216:219], v[184:187], v[36:39]
	v_mfma_f32_16x16x32_bf16 v[24:27], v[208:211], v[192:195], v[24:27]
	v_mfma_f32_16x16x32_bf16 v[20:23], v[216:219], v[192:195], v[20:23]
	v_mfma_f32_16x16x32_bf16 v[8:11], v[208:211], v[200:203], v[8:11]
	v_mfma_f32_16x16x32_bf16 v[4:7], v[216:219], v[200:203], v[4:7]
	s_cbranch_scc1 .LBB0_275
	s_nor_b64 s[10:11], s[6:7], s[8:9]
	s_and_saveexec_b64 s[24:25], s[10:11]
	s_cbranch_execz .LBB0_278
	v_lshl_add_u32 v132, s14, 8, v140
	v_ashrrev_i32_e32 v133, 31, v132
	v_readlane_b32 s10, v255, 2
	v_lshlrev_b64 v[132:133], 7, v[132:133]
	v_readlane_b32 s11, v255, 3
	s_nop 1
	v_lshl_add_u64 v[152:153], s[10:11], 0, v[132:133]
	global_load_dwordx4 v[132:135], v[152:153], off offset:48
	global_load_dwordx4 v[136:139], v[152:153], off offset:32
	global_load_dwordx4 v[142:145], v[152:153], off
	global_load_dwordx4 v[146:149], v[152:153], off offset:16
	s_waitcnt vmcnt(0)
	v_pk_add_f32 v[144:145], v[144:145], v[148:149]
	v_pk_add_f32 v[142:143], v[142:143], v[146:147]
	v_pk_add_f32 v[138:139], v[144:145], v[138:139]
	v_pk_add_f32 v[136:137], v[142:143], v[136:137]
	v_pk_add_f32 v[154:155], v[138:139], v[134:135]
	v_pk_add_f32 v[156:157], v[136:137], v[132:133]
	global_load_dwordx4 v[132:135], v[152:153], off offset:112
	global_load_dwordx4 v[136:139], v[152:153], off offset:96
	global_load_dwordx4 v[142:145], v[152:153], off offset:80
	global_load_dwordx4 v[146:149], v[152:153], off offset:64
	s_waitcnt vmcnt(0)
	v_pk_add_f32 v[148:149], v[154:155], v[148:149]
	v_pk_add_f32 v[146:147], v[156:157], v[146:147]
	v_pk_add_f32 v[144:145], v[148:149], v[144:145]
	v_pk_add_f32 v[142:143], v[146:147], v[142:143]
	v_pk_add_f32 v[138:139], v[144:145], v[138:139]
	v_pk_add_f32 v[136:137], v[142:143], v[136:137]
	v_pk_add_f32 v[134:135], v[138:139], v[134:135]
	v_pk_add_f32 v[132:133], v[136:137], v[132:133]
	s_nop 0
	v_pk_mov_b32 v[136:137], v[132:133], v[134:135] op_sel:[1,0]
	v_mov_b32_e32 v133, v135
	v_pk_add_f32 v[132:133], v[136:137], v[132:133]
	s_nop 0
	v_add_f32_e32 v132, v132, v133
	v_fmamk_f32 v132, v132, 0x3a000000, v164
	v_cmp_gt_f32_e32 vcc, s69, v132
	v_mul_f32_e32 v133, 0x4f800000, v132
	s_nop 0
	v_cndmask_b32_e32 v132, v132, v133, vcc
	v_sqrt_f32_e32 v133, v132
	s_nop 0
	v_add_u32_e32 v134, -1, v133
	v_fma_f32 v135, -v134, v133, v132
	v_cmp_ge_f32_e64 s[10:11], 0, v135
	v_add_u32_e32 v135, 1, v133
	s_nop 0
	v_cndmask_b32_e64 v134, v133, v134, s[10:11]
	v_fma_f32 v133, -v135, v133, v132
	v_cmp_lt_f32_e64 s[10:11], 0, v133
	s_nop 1
	v_cndmask_b32_e64 v133, v134, v135, s[10:11]
	v_mul_f32_e32 v134, 0x37800000, v133
	v_cndmask_b32_e32 v133, v133, v134, vcc
	v_cmp_class_f32_e32 vcc, v132, v165
	s_nop 1
	v_cndmask_b32_e32 v132, v133, v132, vcc
	v_div_scale_f32 v133, s[10:11], v132, v132, 1.0
	v_rcp_f32_e32 v134, v133
	s_lshl_b32 s10, s59, 10
	s_and_b32 s10, s10, 0x400
	v_fma_f32 v135, -v133, v134, 1.0
	v_fmac_f32_e32 v134, v135, v134
	v_div_scale_f32 v135, vcc, 1.0, v132, 1.0
	v_mul_f32_e32 v136, v135, v134
	v_fma_f32 v137, -v133, v136, v135
	v_fmac_f32_e32 v136, v137, v134
	v_fma_f32 v133, -v133, v136, v135
	v_div_fmas_f32 v133, v133, v134, v136
	v_div_fixup_f32 v132, v133, v132, 1.0
	v_add_u32_e32 v133, s10, v172
	ds_write_b32 v133, v132

; template <class Epi, class Sched>
; __device__ __forceinline__ void gemm_simple(PG8_LAS unsigned char* lds, const Gemm g, const Sched& S, const Epi& E, int wave_s) {
;     ...
;         for (; t < nt; t += 2) {
;             const bool last = (t == nt - 2);
;             PG8_TILE(0, cA + (size_t)(t + 1) * kstep, cB + (size_t)(t + 1) * kstep, true);
.LBB0_307:
	s_waitcnt vmcnt(2) lgkmcnt(0)
	s_barrier
	ds_read_b128 v[136:139], v132
	ds_read_b128 v[178:181], v177
	ds_read_b128 v[156:159], v132 offset:2048
	ds_read_b128 v[186:189], v177 offset:2048
	s_add_u32 s60, s10, s59
	s_addc_u32 s61, s11, 0
	s_add_u32 s24, s60, 0x80
	s_addc_u32 s25, s61, 0
	s_mov_b32 m0, s43
	s_nop 0
	global_load_lds_dwordx4 v172, s[24:25]
	s_mov_b32 m0, s49
	s_nop 0
	global_load_lds_dwordx4 v174, s[24:25]
	s_waitcnt lgkmcnt(2)
	v_mfma_f32_16x16x32_bf16 v[120:123], v[136:139], v[178:181], v[120:123]
	ds_read_b128 v[194:197], v177 offset:4096
	s_waitcnt lgkmcnt(2)
	v_mfma_f32_16x16x32_bf16 v[116:119], v[156:159], v[178:181], v[116:119]
	ds_read_b128 v[202:205], v177 offset:6144
	s_waitcnt lgkmcnt(2)
	v_mfma_f32_16x16x32_bf16 v[104:107], v[136:139], v[186:189], v[104:107]
	v_mfma_f32_16x16x32_bf16 v[100:103], v[156:159], v[186:189], v[100:103]
	ds_read_b128 v[152:155], v132 offset:1024
	ds_read_b128 v[182:185], v177 offset:1024
	s_waitcnt lgkmcnt(3)
	v_mfma_f32_16x16x32_bf16 v[88:91], v[136:139], v[194:197], v[88:91]
	ds_read_b128 v[160:163], v132 offset:3072
	v_mfma_f32_16x16x32_bf16 v[84:87], v[156:159], v[194:197], v[84:87]
	ds_read_b128 v[190:193], v177 offset:3072
	s_waitcnt lgkmcnt(4)
	v_mfma_f32_16x16x32_bf16 v[72:75], v[136:139], v[202:205], v[72:75]
	v_mfma_f32_16x16x32_bf16 v[68:71], v[156:159], v[202:205], v[68:71]
	ds_read_b128 v[198:201], v177 offset:5120
	s_waitcnt lgkmcnt(3)
	v_mfma_f32_16x16x32_bf16 v[120:123], v[152:155], v[182:185], v[120:123]
	s_waitcnt lgkmcnt(2)
	v_mfma_f32_16x16x32_bf16 v[116:119], v[160:163], v[182:185], v[116:119]
	ds_read_b128 v[206:209], v177 offset:7168
	s_waitcnt lgkmcnt(2)
	v_mfma_f32_16x16x32_bf16 v[104:107], v[152:155], v[190:193], v[104:107]
	v_mfma_f32_16x16x32_bf16 v[100:103], v[160:163], v[190:193], v[100:103]
	ds_read_b128 v[210:213], v133
	s_waitcnt lgkmcnt(2)
	v_mfma_f32_16x16x32_bf16 v[88:91], v[152:155], v[198:201], v[88:91]
	ds_read_b128 v[218:221], v133 offset:2048
	v_mfma_f32_16x16x32_bf16 v[84:87], v[160:163], v[198:201], v[84:87]
	s_waitcnt lgkmcnt(2)
	v_mfma_f32_16x16x32_bf16 v[72:75], v[152:155], v[206:209], v[72:75]
	v_mfma_f32_16x16x32_bf16 v[68:71], v[160:163], v[206:209], v[68:71]
	s_add_u32 s62, s20, s59
	s_addc_u32 s63, s21, 0
	s_add_u32 s24, s62, 0x80
	s_addc_u32 s25, s63, 0
	s_mov_b32 m0, s44
	s_nop 0
	global_load_lds_dwordx4 v171, s[24:25]
	s_mov_b32 m0, s50
	s_nop 0
	global_load_lds_dwordx4 v173, s[24:25]
	s_waitcnt lgkmcnt(1)
	v_mfma_f32_16x16x32_bf16 v[128:131], v[210:213], v[178:181], v[128:131]
	s_waitcnt lgkmcnt(0)
	v_mfma_f32_16x16x32_bf16 v[124:127], v[218:221], v[178:181], v[124:127]
	v_mfma_f32_16x16x32_bf16 v[112:115], v[210:213], v[186:189], v[112:115]
	v_mfma_f32_16x16x32_bf16 v[108:111], v[218:221], v[186:189], v[108:111]
	ds_read_b128 v[214:217], v133 offset:1024
	v_mfma_f32_16x16x32_bf16 v[96:99], v[210:213], v[194:197], v[96:99]
	ds_read_b128 v[222:225], v133 offset:3072
	v_mfma_f32_16x16x32_bf16 v[92:95], v[218:221], v[194:197], v[92:95]
	v_mfma_f32_16x16x32_bf16 v[80:83], v[210:213], v[202:205], v[80:83]
	v_mfma_f32_16x16x32_bf16 v[76:79], v[218:221], v[202:205], v[76:79]
	s_waitcnt lgkmcnt(1)
	v_mfma_f32_16x16x32_bf16 v[128:131], v[214:217], v[182:185], v[128:131]
	s_waitcnt lgkmcnt(0)
	v_mfma_f32_16x16x32_bf16 v[124:127], v[222:225], v[182:185], v[124:127]
	v_mfma_f32_16x16x32_bf16 v[112:115], v[214:217], v[190:193], v[112:115]
	v_mfma_f32_16x16x32_bf16 v[108:111], v[222:225], v[190:193], v[108:111]
	v_mfma_f32_16x16x32_bf16 v[96:99], v[214:217], v[198:201], v[96:99]
	v_mfma_f32_16x16x32_bf16 v[92:95], v[222:225], v[198:201], v[92:95]
	v_mfma_f32_16x16x32_bf16 v[80:83], v[214:217], v[206:209], v[80:83]
	v_mfma_f32_16x16x32_bf16 v[76:79], v[222:225], v[206:209], v[76:79]
	s_waitcnt vmcnt(4) lgkmcnt(0)
	s_barrier
	ds_read_b128 v[178:181], v177 offset:16384
	ds_read_b128 v[186:189], v177 offset:18432
	s_add_u32 s24, s60, 0x80080
	s_addc_u32 s25, s61, 0
	s_mov_b32 m0, s45
	s_nop 0
	global_load_lds_dwordx4 v172, s[24:25]
	s_mov_b32 m0, s51
	s_nop 0
	global_load_lds_dwordx4 v174, s[24:25]
	s_waitcnt lgkmcnt(1)
	v_mfma_f32_16x16x32_bf16 v[56:59], v[136:139], v[178:181], v[56:59]
	ds_read_b128 v[194:197], v177 offset:20480
	v_mfma_f32_16x16x32_bf16 v[52:55], v[156:159], v[178:181], v[52:55]
	ds_read_b128 v[202:205], v177 offset:22528
	s_waitcnt lgkmcnt(2)
	v_mfma_f32_16x16x32_bf16 v[40:43], v[136:139], v[186:189], v[40:43]
	v_mfma_f32_16x16x32_bf16 v[36:39], v[156:159], v[186:189], v[36:39]
	ds_read_b128 v[182:185], v177 offset:17408
	s_waitcnt lgkmcnt(2)
	v_mfma_f32_16x16x32_bf16 v[24:27], v[136:139], v[194:197], v[24:27]
	v_mfma_f32_16x16x32_bf16 v[20:23], v[156:159], v[194:197], v[20:23]
	ds_read_b128 v[190:193], v177 offset:19456
	s_waitcnt lgkmcnt(2)
	v_mfma_f32_16x16x32_bf16 v[8:11], v[136:139], v[202:205], v[8:11]
	v_mfma_f32_16x16x32_bf16 v[4:7], v[156:159], v[202:205], v[4:7]
	ds_read_b128 v[198:201], v177 offset:21504
	s_waitcnt lgkmcnt(2)
	v_mfma_f32_16x16x32_bf16 v[56:59], v[152:155], v[182:185], v[56:59]
	v_mfma_f32_16x16x32_bf16 v[52:55], v[160:163], v[182:185], v[52:55]
	ds_read_b128 v[206:209], v177 offset:23552
	s_waitcnt lgkmcnt(2)
	v_mfma_f32_16x16x32_bf16 v[40:43], v[152:155], v[190:193], v[40:43]
	v_mfma_f32_16x16x32_bf16 v[36:39], v[160:163], v[190:193], v[36:39]
	s_waitcnt lgkmcnt(1)
	v_mfma_f32_16x16x32_bf16 v[24:27], v[152:155], v[198:201], v[24:27]
	v_mfma_f32_16x16x32_bf16 v[20:23], v[160:163], v[198:201], v[20:23]
	s_waitcnt lgkmcnt(0)
	v_mfma_f32_16x16x32_bf16 v[8:11], v[152:155], v[206:209], v[8:11]
	v_mfma_f32_16x16x32_bf16 v[4:7], v[160:163], v[206:209], v[4:7]
	s_add_u32 s24, s62, 0x80080
	s_addc_u32 s25, s63, 0
	s_mov_b32 m0, s46
	s_nop 0
	global_load_lds_dwordx4 v171, s[24:25]
	s_mov_b32 m0, s52
	s_nop 0
	global_load_lds_dwordx4 v173, s[24:25]
	v_mfma_f32_16x16x32_bf16 v[64:67], v[210:213], v[178:181], v[64:67]
	s_add_u32 s24, s62, 0x100
	s_addc_u32 s25, s63, 0
	s_add_u32 s60, s60, 0x100
	v_mfma_f32_16x16x32_bf16 v[60:63], v[218:221], v[178:181], v[60:63]
	s_addc_u32 s61, s61, 0
	v_mfma_f32_16x16x32_bf16 v[48:51], v[210:213], v[186:189], v[48:51]
	v_mfma_f32_16x16x32_bf16 v[44:47], v[218:221], v[186:189], v[44:47]
	v_mfma_f32_16x16x32_bf16 v[32:35], v[210:213], v[194:197], v[32:35]
	v_mfma_f32_16x16x32_bf16 v[28:31], v[218:221], v[194:197], v[28:31]
	v_mfma_f32_16x16x32_bf16 v[12:15], v[210:213], v[202:205], v[12:15]
	v_mfma_f32_16x16x32_bf16 v[16:19], v[218:221], v[202:205], v[16:19]
	v_mfma_f32_16x16x32_bf16 v[64:67], v[214:217], v[182:185], v[64:67]
	v_mfma_f32_16x16x32_bf16 v[60:63], v[222:225], v[182:185], v[60:63]
	v_mfma_f32_16x16x32_bf16 v[48:51], v[214:217], v[190:193], v[48:51]
	v_mfma_f32_16x16x32_bf16 v[44:47], v[222:225], v[190:193], v[44:47]
	v_mfma_f32_16x16x32_bf16 v[32:35], v[214:217], v[198:201], v[32:35]
	v_mfma_f32_16x16x32_bf16 v[28:31], v[222:225], v[198:201], v[28:31]
	v_mfma_f32_16x16x32_bf16 v[12:15], v[214:217], v[206:209], v[12:15]
	v_mfma_f32_16x16x32_bf16 v[16:19], v[222:225], v[206:209], v[16:19]
	s_waitcnt vmcnt(2) lgkmcnt(0)
	s_barrier
; template <class Epi, class Sched>
; __device__ __forceinline__ void gemm_simple(PG8_LAS unsigned char* lds, const Gemm g, const Sched& S, const Epi& E, int wave_s) {
;     ...
;             const char* a2 = last ? nA : cA + (size_t)(t + 2) * kstep; const char* b2 = last ? nB : cB + (size_t)(t + 2) * kstep;
;             PG8_TILE(1, a2, b2, (!last || has_next));
	ds_read_b128 v[136:139], v134
	ds_read_b128 v[178:181], v177 offset:32768
	ds_read_b128 v[156:159], v134 offset:2048
	ds_read_b128 v[186:189], v177 offset:34816
	s_cmp_eq_u32 s59, s22
	s_cselect_b32 s25, s13, s25
	s_cselect_b32 s24, s56, s24
	s_cselect_b32 s61, s5, s61
	s_cselect_b32 s60, s57, s60
	s_mov_b32 m0, s27
	s_nop 0
	global_load_lds_dwordx4 v172, s[60:61]
	s_mov_b32 m0, s28
	s_nop 0
	global_load_lds_dwordx4 v174, s[60:61]
	s_waitcnt lgkmcnt(2)
	v_mfma_f32_16x16x32_bf16 v[120:123], v[136:139], v[178:181], v[120:123]
	ds_read_b128 v[194:197], v177 offset:36864
	s_waitcnt lgkmcnt(2)
	v_mfma_f32_16x16x32_bf16 v[116:119], v[156:159], v[178:181], v[116:119]
	ds_read_b128 v[202:205], v177 offset:38912
	s_waitcnt lgkmcnt(2)
	v_mfma_f32_16x16x32_bf16 v[104:107], v[136:139], v[186:189], v[104:107]
	v_mfma_f32_16x16x32_bf16 v[100:103], v[156:159], v[186:189], v[100:103]
	ds_read_b128 v[152:155], v134 offset:1024
	ds_read_b128 v[182:185], v177 offset:33792
	s_waitcnt lgkmcnt(3)
	v_mfma_f32_16x16x32_bf16 v[88:91], v[136:139], v[194:197], v[88:91]
	ds_read_b128 v[160:163], v134 offset:3072
	v_mfma_f32_16x16x32_bf16 v[84:87], v[156:159], v[194:197], v[84:87]
	ds_read_b128 v[190:193], v177 offset:35840
	s_waitcnt lgkmcnt(4)
	v_mfma_f32_16x16x32_bf16 v[72:75], v[136:139], v[202:205], v[72:75]
	v_mfma_f32_16x16x32_bf16 v[68:71], v[156:159], v[202:205], v[68:71]
	ds_read_b128 v[198:201], v177 offset:37888
	s_waitcnt lgkmcnt(3)
	v_mfma_f32_16x16x32_bf16 v[120:123], v[152:155], v[182:185], v[120:123]
	s_waitcnt lgkmcnt(2)
	v_mfma_f32_16x16x32_bf16 v[116:119], v[160:163], v[182:185], v[116:119]
	ds_read_b128 v[206:209], v177 offset:39936
	s_waitcnt lgkmcnt(2)
	v_mfma_f32_16x16x32_bf16 v[104:107], v[152:155], v[190:193], v[104:107]
	v_mfma_f32_16x16x32_bf16 v[100:103], v[160:163], v[190:193], v[100:103]
	ds_read_b128 v[210:213], v135
	s_waitcnt lgkmcnt(2)
	v_mfma_f32_16x16x32_bf16 v[88:91], v[152:155], v[198:201], v[88:91]
	ds_read_b128 v[218:221], v135 offset:2048
	v_mfma_f32_16x16x32_bf16 v[84:87], v[160:163], v[198:201], v[84:87]
	s_waitcnt lgkmcnt(2)
	v_mfma_f32_16x16x32_bf16 v[72:75], v[152:155], v[206:209], v[72:75]
	v_mfma_f32_16x16x32_bf16 v[68:71], v[160:163], v[206:209], v[68:71]
	s_mov_b32 m0, s19
	s_nop 0
	global_load_lds_dwordx4 v171, s[24:25]
	s_mov_b32 m0, s29
	s_nop 0
	global_load_lds_dwordx4 v173, s[24:25]
	s_waitcnt lgkmcnt(1)
	v_mfma_f32_16x16x32_bf16 v[128:131], v[210:213], v[178:181], v[128:131]
	s_waitcnt lgkmcnt(0)
	v_mfma_f32_16x16x32_bf16 v[124:127], v[218:221], v[178:181], v[124:127]
	v_mfma_f32_16x16x32_bf16 v[112:115], v[210:213], v[186:189], v[112:115]
	v_mfma_f32_16x16x32_bf16 v[108:111], v[218:221], v[186:189], v[108:111]
	ds_read_b128 v[214:217], v135 offset:1024
	v_mfma_f32_16x16x32_bf16 v[96:99], v[210:213], v[194:197], v[96:99]
	ds_read_b128 v[222:225], v135 offset:3072
	v_mfma_f32_16x16x32_bf16 v[92:95], v[218:221], v[194:197], v[92:95]
	v_mfma_f32_16x16x32_bf16 v[80:83], v[210:213], v[202:205], v[80:83]
	v_mfma_f32_16x16x32_bf16 v[76:79], v[218:221], v[202:205], v[76:79]
	s_waitcnt lgkmcnt(1)
	v_mfma_f32_16x16x32_bf16 v[128:131], v[214:217], v[182:185], v[128:131]
	s_waitcnt lgkmcnt(0)
	v_mfma_f32_16x16x32_bf16 v[124:127], v[222:225], v[182:185], v[124:127]
	v_mfma_f32_16x16x32_bf16 v[112:115], v[214:217], v[190:193], v[112:115]
	v_mfma_f32_16x16x32_bf16 v[108:111], v[222:225], v[190:193], v[108:111]
	v_mfma_f32_16x16x32_bf16 v[96:99], v[214:217], v[198:201], v[96:99]
	v_mfma_f32_16x16x32_bf16 v[92:95], v[222:225], v[198:201], v[92:95]
	v_mfma_f32_16x16x32_bf16 v[80:83], v[214:217], v[206:209], v[80:83]
	v_mfma_f32_16x16x32_bf16 v[76:79], v[222:225], v[206:209], v[76:79]
	s_waitcnt vmcnt(4) lgkmcnt(0)
	s_barrier
; #define LAS __attribute__((address_space(3)))
; __device__ __forceinline__ void rstd_table(const float* ssq, LAS unsigned char* lds, const Unit& u, int tid, int par) {
;     if (tid < 256) { const f32x4* p = (const f32x4*)(ssq + (size_t)(u.pm * 256 + tid) * 32); f32x4 a = p[0];
; #pragma unroll
;         for (int i = 1; i < 8; ++i) a += p[i];
;         ((LAS float*)(lds + 131072 + par * 1024))[tid] = 1.0f / sqrtf(((a[0] + a[1]) + (a[2] + a[3])) * (1.0f / DM) + 1e-6f); }
	ds_read_b128 v[178:181], v177 offset:49152
	ds_read_b128 v[186:189], v177 offset:51200
	s_add_u32 s60, s60, 0x80000
	s_addc_u32 s61, s61, 0
	s_mov_b32 m0, s36
	s_nop 0
	global_load_lds_dwordx4 v172, s[60:61]
	s_mov_b32 m0, s37
	s_nop 0
	global_load_lds_dwordx4 v174, s[60:61]
	s_waitcnt lgkmcnt(1)
	v_mfma_f32_16x16x32_bf16 v[56:59], v[136:139], v[178:181], v[56:59]
	ds_read_b128 v[194:197], v177 offset:53248
	v_mfma_f32_16x16x32_bf16 v[52:55], v[156:159], v[178:181], v[52:55]
	ds_read_b128 v[202:205], v177 offset:55296
	s_waitcnt lgkmcnt(2)
	v_mfma_f32_16x16x32_bf16 v[40:43], v[136:139], v[186:189], v[40:43]
	v_mfma_f32_16x16x32_bf16 v[36:39], v[156:159], v[186:189], v[36:39]
	ds_read_b128 v[182:185], v177 offset:50176
	s_waitcnt lgkmcnt(2)
	v_mfma_f32_16x16x32_bf16 v[24:27], v[136:139], v[194:197], v[24:27]
	v_mfma_f32_16x16x32_bf16 v[20:23], v[156:159], v[194:197], v[20:23]
	ds_read_b128 v[190:193], v177 offset:52224
	s_waitcnt lgkmcnt(2)
	v_mfma_f32_16x16x32_bf16 v[8:11], v[136:139], v[202:205], v[8:11]
	v_mfma_f32_16x16x32_bf16 v[4:7], v[156:159], v[202:205], v[4:7]
	ds_read_b128 v[198:201], v177 offset:54272
	s_waitcnt lgkmcnt(2)
	v_mfma_f32_16x16x32_bf16 v[56:59], v[152:155], v[182:185], v[56:59]
	v_mfma_f32_16x16x32_bf16 v[52:55], v[160:163], v[182:185], v[52:55]
	ds_read_b128 v[206:209], v177 offset:56320
	s_waitcnt lgkmcnt(2)
	v_mfma_f32_16x16x32_bf16 v[40:43], v[152:155], v[190:193], v[40:43]
	v_mfma_f32_16x16x32_bf16 v[36:39], v[160:163], v[190:193], v[36:39]
	s_waitcnt lgkmcnt(1)
	v_mfma_f32_16x16x32_bf16 v[24:27], v[152:155], v[198:201], v[24:27]
	v_mfma_f32_16x16x32_bf16 v[20:23], v[160:163], v[198:201], v[20:23]
	s_waitcnt lgkmcnt(0)
	v_mfma_f32_16x16x32_bf16 v[8:11], v[152:155], v[206:209], v[8:11]
	v_mfma_f32_16x16x32_bf16 v[4:7], v[160:163], v[206:209], v[4:7]
	s_add_u32 s24, s24, 0x80000
	s_addc_u32 s25, s25, 0
	s_mov_b32 m0, s38
	s_nop 0
	global_load_lds_dwordx4 v171, s[24:25]
	s_mov_b32 m0, s39
	s_nop 0
	global_load_lds_dwordx4 v173, s[24:25]
	v_mfma_f32_16x16x32_bf16 v[64:67], v[210:213], v[178:181], v[64:67]
	s_add_i32 s58, s58, 2
	s_add_u32 s22, s22, 0xffffff00
	s_addc_u32 s23, s23, -1
	v_mfma_f32_16x16x32_bf16 v[60:63], v[218:221], v[178:181], v[60:63]
	s_add_u32 s20, s20, 0x100
	s_addc_u32 s21, s21, 0
	s_add_u32 s10, s10, 0x100
	v_mfma_f32_16x16x32_bf16 v[48:51], v[210:213], v[186:189], v[48:51]
	s_addc_u32 s11, s11, 0
	s_cmp_lt_u32 s58, 30
	v_mfma_f32_16x16x32_bf16 v[44:47], v[218:221], v[186:189], v[44:47]
	v_mfma_f32_16x16x32_bf16 v[32:35], v[210:213], v[194:197], v[32:35]
	v_mfma_f32_16x16x32_bf16 v[28:31], v[218:221], v[194:197], v[28:31]
	v_mfma_f32_16x16x32_bf16 v[12:15], v[210:213], v[202:205], v[12:15]
	v_mfma_f32_16x16x32_bf16 v[16:19], v[218:221], v[202:205], v[16:19]
	v_mfma_f32_16x16x32_bf16 v[64:67], v[214:217], v[182:185], v[64:67]
	v_mfma_f32_16x16x32_bf16 v[60:63], v[222:225], v[182:185], v[60:63]
	v_mfma_f32_16x16x32_bf16 v[48:51], v[214:217], v[190:193], v[48:51]
	v_mfma_f32_16x16x32_bf16 v[44:47], v[222:225], v[190:193], v[44:47]
	v_mfma_f32_16x16x32_bf16 v[32:35], v[214:217], v[198:201], v[32:35]
	v_mfma_f32_16x16x32_bf16 v[28:31], v[222:225], v[198:201], v[28:31]
	v_mfma_f32_16x16x32_bf16 v[12:15], v[214:217], v[206:209], v[12:15]
	v_mfma_f32_16x16x32_bf16 v[16:19], v[222:225], v[206:209], v[16:19]
	s_cbranch_scc1 .LBB0_307
	s_nor_b64 s[10:11], s[6:7], s[8:9]
	s_and_saveexec_b64 s[20:21], s[10:11]
	s_cbranch_execz .LBB0_310
	v_lshl_add_u32 v132, s12, 8, v170
	v_ashrrev_i32_e32 v133, 31, v132
	v_readlane_b32 s10, v255, 2
	v_lshlrev_b64 v[132:133], 7, v[132:133]
	v_readlane_b32 s11, v255, 3
	s_lshl_b32 s5, s54, 10
	s_and_b32 s5, s5, 0x400
	v_lshl_add_u64 v[142:143], s[10:11], 0, v[132:133]
	global_load_dwordx4 v[132:135], v[142:143], off offset:48
	global_load_dwordx4 v[136:139], v[142:143], off offset:32
	global_load_dwordx4 v[152:155], v[142:143], off
	global_load_dwordx4 v[156:159], v[142:143], off offset:16
	s_waitcnt vmcnt(0)
	v_pk_add_f32 v[144:145], v[154:155], v[158:159]
	v_pk_add_f32 v[146:147], v[152:153], v[156:157]
	v_pk_add_f32 v[138:139], v[144:145], v[138:139]
	v_pk_add_f32 v[136:137], v[146:147], v[136:137]
	v_pk_add_f32 v[144:145], v[138:139], v[134:135]
	v_pk_add_f32 v[146:147], v[136:137], v[132:133]
	global_load_dwordx4 v[132:135], v[142:143], off offset:112
	global_load_dwordx4 v[136:139], v[142:143], off offset:96
	global_load_dwordx4 v[152:155], v[142:143], off offset:80
	global_load_dwordx4 v[156:159], v[142:143], off offset:64
	s_waitcnt vmcnt(0)
	v_pk_add_f32 v[142:143], v[144:145], v[158:159]
	v_pk_add_f32 v[144:145], v[146:147], v[156:157]
	v_pk_add_f32 v[142:143], v[142:143], v[154:155]
	v_pk_add_f32 v[144:145], v[144:145], v[152:153]
	v_pk_add_f32 v[138:139], v[142:143], v[138:139]
	v_pk_add_f32 v[136:137], v[144:145], v[136:137]
	v_pk_add_f32 v[134:135], v[138:139], v[134:135]
	v_pk_add_f32 v[132:133], v[136:137], v[132:133]
	s_nop 0
	v_pk_mov_b32 v[136:137], v[132:133], v[134:135] op_sel:[1,0]
	v_mov_b32_e32 v133, v135
	v_pk_add_f32 v[132:133], v[136:137], v[132:133]
	s_nop 0
	v_add_f32_e32 v132, v132, v133
	v_fmamk_f32 v132, v132, 0x3a000000, v164
	v_cmp_gt_f32_e32 vcc, s69, v132
	v_mul_f32_e32 v133, 0x4f800000, v132
	s_nop 0
	v_cndmask_b32_e32 v132, v132, v133, vcc
	v_sqrt_f32_e32 v133, v132
	s_nop 0
	v_add_u32_e32 v134, -1, v133
	v_fma_f32 v135, -v134, v133, v132
	v_cmp_ge_f32_e64 s[10:11], 0, v135
	v_add_u32_e32 v135, 1, v133
	s_nop 0
	v_cndmask_b32_e64 v134, v133, v134, s[10:11]
	v_fma_f32 v133, -v135, v133, v132
	v_cmp_lt_f32_e64 s[10:11], 0, v133
	s_nop 1
	v_cndmask_b32_e64 v133, v134, v135, s[10:11]
	v_mul_f32_e32 v134, 0x37800000, v133
	v_cndmask_b32_e32 v133, v133, v134, vcc
	v_cmp_class_f32_e32 vcc, v132, v165
	s_nop 1
	v_cndmask_b32_e32 v132, v133, v132, vcc
	v_div_scale_f32 v133, s[10:11], v132, v132, 1.0
	v_rcp_f32_e32 v134, v133
	s_nop 0
	v_fma_f32 v135, -v133, v134, 1.0
	v_fmac_f32_e32 v134, v135, v134
	v_div_scale_f32 v135, vcc, 1.0, v132, 1.0
	v_mul_f32_e32 v136, v135, v134
	v_fma_f32 v137, -v133, v136, v135
	v_fmac_f32_e32 v136, v137, v134
	v_fma_f32 v133, -v133, v136, v135
	v_div_fmas_f32 v133, v133, v134, v136
	v_div_fixup_f32 v132, v133, v132, 1.0
	v_add_u32_e32 v133, s5, v175
	ds_write_b32 v133, v132
